# LN row statistics: ds_bpermute xor-16/xor-32 shuffles replaced by v_permlane16/32_swap (110 sites)
# speedup vs baseline: 1.0079x; 1.0034x over previous
.LBB0_438:
	s_lshl_b32 s2, s14, 5
	s_lshl_b32 s3, s0, 8
	s_or_b32 s2, s3, s2
	v_lshrrev_b32_e32 v0, 2, v148
	s_lshl_b32 s6, s87, 8
	v_and_or_b32 v164, v0, 12, s2
	s_add_i32 s2, s6, s96
	v_or_b32_e32 v0, s2, v176
	v_readlane_b32 s2, v253, 15
	v_lshl_add_u32 v2, v0, 10, v164
	v_readlane_b32 s3, v253, 16
	s_waitcnt vmcnt(0)
	s_barrier
	v_mov_b32_e32 v134, v3
	v_lshl_add_u64 v[0:1], v[2:3], 1, s[2:3]
	global_load_dwordx2 v[132:133], v[0:1], off
	global_load_dwordx2 v[136:137], v[0:1], off offset:32
	global_load_dwordx2 v[140:141], v[0:1], off offset:256
	global_load_dwordx2 v[144:145], v[0:1], off offset:288
	v_add_u32_e32 v0, 0x4000, v2
	v_mov_b32_e32 v1, v3
	v_lshl_add_u64 v[0:1], v[0:1], 1, s[2:3]
	global_load_dwordx2 v[150:151], v[0:1], off
	global_load_dwordx2 v[178:179], v[0:1], off offset:32
	global_load_dwordx2 v[182:183], v[0:1], off offset:256
	global_load_dwordx2 v[186:187], v[0:1], off offset:288
	v_mov_b32_e32 v135, v3
	v_mov_b32_e32 v138, v3
	v_mov_b32_e32 v139, v3
	v_mov_b32_e32 v142, v3
	v_mov_b32_e32 v143, v3
	v_mov_b32_e32 v146, v3
	v_mov_b32_e32 v147, v3
	v_mov_b32_e32 v152, v3
	v_mov_b32_e32 v153, v3
	v_mov_b32_e32 v180, v3
	v_mov_b32_e32 v181, v3
	v_mov_b32_e32 v184, v3
	v_mov_b32_e32 v185, v3
	v_mov_b32_e32 v188, v3
	v_mov_b32_e32 v189, v3
	v_and_b32_e32 v149, 63, v148
	v_add_u32_e32 v0, 0x8000, v2
	v_mov_b32_e32 v1, v3
	v_lshl_add_u64 v[0:1], v[0:1], 1, s[2:3]
	global_load_dwordx2 v[200:201], v[0:1], off
	global_load_dwordx2 v[202:203], v[0:1], off offset:32
	global_load_dwordx2 v[204:205], v[0:1], off offset:256
	global_load_dwordx2 v[206:207], v[0:1], off offset:288
	v_add_u32_e32 v0, 0xc000, v2
	v_mov_b32_e32 v1, v3
	v_lshl_add_u64 v[0:1], v[0:1], 1, s[2:3]
	global_load_dwordx2 v[208:209], v[0:1], off
	global_load_dwordx2 v[210:211], v[0:1], off offset:32
	global_load_dwordx2 v[212:213], v[0:1], off offset:256
	global_load_dwordx2 v[214:215], v[0:1], off offset:288
	v_add_u32_e32 v0, 0x20000, v2
	v_mov_b32_e32 v1, v3
	v_lshl_add_u64 v[0:1], v[0:1], 1, s[2:3]
	global_load_dwordx2 v[222:223], v[0:1], off
	global_load_dwordx2 v[220:221], v[0:1], off offset:32
	global_load_dwordx2 v[218:219], v[0:1], off offset:256
	global_load_dwordx2 v[216:217], v[0:1], off offset:288
	v_add_u32_e32 v0, 0x24000, v2
	v_mov_b32_e32 v1, v3
	v_lshl_add_u64 v[0:1], v[0:1], 1, s[2:3]
	global_load_dwordx2 v[224:225], v[0:1], off
	global_load_dwordx2 v[226:227], v[0:1], off offset:32
	global_load_dwordx2 v[228:229], v[0:1], off offset:256
	global_load_dwordx2 v[230:231], v[0:1], off offset:288
	s_waitcnt vmcnt(16)
	s_nop 0
	v_cvt_f32_f16_e32 v0, v132
	v_cvt_f32_f16_sdwa v1, v132 dst_sel:DWORD dst_unused:UNUSED_PAD src0_sel:WORD_1
	v_cvt_f32_f16_e32 v132, v133
	v_cvt_f32_f16_sdwa v133, v133 dst_sel:DWORD dst_unused:UNUSED_PAD src0_sel:WORD_1
	v_mov_b32_e32 v134, v3
	v_pk_fma_f32 v[28:29], v[0:1], s[86:87], v[28:29] op_sel_hi:[1,0,1]
	v_cvt_f32_f16_e32 v0, v136
	v_pk_fma_f32 v[30:31], v[132:133], s[86:87], v[30:31] op_sel_hi:[1,0,1]
	v_cvt_f32_f16_sdwa v1, v136 dst_sel:DWORD dst_unused:UNUSED_PAD src0_sel:WORD_1
	v_cvt_f32_f16_e32 v132, v137
	v_cvt_f32_f16_sdwa v133, v137 dst_sel:DWORD dst_unused:UNUSED_PAD src0_sel:WORD_1
	v_mov_b32_e32 v135, v3
	v_pk_fma_f32 v[20:21], v[0:1], s[86:87], v[20:21] op_sel_hi:[1,0,1]
	v_cvt_f32_f16_e32 v0, v140
	v_pk_fma_f32 v[22:23], v[132:133], s[86:87], v[22:23] op_sel_hi:[1,0,1]
	v_cvt_f32_f16_sdwa v1, v140 dst_sel:DWORD dst_unused:UNUSED_PAD src0_sel:WORD_1
	v_cvt_f32_f16_e32 v132, v141
	v_cvt_f32_f16_sdwa v133, v141 dst_sel:DWORD dst_unused:UNUSED_PAD src0_sel:WORD_1
	v_mov_b32_e32 v138, v3
	v_pk_fma_f32 v[12:13], v[0:1], s[86:87], v[12:13] op_sel_hi:[1,0,1]
	v_cvt_f32_f16_e32 v0, v144
	v_pk_fma_f32 v[14:15], v[132:133], s[86:87], v[14:15] op_sel_hi:[1,0,1]
	v_cvt_f32_f16_sdwa v1, v144 dst_sel:DWORD dst_unused:UNUSED_PAD src0_sel:WORD_1
	v_cvt_f32_f16_e32 v132, v145
	v_cvt_f32_f16_sdwa v133, v145 dst_sel:DWORD dst_unused:UNUSED_PAD src0_sel:WORD_1
	v_mov_b32_e32 v139, v3
	v_pk_fma_f32 v[4:5], v[0:1], s[86:87], v[4:5] op_sel_hi:[1,0,1]
	v_cvt_f32_f16_e32 v0, v150
	v_pk_fma_f32 v[6:7], v[132:133], s[86:87], v[6:7] op_sel_hi:[1,0,1]
	v_cvt_f32_f16_sdwa v1, v150 dst_sel:DWORD dst_unused:UNUSED_PAD src0_sel:WORD_1
	v_cvt_f32_f16_e32 v132, v151
	v_cvt_f32_f16_sdwa v133, v151 dst_sel:DWORD dst_unused:UNUSED_PAD src0_sel:WORD_1
	v_pk_fma_f32 v[32:33], v[0:1], s[86:87], v[32:33] op_sel_hi:[1,0,1]
	v_cvt_f32_f16_e32 v0, v178
	v_pk_fma_f32 v[34:35], v[132:133], s[86:87], v[34:35] op_sel_hi:[1,0,1]
	v_cvt_f32_f16_sdwa v1, v178 dst_sel:DWORD dst_unused:UNUSED_PAD src0_sel:WORD_1
	v_cvt_f32_f16_e32 v132, v179
	v_cvt_f32_f16_sdwa v133, v179 dst_sel:DWORD dst_unused:UNUSED_PAD src0_sel:WORD_1
	v_mov_b32_e32 v142, v3
	v_pk_fma_f32 v[24:25], v[0:1], s[86:87], v[24:25] op_sel_hi:[1,0,1]
	v_cvt_f32_f16_e32 v0, v182
	v_pk_fma_f32 v[26:27], v[132:133], s[86:87], v[26:27] op_sel_hi:[1,0,1]
	v_cvt_f32_f16_sdwa v1, v182 dst_sel:DWORD dst_unused:UNUSED_PAD src0_sel:WORD_1
	v_cvt_f32_f16_e32 v132, v183
	v_cvt_f32_f16_sdwa v133, v183 dst_sel:DWORD dst_unused:UNUSED_PAD src0_sel:WORD_1
	v_mov_b32_e32 v143, v3
	v_pk_fma_f32 v[16:17], v[0:1], s[86:87], v[16:17] op_sel_hi:[1,0,1]
	v_cvt_f32_f16_e32 v0, v186
	v_pk_fma_f32 v[18:19], v[132:133], s[86:87], v[18:19] op_sel_hi:[1,0,1]
	v_cvt_f32_f16_sdwa v1, v186 dst_sel:DWORD dst_unused:UNUSED_PAD src0_sel:WORD_1
	v_cvt_f32_f16_e32 v132, v187
	v_cvt_f32_f16_sdwa v133, v187 dst_sel:DWORD dst_unused:UNUSED_PAD src0_sel:WORD_1
	v_mov_b32_e32 v146, v3
	v_pk_fma_f32 v[8:9], v[0:1], s[86:87], v[8:9] op_sel_hi:[1,0,1]
	v_pk_fma_f32 v[10:11], v[132:133], s[86:87], v[10:11] op_sel_hi:[1,0,1]
	v_mov_b32_e32 v147, v3
	v_mov_b32_e32 v152, v3
	v_mov_b32_e32 v153, v3
	v_mov_b32_e32 v180, v3
	v_mov_b32_e32 v181, v3
	v_mov_b32_e32 v184, v3
	v_mov_b32_e32 v185, v3
	v_mov_b32_e32 v188, v3
	v_mov_b32_e32 v189, v3
	s_waitcnt vmcnt(8)
	s_nop 0
	v_cvt_f32_f16_e32 v0, v200
	v_cvt_f32_f16_sdwa v1, v200 dst_sel:DWORD dst_unused:UNUSED_PAD src0_sel:WORD_1
	v_cvt_f32_f16_e32 v200, v201
	v_cvt_f32_f16_sdwa v201, v201 dst_sel:DWORD dst_unused:UNUSED_PAD src0_sel:WORD_1
	v_mov_b32_e32 v146, v3
	v_pk_fma_f32 v[60:61], v[0:1], s[86:87], v[60:61] op_sel_hi:[1,0,1]
	v_cvt_f32_f16_e32 v0, v202
	v_pk_fma_f32 v[62:63], v[200:201], s[86:87], v[62:63] op_sel_hi:[1,0,1]
	v_cvt_f32_f16_sdwa v1, v202 dst_sel:DWORD dst_unused:UNUSED_PAD src0_sel:WORD_1
	v_cvt_f32_f16_e32 v200, v203
	v_cvt_f32_f16_sdwa v201, v203 dst_sel:DWORD dst_unused:UNUSED_PAD src0_sel:WORD_1
	v_mov_b32_e32 v147, v3
	v_pk_fma_f32 v[52:53], v[0:1], s[86:87], v[52:53] op_sel_hi:[1,0,1]
	v_cvt_f32_f16_e32 v0, v204
	v_pk_fma_f32 v[54:55], v[200:201], s[86:87], v[54:55] op_sel_hi:[1,0,1]
	v_cvt_f32_f16_sdwa v1, v204 dst_sel:DWORD dst_unused:UNUSED_PAD src0_sel:WORD_1
	v_cvt_f32_f16_e32 v200, v205
	v_cvt_f32_f16_sdwa v201, v205 dst_sel:DWORD dst_unused:UNUSED_PAD src0_sel:WORD_1
	v_mov_b32_e32 v142, v3
	v_pk_fma_f32 v[44:45], v[0:1], s[86:87], v[44:45] op_sel_hi:[1,0,1]
	v_cvt_f32_f16_e32 v0, v206
	v_pk_fma_f32 v[46:47], v[200:201], s[86:87], v[46:47] op_sel_hi:[1,0,1]
	v_cvt_f32_f16_sdwa v1, v206 dst_sel:DWORD dst_unused:UNUSED_PAD src0_sel:WORD_1
	v_cvt_f32_f16_e32 v200, v207
	v_cvt_f32_f16_sdwa v201, v207 dst_sel:DWORD dst_unused:UNUSED_PAD src0_sel:WORD_1
	v_mov_b32_e32 v143, v3
	v_pk_fma_f32 v[36:37], v[0:1], s[86:87], v[36:37] op_sel_hi:[1,0,1]
	v_cvt_f32_f16_e32 v0, v208
	v_pk_fma_f32 v[38:39], v[200:201], s[86:87], v[38:39] op_sel_hi:[1,0,1]
	v_cvt_f32_f16_sdwa v1, v208 dst_sel:DWORD dst_unused:UNUSED_PAD src0_sel:WORD_1
	v_cvt_f32_f16_e32 v200, v209
	v_cvt_f32_f16_sdwa v201, v209 dst_sel:DWORD dst_unused:UNUSED_PAD src0_sel:WORD_1
	v_pk_fma_f32 v[64:65], v[0:1], s[86:87], v[64:65] op_sel_hi:[1,0,1]
	v_cvt_f32_f16_e32 v0, v210
	v_pk_fma_f32 v[66:67], v[200:201], s[86:87], v[66:67] op_sel_hi:[1,0,1]
	v_cvt_f32_f16_sdwa v1, v210 dst_sel:DWORD dst_unused:UNUSED_PAD src0_sel:WORD_1
	v_cvt_f32_f16_e32 v200, v211
	v_cvt_f32_f16_sdwa v201, v211 dst_sel:DWORD dst_unused:UNUSED_PAD src0_sel:WORD_1
	v_mov_b32_e32 v138, v3
	v_pk_fma_f32 v[56:57], v[0:1], s[86:87], v[56:57] op_sel_hi:[1,0,1]
	v_cvt_f32_f16_e32 v0, v212
	v_pk_fma_f32 v[58:59], v[200:201], s[86:87], v[58:59] op_sel_hi:[1,0,1]
	v_cvt_f32_f16_sdwa v1, v212 dst_sel:DWORD dst_unused:UNUSED_PAD src0_sel:WORD_1
	v_cvt_f32_f16_e32 v200, v213
	v_cvt_f32_f16_sdwa v201, v213 dst_sel:DWORD dst_unused:UNUSED_PAD src0_sel:WORD_1
	v_mov_b32_e32 v139, v3
	v_pk_fma_f32 v[48:49], v[0:1], s[86:87], v[48:49] op_sel_hi:[1,0,1]
	v_cvt_f32_f16_e32 v0, v214
	v_pk_fma_f32 v[50:51], v[200:201], s[86:87], v[50:51] op_sel_hi:[1,0,1]
	v_cvt_f32_f16_sdwa v1, v214 dst_sel:DWORD dst_unused:UNUSED_PAD src0_sel:WORD_1
	v_cvt_f32_f16_e32 v200, v215
	v_cvt_f32_f16_sdwa v201, v215 dst_sel:DWORD dst_unused:UNUSED_PAD src0_sel:WORD_1
	v_mov_b32_e32 v134, v3
	v_pk_fma_f32 v[40:41], v[0:1], s[86:87], v[40:41] op_sel_hi:[1,0,1]
	v_pk_fma_f32 v[42:43], v[200:201], s[86:87], v[42:43] op_sel_hi:[1,0,1]
	v_mov_b32_e32 v135, v3
	v_mov_b32_e32 v152, v3
	v_mov_b32_e32 v153, v3
	v_mov_b32_e32 v180, v3
	v_mov_b32_e32 v181, v3
	v_mov_b32_e32 v184, v3
	v_mov_b32_e32 v185, v3
	v_mov_b32_e32 v188, v3
	v_mov_b32_e32 v189, v3
	s_waitcnt vmcnt(0)
	s_nop 0
	v_cvt_f32_f16_e32 v0, v222
	v_cvt_f32_f16_sdwa v1, v222 dst_sel:DWORD dst_unused:UNUSED_PAD src0_sel:WORD_1
	v_cvt_f32_f16_e32 v134, v223
	v_cvt_f32_f16_sdwa v135, v223 dst_sel:DWORD dst_unused:UNUSED_PAD src0_sel:WORD_1
	v_mov_b32_e32 v142, v3
	v_pk_fma_f32 v[92:93], v[0:1], s[86:87], v[92:93] op_sel_hi:[1,0,1]
	v_cvt_f32_f16_e32 v0, v220
	v_cvt_f32_f16_sdwa v1, v220 dst_sel:DWORD dst_unused:UNUSED_PAD src0_sel:WORD_1
	v_pk_fma_f32 v[94:95], v[134:135], s[86:87], v[94:95] op_sel_hi:[1,0,1]
	v_cvt_f32_f16_e32 v134, v221
	v_cvt_f32_f16_sdwa v135, v221 dst_sel:DWORD dst_unused:UNUSED_PAD src0_sel:WORD_1
	v_pk_fma_f32 v[84:85], v[0:1], s[86:87], v[84:85] op_sel_hi:[1,0,1]
	v_cvt_f32_f16_e32 v0, v218
	v_cvt_f32_f16_sdwa v1, v218 dst_sel:DWORD dst_unused:UNUSED_PAD src0_sel:WORD_1
	v_pk_fma_f32 v[86:87], v[134:135], s[86:87], v[86:87] op_sel_hi:[1,0,1]
	v_cvt_f32_f16_e32 v134, v219
	v_cvt_f32_f16_sdwa v135, v219 dst_sel:DWORD dst_unused:UNUSED_PAD src0_sel:WORD_1
	v_pk_fma_f32 v[76:77], v[0:1], s[86:87], v[76:77] op_sel_hi:[1,0,1]
	v_cvt_f32_f16_e32 v0, v216
	v_cvt_f32_f16_sdwa v1, v216 dst_sel:DWORD dst_unused:UNUSED_PAD src0_sel:WORD_1
	v_cvt_f32_f16_e32 v216, v217
	v_cvt_f32_f16_sdwa v217, v217 dst_sel:DWORD dst_unused:UNUSED_PAD src0_sel:WORD_1
	v_pk_fma_f32 v[78:79], v[134:135], s[86:87], v[78:79] op_sel_hi:[1,0,1]
	v_pk_fma_f32 v[68:69], v[0:1], s[86:87], v[68:69] op_sel_hi:[1,0,1]
	v_cvt_f32_f16_e32 v0, v224
	v_pk_fma_f32 v[70:71], v[216:217], s[86:87], v[70:71] op_sel_hi:[1,0,1]
	v_cvt_f32_f16_sdwa v1, v224 dst_sel:DWORD dst_unused:UNUSED_PAD src0_sel:WORD_1
	v_cvt_f32_f16_e32 v216, v225
	v_cvt_f32_f16_sdwa v217, v225 dst_sel:DWORD dst_unused:UNUSED_PAD src0_sel:WORD_1
	v_pk_fma_f32 v[96:97], v[0:1], s[86:87], v[96:97] op_sel_hi:[1,0,1]
	v_cvt_f32_f16_e32 v0, v226
	v_pk_fma_f32 v[98:99], v[216:217], s[86:87], v[98:99] op_sel_hi:[1,0,1]
	v_cvt_f32_f16_sdwa v1, v226 dst_sel:DWORD dst_unused:UNUSED_PAD src0_sel:WORD_1
	v_cvt_f32_f16_e32 v216, v227
	v_cvt_f32_f16_sdwa v217, v227 dst_sel:DWORD dst_unused:UNUSED_PAD src0_sel:WORD_1
	v_mov_b32_e32 v143, v3
	v_pk_fma_f32 v[88:89], v[0:1], s[86:87], v[88:89] op_sel_hi:[1,0,1]
	v_cvt_f32_f16_e32 v0, v228
	v_pk_fma_f32 v[90:91], v[216:217], s[86:87], v[90:91] op_sel_hi:[1,0,1]
	v_cvt_f32_f16_sdwa v1, v228 dst_sel:DWORD dst_unused:UNUSED_PAD src0_sel:WORD_1
	v_cvt_f32_f16_e32 v216, v229
	v_cvt_f32_f16_sdwa v217, v229 dst_sel:DWORD dst_unused:UNUSED_PAD src0_sel:WORD_1
	v_mov_b32_e32 v138, v3
	v_pk_fma_f32 v[80:81], v[0:1], s[86:87], v[80:81] op_sel_hi:[1,0,1]
	v_cvt_f32_f16_e32 v0, v230
	v_pk_fma_f32 v[82:83], v[216:217], s[86:87], v[82:83] op_sel_hi:[1,0,1]
	v_cvt_f32_f16_sdwa v1, v230 dst_sel:DWORD dst_unused:UNUSED_PAD src0_sel:WORD_1
	v_cvt_f32_f16_e32 v216, v231
	v_cvt_f32_f16_sdwa v217, v231 dst_sel:DWORD dst_unused:UNUSED_PAD src0_sel:WORD_1
	v_mov_b32_e32 v139, v3
	v_pk_fma_f32 v[72:73], v[0:1], s[86:87], v[72:73] op_sel_hi:[1,0,1]
	v_add_u32_e32 v0, 0x28000, v2
	v_pk_fma_f32 v[74:75], v[216:217], s[86:87], v[74:75] op_sel_hi:[1,0,1]
	v_mov_b32_e32 v1, v3
	v_add_u32_e32 v2, 0x2c000, v2
	v_lshl_add_u64 v[132:133], v[0:1], 1, s[2:3]
	v_lshl_add_u64 v[134:135], v[2:3], 1, s[2:3]
	global_load_dwordx2 v[0:1], v[132:133], off
	global_load_dwordx2 v[140:141], v[132:133], off offset:32
	global_load_dwordx2 v[136:137], v[132:133], off offset:256
	s_nop 0
	global_load_dwordx2 v[132:133], v[132:133], off offset:288
	s_nop 0
	global_load_dwordx2 v[144:145], v[134:135], off
	global_load_dwordx2 v[150:151], v[134:135], off offset:32
	global_load_dwordx2 v[178:179], v[134:135], off offset:256
	global_load_dwordx2 v[182:183], v[134:135], off offset:288
	v_mov_b32_e32 v2, v3
	v_mov_b32_e32 v134, v3
	v_mov_b32_e32 v135, v3
	v_mov_b32_e32 v146, v3
	v_mov_b32_e32 v147, v3
	v_mov_b32_e32 v152, v3
	v_mov_b32_e32 v153, v3
	v_mov_b32_e32 v180, v3
	v_mov_b32_e32 v181, v3
	v_mov_b32_e32 v184, v3
	v_mov_b32_e32 v185, v3
	s_lshl_b32 s2, s14, 3
	s_add_i32 s7, s2, 0
	s_waitcnt vmcnt(7)
	v_mov_b64_e32 v[188:189], v[2:3]
	v_mov_b64_e32 v[186:187], v[0:1]
	s_waitcnt vmcnt(0)
	s_nop 0
	v_cvt_f32_f16_e32 v0, v186
	v_cvt_f32_f16_sdwa v1, v186 dst_sel:DWORD dst_unused:UNUSED_PAD src0_sel:WORD_1
	v_cvt_f32_f16_e32 v134, v187
	v_cvt_f32_f16_sdwa v135, v187 dst_sel:DWORD dst_unused:UNUSED_PAD src0_sel:WORD_1
	v_xor_b32_e32 v2, 32, v171
	v_pk_fma_f32 v[124:125], v[0:1], s[86:87], v[124:125] op_sel_hi:[1,0,1]
	v_cvt_f32_f16_e32 v0, v140
	v_cvt_f32_f16_sdwa v1, v140 dst_sel:DWORD dst_unused:UNUSED_PAD src0_sel:WORD_1
	v_pk_fma_f32 v[126:127], v[134:135], s[86:87], v[126:127] op_sel_hi:[1,0,1]
	v_cvt_f32_f16_e32 v134, v141
	v_cvt_f32_f16_sdwa v135, v141 dst_sel:DWORD dst_unused:UNUSED_PAD src0_sel:WORD_1
	v_pk_fma_f32 v[116:117], v[0:1], s[86:87], v[116:117] op_sel_hi:[1,0,1]
	v_cvt_f32_f16_e32 v0, v136
	v_cvt_f32_f16_sdwa v1, v136 dst_sel:DWORD dst_unused:UNUSED_PAD src0_sel:WORD_1
	v_pk_fma_f32 v[118:119], v[134:135], s[86:87], v[118:119] op_sel_hi:[1,0,1]
	v_cvt_f32_f16_e32 v134, v137
	v_cvt_f32_f16_sdwa v135, v137 dst_sel:DWORD dst_unused:UNUSED_PAD src0_sel:WORD_1
	v_pk_fma_f32 v[108:109], v[0:1], s[86:87], v[108:109] op_sel_hi:[1,0,1]
	v_cvt_f32_f16_e32 v0, v132
	v_cvt_f32_f16_sdwa v1, v132 dst_sel:DWORD dst_unused:UNUSED_PAD src0_sel:WORD_1
	v_cvt_f32_f16_e32 v132, v133
	v_cvt_f32_f16_sdwa v133, v133 dst_sel:DWORD dst_unused:UNUSED_PAD src0_sel:WORD_1
	v_pk_fma_f32 v[110:111], v[134:135], s[86:87], v[110:111] op_sel_hi:[1,0,1]
	v_pk_fma_f32 v[100:101], v[0:1], s[86:87], v[100:101] op_sel_hi:[1,0,1]
	v_cvt_f32_f16_e32 v0, v144
	v_cvt_f32_f16_sdwa v1, v144 dst_sel:DWORD dst_unused:UNUSED_PAD src0_sel:WORD_1
	v_pk_fma_f32 v[102:103], v[132:133], s[86:87], v[102:103] op_sel_hi:[1,0,1]
	v_cvt_f32_f16_e32 v132, v145
	v_cvt_f32_f16_sdwa v133, v145 dst_sel:DWORD dst_unused:UNUSED_PAD src0_sel:WORD_1
	v_pk_fma_f32 v[128:129], v[0:1], s[86:87], v[128:129] op_sel_hi:[1,0,1]
	v_cvt_f32_f16_e32 v0, v150
	v_cvt_f32_f16_sdwa v1, v150 dst_sel:DWORD dst_unused:UNUSED_PAD src0_sel:WORD_1
	v_pk_fma_f32 v[130:131], v[132:133], s[86:87], v[130:131] op_sel_hi:[1,0,1]
	v_cvt_f32_f16_e32 v132, v151
	v_cvt_f32_f16_sdwa v133, v151 dst_sel:DWORD dst_unused:UNUSED_PAD src0_sel:WORD_1
	v_pk_fma_f32 v[120:121], v[0:1], s[86:87], v[120:121] op_sel_hi:[1,0,1]
	v_cvt_f32_f16_e32 v0, v178
	v_cvt_f32_f16_sdwa v1, v178 dst_sel:DWORD dst_unused:UNUSED_PAD src0_sel:WORD_1
	v_pk_fma_f32 v[122:123], v[132:133], s[86:87], v[122:123] op_sel_hi:[1,0,1]
	v_cvt_f32_f16_e32 v132, v179
	v_cvt_f32_f16_sdwa v133, v179 dst_sel:DWORD dst_unused:UNUSED_PAD src0_sel:WORD_1
	v_pk_fma_f32 v[112:113], v[0:1], s[86:87], v[112:113] op_sel_hi:[1,0,1]
	v_cvt_f32_f16_e32 v0, v182
	v_cvt_f32_f16_sdwa v1, v182 dst_sel:DWORD dst_unused:UNUSED_PAD src0_sel:WORD_1
	v_pk_fma_f32 v[114:115], v[132:133], s[86:87], v[114:115] op_sel_hi:[1,0,1]
	v_cvt_f32_f16_e32 v132, v183
	v_cvt_f32_f16_sdwa v133, v183 dst_sel:DWORD dst_unused:UNUSED_PAD src0_sel:WORD_1
	v_pk_fma_f32 v[104:105], v[0:1], s[86:87], v[104:105] op_sel_hi:[1,0,1]
	v_and_b32_e32 v1, 64, v171
	v_xor_b32_e32 v0, 16, v171
	v_pk_fma_f32 v[106:107], v[132:133], s[86:87], v[106:107] op_sel_hi:[1,0,1]
	v_add_u32_e32 v1, 64, v1
	v_mov_b32_e32 v132, v29
	v_mov_b32_e32 v133, v30
	v_mov_b32_e32 v134, v28
	v_mov_b32_e32 v135, v31
	v_cmp_lt_i32_e32 vcc, v0, v1
	v_pk_add_f32 v[132:133], v[132:133], v[134:135]
	v_mov_b32_e32 v134, v21
	v_mov_b32_e32 v135, v22
	v_mov_b32_e32 v136, v20
	v_mov_b32_e32 v137, v23
	v_cndmask_b32_e32 v0, v171, v0, vcc
	v_cmp_lt_i32_e32 vcc, v2, v1
	v_pk_add_f32 v[134:135], v[134:135], v[136:137]
	v_add_f32_e32 v137, v12, v13
	v_cndmask_b32_e32 v1, v171, v2, vcc
	v_add_f32_e32 v2, v132, v133
	v_pk_add_f32 v[134:135], v[134:135], v[134:135] op_sel_hi:[0,1]
	v_add_f32_e32 v133, 0, v2
	v_add_f32_e32 v139, v14, v15
	v_mov_b32_e32 v136, v4
	v_mov_b32_e32 v138, v5
	v_mov_b32_e32 v134, v6
	v_mov_b32_e32 v132, v7
	v_pk_add_f32 v[136:137], v[136:137], v[138:139]
	v_pk_add_f32 v[132:133], v[134:135], v[132:133]
	v_lshlrev_b32_e32 v0, 2, v0
	v_pk_add_f32 v[132:133], v[136:137], v[132:133]
	v_lshlrev_b32_e32 v1, 2, v1
	v_add_f32_e32 v2, v132, v133
	v_mov_b32_e32 v132, v2
	s_nop 1
	v_permlane16_swap_b32 v2, v132
	v_cmp_gt_u32_e32 vcc, 16, v149
	s_waitcnt lgkmcnt(0)
	v_add_f32_e32 v2, v2, v132
	v_mov_b32_e32 v132, v2
	s_nop 1
	v_permlane32_swap_b32 v2, v132
	s_waitcnt lgkmcnt(0)
	v_add_f32_e32 v2, v2, v132
	v_fmamk_f32 v133, v2, 0xbc800000, v31
	v_fmamk_f32 v135, v2, 0xbc800000, v29
	v_fmamk_f32 v132, v2, 0xbc800000, v30
	v_fmamk_f32 v134, v2, 0xbc800000, v28
	v_mul_f32_e32 v135, v135, v135
	v_mul_f32_e32 v133, v133, v133
	v_fmac_f32_e32 v135, v134, v134
	v_fmac_f32_e32 v133, v132, v132
	v_fmamk_f32 v134, v2, 0xbc800000, v23
	v_fmamk_f32 v136, v2, 0xbc800000, v21
	v_add_f32_e32 v132, v135, v133
	v_fmamk_f32 v133, v2, 0xbc800000, v22
	v_fmamk_f32 v135, v2, 0xbc800000, v20
	v_mul_f32_e32 v136, v136, v136
	v_mul_f32_e32 v134, v134, v134
	v_fmac_f32_e32 v136, v135, v135
	v_fmac_f32_e32 v134, v133, v133
	v_add_f32_e32 v133, v136, v134
	v_fmamk_f32 v134, v2, 0xbc800000, v15
	v_fmamk_f32 v136, v2, 0xbc800000, v13
	v_add_f32_e32 v132, v132, v133
	v_fmamk_f32 v133, v2, 0xbc800000, v14
	v_fmamk_f32 v135, v2, 0xbc800000, v12
	v_mul_f32_e32 v136, v136, v136
	v_mul_f32_e32 v134, v134, v134
	v_fmac_f32_e32 v136, v135, v135
	v_fmac_f32_e32 v134, v133, v133
	v_add_f32_e32 v133, v136, v134
	v_fmamk_f32 v134, v2, 0xbc800000, v7
	v_fmamk_f32 v136, v2, 0xbc800000, v5
	v_add_f32_e32 v132, v133, v132
	v_fmamk_f32 v133, v2, 0xbc800000, v6
	v_fmamk_f32 v135, v2, 0xbc800000, v4
	v_mul_f32_e32 v136, v136, v136
	v_mul_f32_e32 v134, v134, v134
	v_fmac_f32_e32 v136, v135, v135
	v_fmac_f32_e32 v134, v133, v133
	v_add_f32_e32 v133, v136, v134
	v_add_f32_e32 v132, v133, v132
	v_mov_b32_e32 v133, v132
	s_nop 1
	v_permlane16_swap_b32 v132, v133
	s_waitcnt lgkmcnt(0)
	v_add_f32_e32 v132, v132, v133
	ds_bpermute_b32 v133, v1, v132
	s_and_saveexec_b64 s[4:5], vcc
	s_cbranch_execz .LBB0_440
	s_lshl_b32 s2, s80, 11
	s_add_i32 s2, s7, s2
	v_mul_f32_e32 v134, 0x3c800000, v2
	s_waitcnt lgkmcnt(0)
	v_add_f32_e32 v135, v132, v133
	v_lshl_add_u32 v2, v176, 5, s2
	ds_write_b64 v2, v[134:135]
.LBB0_440:
	s_or_b64 exec, exec, s[4:5]
	v_mov_b32_e32 v132, v33
	s_waitcnt lgkmcnt(0)
	v_mov_b32_e32 v133, v34
	v_mov_b32_e32 v134, v32
	v_mov_b32_e32 v135, v35
	v_pk_add_f32 v[132:133], v[132:133], v[134:135]
	v_mov_b32_e32 v134, v25
	v_mov_b32_e32 v135, v26
	v_mov_b32_e32 v136, v24
	v_mov_b32_e32 v137, v27
	v_pk_add_f32 v[134:135], v[134:135], v[136:137]
	v_add_f32_e32 v2, v132, v133
	v_pk_add_f32 v[134:135], v[134:135], v[134:135] op_sel_hi:[0,1]
	v_add_f32_e32 v133, 0, v2
	v_add_f32_e32 v137, v16, v17
	v_add_f32_e32 v139, v18, v19
	v_mov_b32_e32 v136, v8
	v_mov_b32_e32 v138, v9
	v_mov_b32_e32 v134, v10
	v_mov_b32_e32 v132, v11
	v_pk_add_f32 v[136:137], v[136:137], v[138:139]
	v_pk_add_f32 v[132:133], v[134:135], v[132:133]
	s_nop 0
	v_pk_add_f32 v[132:133], v[136:137], v[132:133]
	s_nop 0
	v_add_f32_e32 v2, v132, v133
	v_mov_b32_e32 v132, v2
	s_nop 1
	v_permlane16_swap_b32 v2, v132
	s_waitcnt lgkmcnt(0)
	v_add_f32_e32 v2, v2, v132
	v_mov_b32_e32 v132, v2
	s_nop 1
	v_permlane32_swap_b32 v2, v132
	s_waitcnt lgkmcnt(0)
	v_add_f32_e32 v2, v2, v132
	v_fmamk_f32 v133, v2, 0xbc800000, v35
	v_fmamk_f32 v135, v2, 0xbc800000, v33
	v_fmamk_f32 v132, v2, 0xbc800000, v34
	v_fmamk_f32 v134, v2, 0xbc800000, v32
	v_mul_f32_e32 v135, v135, v135
	v_mul_f32_e32 v133, v133, v133
	v_fmac_f32_e32 v135, v134, v134
	v_fmac_f32_e32 v133, v132, v132
	v_fmamk_f32 v134, v2, 0xbc800000, v27
	v_fmamk_f32 v136, v2, 0xbc800000, v25
	v_add_f32_e32 v132, v135, v133
	v_fmamk_f32 v133, v2, 0xbc800000, v26
	v_fmamk_f32 v135, v2, 0xbc800000, v24
	v_mul_f32_e32 v136, v136, v136
	v_mul_f32_e32 v134, v134, v134
	v_fmac_f32_e32 v136, v135, v135
	v_fmac_f32_e32 v134, v133, v133
	v_add_f32_e32 v133, v136, v134
	v_fmamk_f32 v134, v2, 0xbc800000, v19
	v_fmamk_f32 v136, v2, 0xbc800000, v17
	v_add_f32_e32 v132, v132, v133
	v_fmamk_f32 v133, v2, 0xbc800000, v18
	v_fmamk_f32 v135, v2, 0xbc800000, v16
	v_mul_f32_e32 v136, v136, v136
	v_mul_f32_e32 v134, v134, v134
	v_fmac_f32_e32 v136, v135, v135
	v_fmac_f32_e32 v134, v133, v133
	v_add_f32_e32 v133, v136, v134
	v_fmamk_f32 v134, v2, 0xbc800000, v11
	v_fmamk_f32 v136, v2, 0xbc800000, v9
	v_add_f32_e32 v132, v133, v132
	v_fmamk_f32 v133, v2, 0xbc800000, v10
	v_fmamk_f32 v135, v2, 0xbc800000, v8
	v_mul_f32_e32 v136, v136, v136
	v_mul_f32_e32 v134, v134, v134
	v_fmac_f32_e32 v136, v135, v135
	v_fmac_f32_e32 v134, v133, v133
	v_add_f32_e32 v133, v136, v134
	v_add_f32_e32 v132, v133, v132
	v_mov_b32_e32 v133, v132
	s_nop 1
	v_permlane16_swap_b32 v132, v133
	s_waitcnt lgkmcnt(0)
	v_add_f32_e32 v132, v132, v133
	ds_bpermute_b32 v133, v1, v132
	s_and_saveexec_b64 s[4:5], vcc
	v_readlane_b32 s56, v253, 19
	v_readlane_b32 s16, v253, 21
	v_readlane_b32 s57, v253, 20
	v_readlane_b32 s17, v253, 22
	s_cbranch_execz .LBB0_442
	s_lshl_b32 s2, s80, 11
	s_add_i32 s2, s7, s2
	v_mul_f32_e32 v134, 0x3c800000, v2
	s_waitcnt lgkmcnt(0)
	v_add_f32_e32 v135, v132, v133
	v_lshl_add_u32 v2, v176, 5, s2
	ds_write_b64 v2, v[134:135] offset:512
.LBB0_442:
	s_or_b64 exec, exec, s[4:5]
	v_mov_b32_e32 v132, v61
	s_waitcnt lgkmcnt(0)
	v_mov_b32_e32 v133, v62
	v_mov_b32_e32 v134, v60
	v_mov_b32_e32 v135, v63
	v_pk_add_f32 v[132:133], v[132:133], v[134:135]
	v_mov_b32_e32 v134, v53
	v_mov_b32_e32 v135, v54
	v_mov_b32_e32 v136, v52
	v_mov_b32_e32 v137, v55
	v_pk_add_f32 v[134:135], v[134:135], v[136:137]
	v_add_f32_e32 v2, v132, v133
	v_pk_add_f32 v[134:135], v[134:135], v[134:135] op_sel_hi:[0,1]
	v_add_f32_e32 v133, 0, v2
	v_add_f32_e32 v137, v44, v45
	v_add_f32_e32 v139, v46, v47
	v_mov_b32_e32 v136, v36
	v_mov_b32_e32 v138, v37
	v_mov_b32_e32 v134, v38
	v_mov_b32_e32 v132, v39
	v_pk_add_f32 v[136:137], v[136:137], v[138:139]
	v_pk_add_f32 v[132:133], v[134:135], v[132:133]
	s_nop 0
	v_pk_add_f32 v[132:133], v[136:137], v[132:133]
	s_nop 0
	v_add_f32_e32 v2, v132, v133
	v_mov_b32_e32 v132, v2
	s_nop 1
	v_permlane16_swap_b32 v2, v132
	s_waitcnt lgkmcnt(0)
	v_add_f32_e32 v2, v2, v132
	v_mov_b32_e32 v132, v2
	s_nop 1
	v_permlane32_swap_b32 v2, v132
	s_waitcnt lgkmcnt(0)
	v_add_f32_e32 v2, v2, v132
	v_fmamk_f32 v133, v2, 0xbc800000, v63
	v_fmamk_f32 v135, v2, 0xbc800000, v61
	v_fmamk_f32 v132, v2, 0xbc800000, v62
	v_fmamk_f32 v134, v2, 0xbc800000, v60
	v_mul_f32_e32 v135, v135, v135
	v_mul_f32_e32 v133, v133, v133
	v_fmac_f32_e32 v135, v134, v134
	v_fmac_f32_e32 v133, v132, v132
	v_fmamk_f32 v134, v2, 0xbc800000, v55
	v_fmamk_f32 v136, v2, 0xbc800000, v53
	v_add_f32_e32 v132, v135, v133
	v_fmamk_f32 v133, v2, 0xbc800000, v54
	v_fmamk_f32 v135, v2, 0xbc800000, v52
	v_mul_f32_e32 v136, v136, v136
	v_mul_f32_e32 v134, v134, v134
	v_fmac_f32_e32 v136, v135, v135
	v_fmac_f32_e32 v134, v133, v133
	v_add_f32_e32 v133, v136, v134
	v_fmamk_f32 v134, v2, 0xbc800000, v47
	v_fmamk_f32 v136, v2, 0xbc800000, v45
	v_add_f32_e32 v132, v132, v133
	v_fmamk_f32 v133, v2, 0xbc800000, v46
	v_fmamk_f32 v135, v2, 0xbc800000, v44
	v_mul_f32_e32 v136, v136, v136
	v_mul_f32_e32 v134, v134, v134
	v_fmac_f32_e32 v136, v135, v135
	v_fmac_f32_e32 v134, v133, v133
	v_add_f32_e32 v133, v136, v134
	v_fmamk_f32 v134, v2, 0xbc800000, v39
	v_fmamk_f32 v136, v2, 0xbc800000, v37
	v_add_f32_e32 v132, v133, v132
	v_fmamk_f32 v133, v2, 0xbc800000, v38
	v_fmamk_f32 v135, v2, 0xbc800000, v36
	v_mul_f32_e32 v136, v136, v136
	v_mul_f32_e32 v134, v134, v134
	v_fmac_f32_e32 v136, v135, v135
	v_fmac_f32_e32 v134, v133, v133
	v_add_f32_e32 v133, v136, v134
	v_add_f32_e32 v132, v133, v132
	v_mov_b32_e32 v133, v132
	s_nop 1
	v_permlane16_swap_b32 v132, v133
	s_waitcnt lgkmcnt(0)
	v_add_f32_e32 v132, v132, v133
	ds_bpermute_b32 v133, v1, v132
	s_and_saveexec_b64 s[4:5], vcc
	s_cbranch_execz .LBB0_444
	s_lshl_b32 s2, s80, 11
	s_add_i32 s2, s7, s2
	v_mul_f32_e32 v134, 0x3c800000, v2
	s_waitcnt lgkmcnt(0)
	v_add_f32_e32 v135, v132, v133
	v_lshl_add_u32 v2, v176, 5, s2
	ds_write_b64 v2, v[134:135] offset:1024
.LBB0_444:
	s_or_b64 exec, exec, s[4:5]
	v_mov_b32_e32 v132, v65
	s_waitcnt lgkmcnt(0)
	v_mov_b32_e32 v133, v66
	v_mov_b32_e32 v134, v64
	v_mov_b32_e32 v135, v67
	v_pk_add_f32 v[132:133], v[132:133], v[134:135]
	v_mov_b32_e32 v134, v57
	v_mov_b32_e32 v135, v58
	v_mov_b32_e32 v136, v56
	v_mov_b32_e32 v137, v59
	v_pk_add_f32 v[134:135], v[134:135], v[136:137]
	v_add_f32_e32 v2, v132, v133
	v_pk_add_f32 v[134:135], v[134:135], v[134:135] op_sel_hi:[0,1]
	v_add_f32_e32 v133, 0, v2
	v_add_f32_e32 v137, v48, v49
	v_add_f32_e32 v139, v50, v51
	v_mov_b32_e32 v136, v40
	v_mov_b32_e32 v138, v41
	v_mov_b32_e32 v134, v42
	v_mov_b32_e32 v132, v43
	v_pk_add_f32 v[136:137], v[136:137], v[138:139]
	v_pk_add_f32 v[132:133], v[134:135], v[132:133]
	s_nop 0
	v_pk_add_f32 v[132:133], v[136:137], v[132:133]
	s_nop 0
	v_add_f32_e32 v2, v132, v133
	v_mov_b32_e32 v132, v2
	s_nop 1
	v_permlane16_swap_b32 v2, v132
	s_waitcnt lgkmcnt(0)
	v_add_f32_e32 v2, v2, v132
	v_mov_b32_e32 v132, v2
	s_nop 1
	v_permlane32_swap_b32 v2, v132
	s_waitcnt lgkmcnt(0)
	v_add_f32_e32 v2, v2, v132
	v_fmamk_f32 v133, v2, 0xbc800000, v67
	v_fmamk_f32 v135, v2, 0xbc800000, v65
	v_fmamk_f32 v132, v2, 0xbc800000, v66
	v_fmamk_f32 v134, v2, 0xbc800000, v64
	v_mul_f32_e32 v135, v135, v135
	v_mul_f32_e32 v133, v133, v133
	v_fmac_f32_e32 v135, v134, v134
	v_fmac_f32_e32 v133, v132, v132
	v_fmamk_f32 v134, v2, 0xbc800000, v59
	v_fmamk_f32 v136, v2, 0xbc800000, v57
	v_add_f32_e32 v132, v135, v133
	v_fmamk_f32 v133, v2, 0xbc800000, v58
	v_fmamk_f32 v135, v2, 0xbc800000, v56
	v_mul_f32_e32 v136, v136, v136
	v_mul_f32_e32 v134, v134, v134
	v_fmac_f32_e32 v136, v135, v135
	v_fmac_f32_e32 v134, v133, v133
	v_add_f32_e32 v133, v136, v134
	v_fmamk_f32 v134, v2, 0xbc800000, v51
	v_fmamk_f32 v136, v2, 0xbc800000, v49
	v_add_f32_e32 v132, v132, v133
	v_fmamk_f32 v133, v2, 0xbc800000, v50
	v_fmamk_f32 v135, v2, 0xbc800000, v48
	v_mul_f32_e32 v136, v136, v136
	v_mul_f32_e32 v134, v134, v134
	v_fmac_f32_e32 v136, v135, v135
	v_fmac_f32_e32 v134, v133, v133
	v_add_f32_e32 v133, v136, v134
	v_fmamk_f32 v134, v2, 0xbc800000, v43
	v_fmamk_f32 v136, v2, 0xbc800000, v41
	v_add_f32_e32 v132, v133, v132
	v_fmamk_f32 v133, v2, 0xbc800000, v42
	v_fmamk_f32 v135, v2, 0xbc800000, v40
	v_mul_f32_e32 v136, v136, v136
	v_mul_f32_e32 v134, v134, v134
	v_fmac_f32_e32 v136, v135, v135
	v_fmac_f32_e32 v134, v133, v133
	v_add_f32_e32 v133, v136, v134
	v_add_f32_e32 v132, v133, v132
	v_mov_b32_e32 v133, v132
	s_nop 1
	v_permlane16_swap_b32 v132, v133
	s_waitcnt lgkmcnt(0)
	v_add_f32_e32 v132, v132, v133
	ds_bpermute_b32 v133, v1, v132
	s_and_saveexec_b64 s[4:5], vcc
	s_cbranch_execz .LBB0_446
	s_lshl_b32 s2, s80, 11
	s_add_i32 s2, s7, s2
	v_mul_f32_e32 v134, 0x3c800000, v2
	s_waitcnt lgkmcnt(0)
	v_add_f32_e32 v135, v132, v133
	v_lshl_add_u32 v2, v176, 5, s2
	ds_write_b64 v2, v[134:135] offset:1536
.LBB0_446:
	s_or_b64 exec, exec, s[4:5]
	v_mov_b32_e32 v132, v93
	s_waitcnt lgkmcnt(0)
	v_mov_b32_e32 v133, v94
	v_mov_b32_e32 v134, v92
	v_mov_b32_e32 v135, v95
	v_pk_add_f32 v[132:133], v[132:133], v[134:135]
	v_mov_b32_e32 v134, v85
	v_mov_b32_e32 v135, v86
	v_mov_b32_e32 v136, v84
	v_mov_b32_e32 v137, v87
	v_pk_add_f32 v[134:135], v[134:135], v[136:137]
	v_add_f32_e32 v2, v132, v133
	v_pk_add_f32 v[134:135], v[134:135], v[134:135] op_sel_hi:[0,1]
	v_add_f32_e32 v133, 0, v2
	v_add_f32_e32 v137, v76, v77
	v_add_f32_e32 v139, v78, v79
	v_mov_b32_e32 v136, v68
	v_mov_b32_e32 v138, v69
	v_mov_b32_e32 v134, v70
	v_mov_b32_e32 v132, v71
	v_pk_add_f32 v[136:137], v[136:137], v[138:139]
	v_pk_add_f32 v[132:133], v[134:135], v[132:133]
	s_nop 0
	v_pk_add_f32 v[132:133], v[136:137], v[132:133]
	s_nop 0
	v_add_f32_e32 v2, v132, v133
	v_mov_b32_e32 v132, v2
	s_nop 1
	v_permlane16_swap_b32 v2, v132
	s_waitcnt lgkmcnt(0)
	v_add_f32_e32 v2, v2, v132
	v_mov_b32_e32 v132, v2
	s_nop 1
	v_permlane32_swap_b32 v2, v132
	s_waitcnt lgkmcnt(0)
	v_add_f32_e32 v2, v2, v132
	v_fmamk_f32 v133, v2, 0xbc800000, v95
	v_fmamk_f32 v135, v2, 0xbc800000, v93
	v_fmamk_f32 v132, v2, 0xbc800000, v94
	v_fmamk_f32 v134, v2, 0xbc800000, v92
	v_mul_f32_e32 v135, v135, v135
	v_mul_f32_e32 v133, v133, v133
	v_fmac_f32_e32 v135, v134, v134
	v_fmac_f32_e32 v133, v132, v132
	v_fmamk_f32 v134, v2, 0xbc800000, v87
	v_fmamk_f32 v136, v2, 0xbc800000, v85
	v_add_f32_e32 v132, v135, v133
	v_fmamk_f32 v133, v2, 0xbc800000, v86
	v_fmamk_f32 v135, v2, 0xbc800000, v84
	v_mul_f32_e32 v136, v136, v136
	v_mul_f32_e32 v134, v134, v134
	v_fmac_f32_e32 v136, v135, v135
	v_fmac_f32_e32 v134, v133, v133
	v_add_f32_e32 v133, v136, v134
	v_fmamk_f32 v134, v2, 0xbc800000, v79
	v_fmamk_f32 v136, v2, 0xbc800000, v77
	v_add_f32_e32 v132, v132, v133
	v_fmamk_f32 v133, v2, 0xbc800000, v78
	v_fmamk_f32 v135, v2, 0xbc800000, v76
	v_mul_f32_e32 v136, v136, v136
	v_mul_f32_e32 v134, v134, v134
	v_fmac_f32_e32 v136, v135, v135
	v_fmac_f32_e32 v134, v133, v133
	v_add_f32_e32 v133, v136, v134
	v_fmamk_f32 v134, v2, 0xbc800000, v71
	v_fmamk_f32 v136, v2, 0xbc800000, v69
	v_add_f32_e32 v132, v133, v132
	v_fmamk_f32 v133, v2, 0xbc800000, v70
	v_fmamk_f32 v135, v2, 0xbc800000, v68
	v_mul_f32_e32 v136, v136, v136
	v_mul_f32_e32 v134, v134, v134
	v_fmac_f32_e32 v136, v135, v135
	v_fmac_f32_e32 v134, v133, v133
	v_add_f32_e32 v133, v136, v134
	v_add_f32_e32 v132, v133, v132
	v_mov_b32_e32 v133, v132
	s_nop 1
	v_permlane16_swap_b32 v132, v133
	s_waitcnt lgkmcnt(0)
	v_add_f32_e32 v132, v132, v133
	ds_bpermute_b32 v133, v1, v132
	s_and_saveexec_b64 s[4:5], vcc
	s_cbranch_execz .LBB0_448
	s_lshl_b32 s2, s80, 11
	s_add_i32 s2, s7, s2
	v_mul_f32_e32 v134, 0x3c800000, v2
	s_waitcnt lgkmcnt(0)
	v_add_f32_e32 v135, v132, v133
	v_lshl_add_u32 v2, v176, 5, s2
	ds_write_b64 v2, v[134:135] offset:4096
.LBB0_448:
	s_or_b64 exec, exec, s[4:5]
	v_mov_b32_e32 v132, v97
	s_waitcnt lgkmcnt(0)
	v_mov_b32_e32 v133, v98
	v_mov_b32_e32 v134, v96
	v_mov_b32_e32 v135, v99
	v_pk_add_f32 v[132:133], v[132:133], v[134:135]
	v_mov_b32_e32 v134, v89
	v_mov_b32_e32 v135, v90
	v_mov_b32_e32 v136, v88
	v_mov_b32_e32 v137, v91
	v_pk_add_f32 v[134:135], v[134:135], v[136:137]
	v_add_f32_e32 v2, v132, v133
	v_pk_add_f32 v[134:135], v[134:135], v[134:135] op_sel_hi:[0,1]
	v_add_f32_e32 v133, 0, v2
	v_add_f32_e32 v137, v80, v81
	v_add_f32_e32 v139, v82, v83
	v_mov_b32_e32 v136, v72
	v_mov_b32_e32 v138, v73
	v_mov_b32_e32 v134, v74
	v_mov_b32_e32 v132, v75
	v_pk_add_f32 v[136:137], v[136:137], v[138:139]
	v_pk_add_f32 v[132:133], v[134:135], v[132:133]
	s_nop 0
	v_pk_add_f32 v[132:133], v[136:137], v[132:133]
	s_nop 0
	v_add_f32_e32 v2, v132, v133
	v_mov_b32_e32 v132, v2
	s_nop 1
	v_permlane16_swap_b32 v2, v132
	s_waitcnt lgkmcnt(0)
	v_add_f32_e32 v2, v2, v132
	v_mov_b32_e32 v132, v2
	s_nop 1
	v_permlane32_swap_b32 v2, v132
	s_waitcnt lgkmcnt(0)
	v_add_f32_e32 v2, v2, v132
	v_fmamk_f32 v133, v2, 0xbc800000, v99
	v_fmamk_f32 v135, v2, 0xbc800000, v97
	v_fmamk_f32 v132, v2, 0xbc800000, v98
	v_fmamk_f32 v134, v2, 0xbc800000, v96
	v_mul_f32_e32 v135, v135, v135
	v_mul_f32_e32 v133, v133, v133
	v_fmac_f32_e32 v135, v134, v134
	v_fmac_f32_e32 v133, v132, v132
	v_fmamk_f32 v134, v2, 0xbc800000, v91
	v_fmamk_f32 v136, v2, 0xbc800000, v89
	v_add_f32_e32 v132, v135, v133
	v_fmamk_f32 v133, v2, 0xbc800000, v90
	v_fmamk_f32 v135, v2, 0xbc800000, v88
	v_mul_f32_e32 v136, v136, v136
	v_mul_f32_e32 v134, v134, v134
	v_fmac_f32_e32 v136, v135, v135
	v_fmac_f32_e32 v134, v133, v133
	v_add_f32_e32 v133, v136, v134
	v_fmamk_f32 v134, v2, 0xbc800000, v83
	v_fmamk_f32 v136, v2, 0xbc800000, v81
	v_add_f32_e32 v132, v132, v133
	v_fmamk_f32 v133, v2, 0xbc800000, v82
	v_fmamk_f32 v135, v2, 0xbc800000, v80
	v_mul_f32_e32 v136, v136, v136
	v_mul_f32_e32 v134, v134, v134
	v_fmac_f32_e32 v136, v135, v135
	v_fmac_f32_e32 v134, v133, v133
	v_add_f32_e32 v133, v136, v134
	v_fmamk_f32 v134, v2, 0xbc800000, v75
	v_fmamk_f32 v136, v2, 0xbc800000, v73
	v_add_f32_e32 v132, v133, v132
	v_fmamk_f32 v133, v2, 0xbc800000, v74
	v_fmamk_f32 v135, v2, 0xbc800000, v72
	v_mul_f32_e32 v136, v136, v136
	v_mul_f32_e32 v134, v134, v134
	v_fmac_f32_e32 v136, v135, v135
	v_fmac_f32_e32 v134, v133, v133
	v_add_f32_e32 v133, v136, v134
	v_add_f32_e32 v132, v133, v132
	v_mov_b32_e32 v133, v132
	s_nop 1
	v_permlane16_swap_b32 v132, v133
	s_waitcnt lgkmcnt(0)
	v_add_f32_e32 v132, v132, v133
	ds_bpermute_b32 v133, v1, v132
	s_and_saveexec_b64 s[4:5], vcc
	s_cbranch_execz .LBB0_450
	s_lshl_b32 s2, s80, 11
	s_add_i32 s2, s7, s2
	v_mul_f32_e32 v134, 0x3c800000, v2
	s_waitcnt lgkmcnt(0)
	v_add_f32_e32 v135, v132, v133
	v_lshl_add_u32 v2, v176, 5, s2
	ds_write_b64 v2, v[134:135] offset:4608
.LBB0_450:
	s_or_b64 exec, exec, s[4:5]
	v_mov_b32_e32 v132, v125
	s_waitcnt lgkmcnt(0)
	v_mov_b32_e32 v133, v126
	v_mov_b32_e32 v134, v124
	v_mov_b32_e32 v135, v127
	v_pk_add_f32 v[132:133], v[132:133], v[134:135]
	v_mov_b32_e32 v134, v117
	v_mov_b32_e32 v135, v118
	v_mov_b32_e32 v136, v116
	v_mov_b32_e32 v137, v119
	v_pk_add_f32 v[134:135], v[134:135], v[136:137]
	v_add_f32_e32 v2, v132, v133
	v_pk_add_f32 v[134:135], v[134:135], v[134:135] op_sel_hi:[0,1]
	v_add_f32_e32 v133, 0, v2
	v_add_f32_e32 v137, v108, v109
	v_add_f32_e32 v139, v110, v111
	v_mov_b32_e32 v136, v100
	v_mov_b32_e32 v138, v101
	v_mov_b32_e32 v134, v102
	v_mov_b32_e32 v132, v103
	v_pk_add_f32 v[136:137], v[136:137], v[138:139]
	v_pk_add_f32 v[132:133], v[134:135], v[132:133]
	s_nop 0
	v_pk_add_f32 v[132:133], v[136:137], v[132:133]
	s_nop 0
	v_add_f32_e32 v2, v132, v133
	v_mov_b32_e32 v132, v2
	s_nop 1
	v_permlane16_swap_b32 v2, v132
	s_waitcnt lgkmcnt(0)
	v_add_f32_e32 v2, v2, v132
	v_mov_b32_e32 v132, v2
	s_nop 1
	v_permlane32_swap_b32 v2, v132
	s_waitcnt lgkmcnt(0)
	v_add_f32_e32 v2, v2, v132
	v_fmamk_f32 v133, v2, 0xbc800000, v127
	v_fmamk_f32 v135, v2, 0xbc800000, v125
	v_fmamk_f32 v132, v2, 0xbc800000, v126
	v_fmamk_f32 v134, v2, 0xbc800000, v124
	v_mul_f32_e32 v135, v135, v135
	v_mul_f32_e32 v133, v133, v133
	v_fmac_f32_e32 v135, v134, v134
	v_fmac_f32_e32 v133, v132, v132
	v_fmamk_f32 v134, v2, 0xbc800000, v119
	v_fmamk_f32 v136, v2, 0xbc800000, v117
	v_add_f32_e32 v132, v135, v133
	v_fmamk_f32 v133, v2, 0xbc800000, v118
	v_fmamk_f32 v135, v2, 0xbc800000, v116
	v_mul_f32_e32 v136, v136, v136
	v_mul_f32_e32 v134, v134, v134
	v_fmac_f32_e32 v136, v135, v135
	v_fmac_f32_e32 v134, v133, v133
	v_add_f32_e32 v133, v136, v134
	v_fmamk_f32 v134, v2, 0xbc800000, v111
	v_fmamk_f32 v136, v2, 0xbc800000, v109
	v_add_f32_e32 v132, v132, v133
	v_fmamk_f32 v133, v2, 0xbc800000, v110
	v_fmamk_f32 v135, v2, 0xbc800000, v108
	v_mul_f32_e32 v136, v136, v136
	v_mul_f32_e32 v134, v134, v134
	v_fmac_f32_e32 v136, v135, v135
	v_fmac_f32_e32 v134, v133, v133
	v_add_f32_e32 v133, v136, v134
	v_fmamk_f32 v134, v2, 0xbc800000, v103
	v_fmamk_f32 v136, v2, 0xbc800000, v101
	v_add_f32_e32 v132, v133, v132
	v_fmamk_f32 v133, v2, 0xbc800000, v102
	v_fmamk_f32 v135, v2, 0xbc800000, v100
	v_mul_f32_e32 v136, v136, v136
	v_mul_f32_e32 v134, v134, v134
	v_fmac_f32_e32 v136, v135, v135
	v_fmac_f32_e32 v134, v133, v133
	v_add_f32_e32 v133, v136, v134
	v_add_f32_e32 v132, v133, v132
	v_mov_b32_e32 v133, v132
	s_nop 1
	v_permlane16_swap_b32 v132, v133
	s_waitcnt lgkmcnt(0)
	v_add_f32_e32 v132, v132, v133
	ds_bpermute_b32 v133, v1, v132
	s_and_saveexec_b64 s[4:5], vcc
	s_cbranch_execz .LBB0_452
	s_lshl_b32 s2, s80, 11
	s_add_i32 s2, s7, s2
	v_mul_f32_e32 v134, 0x3c800000, v2
	s_waitcnt lgkmcnt(0)
	v_add_f32_e32 v135, v132, v133
	v_lshl_add_u32 v2, v176, 5, s2
	ds_write_b64 v2, v[134:135] offset:5120
.LBB0_452:
	s_or_b64 exec, exec, s[4:5]
	v_mov_b32_e32 v132, v129
	s_waitcnt lgkmcnt(0)
	v_mov_b32_e32 v133, v130
	v_mov_b32_e32 v134, v128
	v_mov_b32_e32 v135, v131
	v_pk_add_f32 v[132:133], v[132:133], v[134:135]
	v_mov_b32_e32 v134, v121
	v_mov_b32_e32 v135, v122
	v_mov_b32_e32 v136, v120
	v_mov_b32_e32 v137, v123
	v_pk_add_f32 v[134:135], v[134:135], v[136:137]
	v_add_f32_e32 v2, v132, v133
	v_pk_add_f32 v[134:135], v[134:135], v[134:135] op_sel_hi:[0,1]
	v_add_f32_e32 v133, 0, v2
	v_add_f32_e32 v137, v112, v113
	v_add_f32_e32 v139, v114, v115
	v_mov_b32_e32 v136, v104
	v_mov_b32_e32 v138, v105
	v_mov_b32_e32 v134, v106
	v_mov_b32_e32 v132, v107
	v_pk_add_f32 v[136:137], v[136:137], v[138:139]
	v_pk_add_f32 v[132:133], v[134:135], v[132:133]
	s_nop 0
	v_pk_add_f32 v[132:133], v[136:137], v[132:133]
	s_nop 0
	v_add_f32_e32 v2, v132, v133
	v_mov_b32_e32 v132, v2
	s_nop 1
	v_permlane16_swap_b32 v2, v132
	s_waitcnt lgkmcnt(0)
	v_add_f32_e32 v2, v2, v132
	v_mov_b32_e32 v132, v2
	s_nop 1
	v_permlane32_swap_b32 v2, v132
	s_waitcnt lgkmcnt(0)
	v_add_f32_e32 v2, v2, v132
	v_fmamk_f32 v133, v2, 0xbc800000, v131
	v_fmamk_f32 v135, v2, 0xbc800000, v129
	v_fmamk_f32 v132, v2, 0xbc800000, v130
	v_fmamk_f32 v134, v2, 0xbc800000, v128
	v_mul_f32_e32 v135, v135, v135
	v_mul_f32_e32 v133, v133, v133
	v_fmac_f32_e32 v135, v134, v134
	v_fmac_f32_e32 v133, v132, v132
	v_fmamk_f32 v134, v2, 0xbc800000, v123
	v_fmamk_f32 v136, v2, 0xbc800000, v121
	v_add_f32_e32 v132, v135, v133
	v_fmamk_f32 v133, v2, 0xbc800000, v122
	v_fmamk_f32 v135, v2, 0xbc800000, v120
	v_mul_f32_e32 v136, v136, v136
	v_mul_f32_e32 v134, v134, v134
	v_fmac_f32_e32 v136, v135, v135
	v_fmac_f32_e32 v134, v133, v133
	v_add_f32_e32 v133, v136, v134
	v_fmamk_f32 v134, v2, 0xbc800000, v115
	v_fmamk_f32 v136, v2, 0xbc800000, v113
	v_add_f32_e32 v132, v132, v133
	v_fmamk_f32 v133, v2, 0xbc800000, v114
	v_fmamk_f32 v135, v2, 0xbc800000, v112
	v_mul_f32_e32 v136, v136, v136
	v_mul_f32_e32 v134, v134, v134
	v_fmac_f32_e32 v136, v135, v135
	v_fmac_f32_e32 v134, v133, v133
	v_add_f32_e32 v133, v136, v134
	v_fmamk_f32 v134, v2, 0xbc800000, v107
	v_fmamk_f32 v136, v2, 0xbc800000, v105
	v_add_f32_e32 v132, v133, v132
	v_fmamk_f32 v133, v2, 0xbc800000, v106
	v_fmamk_f32 v135, v2, 0xbc800000, v104
	v_mul_f32_e32 v136, v136, v136
	v_mul_f32_e32 v134, v134, v134
	v_fmac_f32_e32 v136, v135, v135
	v_fmac_f32_e32 v134, v133, v133
	v_add_f32_e32 v133, v136, v134
	v_add_f32_e32 v132, v133, v132
	ds_bpermute_b32 v0, v0, v132
	s_waitcnt lgkmcnt(0)
	v_add_f32_e32 v0, v132, v0
	ds_bpermute_b32 v1, v1, v0
	s_and_saveexec_b64 s[4:5], vcc
	s_cbranch_execz .LBB0_454
	s_lshl_b32 s2, s80, 11
	s_add_i32 s7, s7, s2
	v_mul_f32_e32 v132, 0x3c800000, v2
	s_waitcnt lgkmcnt(0)
	v_add_f32_e32 v133, v0, v1
	v_lshl_add_u32 v0, v176, 5, s7
	ds_write_b64 v0, v[132:133] offset:5632

.LBB0_506:
	s_lshl_b32 s2, s14, 5
	s_lshl_b32 s3, s0, 8
	s_or_b32 s2, s3, s2
	v_lshrrev_b32_e32 v0, 2, v148
	s_lshl_b32 s6, s87, 8
	v_and_or_b32 v164, v0, 12, s2
	s_add_i32 s2, s6, s94
	v_or_b32_e32 v0, s2, v176
	v_readlane_b32 s2, v253, 15
	v_lshl_add_u32 v2, v0, 10, v164
	v_readlane_b32 s3, v253, 16
	s_waitcnt vmcnt(0)
	s_barrier
	v_mov_b32_e32 v134, v3
	v_lshl_add_u64 v[0:1], v[2:3], 1, s[2:3]
	global_load_dwordx2 v[132:133], v[0:1], off
	global_load_dwordx2 v[136:137], v[0:1], off offset:32
	global_load_dwordx2 v[140:141], v[0:1], off offset:256
	global_load_dwordx2 v[144:145], v[0:1], off offset:288
	v_add_u32_e32 v0, 0x4000, v2
	v_mov_b32_e32 v1, v3
	v_lshl_add_u64 v[0:1], v[0:1], 1, s[2:3]
	global_load_dwordx2 v[150:151], v[0:1], off
	global_load_dwordx2 v[178:179], v[0:1], off offset:32
	global_load_dwordx2 v[182:183], v[0:1], off offset:256
	global_load_dwordx2 v[186:187], v[0:1], off offset:288
	v_mov_b32_e32 v135, v3
	v_mov_b32_e32 v138, v3
	v_mov_b32_e32 v139, v3
	v_mov_b32_e32 v142, v3
	v_mov_b32_e32 v143, v3
	v_mov_b32_e32 v146, v3
	v_mov_b32_e32 v147, v3
	v_mov_b32_e32 v152, v3
	v_mov_b32_e32 v153, v3
	v_mov_b32_e32 v180, v3
	v_mov_b32_e32 v181, v3
	v_mov_b32_e32 v184, v3
	v_mov_b32_e32 v185, v3
	v_mov_b32_e32 v188, v3
	v_mov_b32_e32 v189, v3
	v_and_b32_e32 v149, 63, v148
	v_add_u32_e32 v0, 0x8000, v2
	v_mov_b32_e32 v1, v3
	v_lshl_add_u64 v[0:1], v[0:1], 1, s[2:3]
	global_load_dwordx2 v[200:201], v[0:1], off
	global_load_dwordx2 v[202:203], v[0:1], off offset:32
	global_load_dwordx2 v[204:205], v[0:1], off offset:256
	global_load_dwordx2 v[206:207], v[0:1], off offset:288
	v_add_u32_e32 v0, 0xc000, v2
	v_mov_b32_e32 v1, v3
	v_lshl_add_u64 v[0:1], v[0:1], 1, s[2:3]
	global_load_dwordx2 v[208:209], v[0:1], off
	global_load_dwordx2 v[210:211], v[0:1], off offset:32
	global_load_dwordx2 v[212:213], v[0:1], off offset:256
	global_load_dwordx2 v[214:215], v[0:1], off offset:288
	v_add_u32_e32 v0, 0x20000, v2
	v_mov_b32_e32 v1, v3
	v_lshl_add_u64 v[0:1], v[0:1], 1, s[2:3]
	global_load_dwordx2 v[222:223], v[0:1], off
	global_load_dwordx2 v[220:221], v[0:1], off offset:32
	global_load_dwordx2 v[218:219], v[0:1], off offset:256
	global_load_dwordx2 v[216:217], v[0:1], off offset:288
	v_add_u32_e32 v0, 0x24000, v2
	v_mov_b32_e32 v1, v3
	v_lshl_add_u64 v[0:1], v[0:1], 1, s[2:3]
	global_load_dwordx2 v[224:225], v[0:1], off
	global_load_dwordx2 v[226:227], v[0:1], off offset:32
	global_load_dwordx2 v[228:229], v[0:1], off offset:256
	global_load_dwordx2 v[230:231], v[0:1], off offset:288
	s_waitcnt vmcnt(16)
	s_nop 0
	v_cvt_f32_f16_e32 v0, v132
	v_cvt_f32_f16_sdwa v1, v132 dst_sel:DWORD dst_unused:UNUSED_PAD src0_sel:WORD_1
	v_cvt_f32_f16_e32 v132, v133
	v_cvt_f32_f16_sdwa v133, v133 dst_sel:DWORD dst_unused:UNUSED_PAD src0_sel:WORD_1
	v_mov_b32_e32 v134, v3
	v_pk_fma_f32 v[28:29], v[0:1], s[86:87], v[28:29] op_sel_hi:[1,0,1]
	v_cvt_f32_f16_e32 v0, v136
	v_pk_fma_f32 v[30:31], v[132:133], s[86:87], v[30:31] op_sel_hi:[1,0,1]
	v_cvt_f32_f16_sdwa v1, v136 dst_sel:DWORD dst_unused:UNUSED_PAD src0_sel:WORD_1
	v_cvt_f32_f16_e32 v132, v137
	v_cvt_f32_f16_sdwa v133, v137 dst_sel:DWORD dst_unused:UNUSED_PAD src0_sel:WORD_1
	v_mov_b32_e32 v135, v3
	v_pk_fma_f32 v[20:21], v[0:1], s[86:87], v[20:21] op_sel_hi:[1,0,1]
	v_cvt_f32_f16_e32 v0, v140
	v_pk_fma_f32 v[22:23], v[132:133], s[86:87], v[22:23] op_sel_hi:[1,0,1]
	v_cvt_f32_f16_sdwa v1, v140 dst_sel:DWORD dst_unused:UNUSED_PAD src0_sel:WORD_1
	v_cvt_f32_f16_e32 v132, v141
	v_cvt_f32_f16_sdwa v133, v141 dst_sel:DWORD dst_unused:UNUSED_PAD src0_sel:WORD_1
	v_mov_b32_e32 v138, v3
	v_pk_fma_f32 v[12:13], v[0:1], s[86:87], v[12:13] op_sel_hi:[1,0,1]
	v_cvt_f32_f16_e32 v0, v144
	v_pk_fma_f32 v[14:15], v[132:133], s[86:87], v[14:15] op_sel_hi:[1,0,1]
	v_cvt_f32_f16_sdwa v1, v144 dst_sel:DWORD dst_unused:UNUSED_PAD src0_sel:WORD_1
	v_cvt_f32_f16_e32 v132, v145
	v_cvt_f32_f16_sdwa v133, v145 dst_sel:DWORD dst_unused:UNUSED_PAD src0_sel:WORD_1
	v_mov_b32_e32 v139, v3
	v_pk_fma_f32 v[4:5], v[0:1], s[86:87], v[4:5] op_sel_hi:[1,0,1]
	v_cvt_f32_f16_e32 v0, v150
	v_pk_fma_f32 v[6:7], v[132:133], s[86:87], v[6:7] op_sel_hi:[1,0,1]
	v_cvt_f32_f16_sdwa v1, v150 dst_sel:DWORD dst_unused:UNUSED_PAD src0_sel:WORD_1
	v_cvt_f32_f16_e32 v132, v151
	v_cvt_f32_f16_sdwa v133, v151 dst_sel:DWORD dst_unused:UNUSED_PAD src0_sel:WORD_1
	v_pk_fma_f32 v[32:33], v[0:1], s[86:87], v[32:33] op_sel_hi:[1,0,1]
	v_cvt_f32_f16_e32 v0, v178
	v_pk_fma_f32 v[34:35], v[132:133], s[86:87], v[34:35] op_sel_hi:[1,0,1]
	v_cvt_f32_f16_sdwa v1, v178 dst_sel:DWORD dst_unused:UNUSED_PAD src0_sel:WORD_1
	v_cvt_f32_f16_e32 v132, v179
	v_cvt_f32_f16_sdwa v133, v179 dst_sel:DWORD dst_unused:UNUSED_PAD src0_sel:WORD_1
	v_mov_b32_e32 v142, v3
	v_pk_fma_f32 v[24:25], v[0:1], s[86:87], v[24:25] op_sel_hi:[1,0,1]
	v_cvt_f32_f16_e32 v0, v182
	v_pk_fma_f32 v[26:27], v[132:133], s[86:87], v[26:27] op_sel_hi:[1,0,1]
	v_cvt_f32_f16_sdwa v1, v182 dst_sel:DWORD dst_unused:UNUSED_PAD src0_sel:WORD_1
	v_cvt_f32_f16_e32 v132, v183
	v_cvt_f32_f16_sdwa v133, v183 dst_sel:DWORD dst_unused:UNUSED_PAD src0_sel:WORD_1
	v_mov_b32_e32 v143, v3
	v_pk_fma_f32 v[16:17], v[0:1], s[86:87], v[16:17] op_sel_hi:[1,0,1]
	v_cvt_f32_f16_e32 v0, v186
	v_pk_fma_f32 v[18:19], v[132:133], s[86:87], v[18:19] op_sel_hi:[1,0,1]
	v_cvt_f32_f16_sdwa v1, v186 dst_sel:DWORD dst_unused:UNUSED_PAD src0_sel:WORD_1
	v_cvt_f32_f16_e32 v132, v187
	v_cvt_f32_f16_sdwa v133, v187 dst_sel:DWORD dst_unused:UNUSED_PAD src0_sel:WORD_1
	v_mov_b32_e32 v146, v3
	v_pk_fma_f32 v[8:9], v[0:1], s[86:87], v[8:9] op_sel_hi:[1,0,1]
	v_pk_fma_f32 v[10:11], v[132:133], s[86:87], v[10:11] op_sel_hi:[1,0,1]
	v_mov_b32_e32 v147, v3
	v_mov_b32_e32 v152, v3
	v_mov_b32_e32 v153, v3
	v_mov_b32_e32 v180, v3
	v_mov_b32_e32 v181, v3
	v_mov_b32_e32 v184, v3
	v_mov_b32_e32 v185, v3
	v_mov_b32_e32 v188, v3
	v_mov_b32_e32 v189, v3
	s_waitcnt vmcnt(8)
	s_nop 0
	v_cvt_f32_f16_e32 v0, v200
	v_cvt_f32_f16_sdwa v1, v200 dst_sel:DWORD dst_unused:UNUSED_PAD src0_sel:WORD_1
	v_cvt_f32_f16_e32 v200, v201
	v_cvt_f32_f16_sdwa v201, v201 dst_sel:DWORD dst_unused:UNUSED_PAD src0_sel:WORD_1
	v_mov_b32_e32 v146, v3
	v_pk_fma_f32 v[60:61], v[0:1], s[86:87], v[60:61] op_sel_hi:[1,0,1]
	v_cvt_f32_f16_e32 v0, v202
	v_pk_fma_f32 v[62:63], v[200:201], s[86:87], v[62:63] op_sel_hi:[1,0,1]
	v_cvt_f32_f16_sdwa v1, v202 dst_sel:DWORD dst_unused:UNUSED_PAD src0_sel:WORD_1
	v_cvt_f32_f16_e32 v200, v203
	v_cvt_f32_f16_sdwa v201, v203 dst_sel:DWORD dst_unused:UNUSED_PAD src0_sel:WORD_1
	v_mov_b32_e32 v147, v3
	v_pk_fma_f32 v[52:53], v[0:1], s[86:87], v[52:53] op_sel_hi:[1,0,1]
	v_cvt_f32_f16_e32 v0, v204
	v_pk_fma_f32 v[54:55], v[200:201], s[86:87], v[54:55] op_sel_hi:[1,0,1]
	v_cvt_f32_f16_sdwa v1, v204 dst_sel:DWORD dst_unused:UNUSED_PAD src0_sel:WORD_1
	v_cvt_f32_f16_e32 v200, v205
	v_cvt_f32_f16_sdwa v201, v205 dst_sel:DWORD dst_unused:UNUSED_PAD src0_sel:WORD_1
	v_mov_b32_e32 v142, v3
	v_pk_fma_f32 v[44:45], v[0:1], s[86:87], v[44:45] op_sel_hi:[1,0,1]
	v_cvt_f32_f16_e32 v0, v206
	v_pk_fma_f32 v[46:47], v[200:201], s[86:87], v[46:47] op_sel_hi:[1,0,1]
	v_cvt_f32_f16_sdwa v1, v206 dst_sel:DWORD dst_unused:UNUSED_PAD src0_sel:WORD_1
	v_cvt_f32_f16_e32 v200, v207
	v_cvt_f32_f16_sdwa v201, v207 dst_sel:DWORD dst_unused:UNUSED_PAD src0_sel:WORD_1
	v_mov_b32_e32 v143, v3
	v_pk_fma_f32 v[36:37], v[0:1], s[86:87], v[36:37] op_sel_hi:[1,0,1]
	v_cvt_f32_f16_e32 v0, v208
	v_pk_fma_f32 v[38:39], v[200:201], s[86:87], v[38:39] op_sel_hi:[1,0,1]
	v_cvt_f32_f16_sdwa v1, v208 dst_sel:DWORD dst_unused:UNUSED_PAD src0_sel:WORD_1
	v_cvt_f32_f16_e32 v200, v209
	v_cvt_f32_f16_sdwa v201, v209 dst_sel:DWORD dst_unused:UNUSED_PAD src0_sel:WORD_1
	v_pk_fma_f32 v[64:65], v[0:1], s[86:87], v[64:65] op_sel_hi:[1,0,1]
	v_cvt_f32_f16_e32 v0, v210
	v_pk_fma_f32 v[66:67], v[200:201], s[86:87], v[66:67] op_sel_hi:[1,0,1]
	v_cvt_f32_f16_sdwa v1, v210 dst_sel:DWORD dst_unused:UNUSED_PAD src0_sel:WORD_1
	v_cvt_f32_f16_e32 v200, v211
	v_cvt_f32_f16_sdwa v201, v211 dst_sel:DWORD dst_unused:UNUSED_PAD src0_sel:WORD_1
	v_mov_b32_e32 v138, v3
	v_pk_fma_f32 v[56:57], v[0:1], s[86:87], v[56:57] op_sel_hi:[1,0,1]
	v_cvt_f32_f16_e32 v0, v212
	v_pk_fma_f32 v[58:59], v[200:201], s[86:87], v[58:59] op_sel_hi:[1,0,1]
	v_cvt_f32_f16_sdwa v1, v212 dst_sel:DWORD dst_unused:UNUSED_PAD src0_sel:WORD_1
	v_cvt_f32_f16_e32 v200, v213
	v_cvt_f32_f16_sdwa v201, v213 dst_sel:DWORD dst_unused:UNUSED_PAD src0_sel:WORD_1
	v_mov_b32_e32 v139, v3
	v_pk_fma_f32 v[48:49], v[0:1], s[86:87], v[48:49] op_sel_hi:[1,0,1]
	v_cvt_f32_f16_e32 v0, v214
	v_pk_fma_f32 v[50:51], v[200:201], s[86:87], v[50:51] op_sel_hi:[1,0,1]
	v_cvt_f32_f16_sdwa v1, v214 dst_sel:DWORD dst_unused:UNUSED_PAD src0_sel:WORD_1
	v_cvt_f32_f16_e32 v200, v215
	v_cvt_f32_f16_sdwa v201, v215 dst_sel:DWORD dst_unused:UNUSED_PAD src0_sel:WORD_1
	v_mov_b32_e32 v134, v3
	v_pk_fma_f32 v[40:41], v[0:1], s[86:87], v[40:41] op_sel_hi:[1,0,1]
	v_pk_fma_f32 v[42:43], v[200:201], s[86:87], v[42:43] op_sel_hi:[1,0,1]
	v_mov_b32_e32 v135, v3
	v_mov_b32_e32 v152, v3
	v_mov_b32_e32 v153, v3
	v_mov_b32_e32 v180, v3
	v_mov_b32_e32 v181, v3
	v_mov_b32_e32 v184, v3
	v_mov_b32_e32 v185, v3
	v_mov_b32_e32 v188, v3
	v_mov_b32_e32 v189, v3
	s_waitcnt vmcnt(0)
	s_nop 0
	v_cvt_f32_f16_e32 v0, v222
	v_cvt_f32_f16_sdwa v1, v222 dst_sel:DWORD dst_unused:UNUSED_PAD src0_sel:WORD_1
	v_cvt_f32_f16_e32 v134, v223
	v_cvt_f32_f16_sdwa v135, v223 dst_sel:DWORD dst_unused:UNUSED_PAD src0_sel:WORD_1
	v_mov_b32_e32 v142, v3
	v_pk_fma_f32 v[92:93], v[0:1], s[86:87], v[92:93] op_sel_hi:[1,0,1]
	v_cvt_f32_f16_e32 v0, v220
	v_cvt_f32_f16_sdwa v1, v220 dst_sel:DWORD dst_unused:UNUSED_PAD src0_sel:WORD_1
	v_pk_fma_f32 v[94:95], v[134:135], s[86:87], v[94:95] op_sel_hi:[1,0,1]
	v_cvt_f32_f16_e32 v134, v221
	v_cvt_f32_f16_sdwa v135, v221 dst_sel:DWORD dst_unused:UNUSED_PAD src0_sel:WORD_1
	v_pk_fma_f32 v[84:85], v[0:1], s[86:87], v[84:85] op_sel_hi:[1,0,1]
	v_cvt_f32_f16_e32 v0, v218
	v_cvt_f32_f16_sdwa v1, v218 dst_sel:DWORD dst_unused:UNUSED_PAD src0_sel:WORD_1
	v_pk_fma_f32 v[86:87], v[134:135], s[86:87], v[86:87] op_sel_hi:[1,0,1]
	v_cvt_f32_f16_e32 v134, v219
	v_cvt_f32_f16_sdwa v135, v219 dst_sel:DWORD dst_unused:UNUSED_PAD src0_sel:WORD_1
	v_pk_fma_f32 v[76:77], v[0:1], s[86:87], v[76:77] op_sel_hi:[1,0,1]
	v_cvt_f32_f16_e32 v0, v216
	v_cvt_f32_f16_sdwa v1, v216 dst_sel:DWORD dst_unused:UNUSED_PAD src0_sel:WORD_1
	v_cvt_f32_f16_e32 v216, v217
	v_cvt_f32_f16_sdwa v217, v217 dst_sel:DWORD dst_unused:UNUSED_PAD src0_sel:WORD_1
	v_pk_fma_f32 v[78:79], v[134:135], s[86:87], v[78:79] op_sel_hi:[1,0,1]
	v_pk_fma_f32 v[68:69], v[0:1], s[86:87], v[68:69] op_sel_hi:[1,0,1]
	v_cvt_f32_f16_e32 v0, v224
	v_pk_fma_f32 v[70:71], v[216:217], s[86:87], v[70:71] op_sel_hi:[1,0,1]
	v_cvt_f32_f16_sdwa v1, v224 dst_sel:DWORD dst_unused:UNUSED_PAD src0_sel:WORD_1
	v_cvt_f32_f16_e32 v216, v225
	v_cvt_f32_f16_sdwa v217, v225 dst_sel:DWORD dst_unused:UNUSED_PAD src0_sel:WORD_1
	v_pk_fma_f32 v[96:97], v[0:1], s[86:87], v[96:97] op_sel_hi:[1,0,1]
	v_cvt_f32_f16_e32 v0, v226
	v_pk_fma_f32 v[98:99], v[216:217], s[86:87], v[98:99] op_sel_hi:[1,0,1]
	v_cvt_f32_f16_sdwa v1, v226 dst_sel:DWORD dst_unused:UNUSED_PAD src0_sel:WORD_1
	v_cvt_f32_f16_e32 v216, v227
	v_cvt_f32_f16_sdwa v217, v227 dst_sel:DWORD dst_unused:UNUSED_PAD src0_sel:WORD_1
	v_mov_b32_e32 v143, v3
	v_pk_fma_f32 v[88:89], v[0:1], s[86:87], v[88:89] op_sel_hi:[1,0,1]
	v_cvt_f32_f16_e32 v0, v228
	v_pk_fma_f32 v[90:91], v[216:217], s[86:87], v[90:91] op_sel_hi:[1,0,1]
	v_cvt_f32_f16_sdwa v1, v228 dst_sel:DWORD dst_unused:UNUSED_PAD src0_sel:WORD_1
	v_cvt_f32_f16_e32 v216, v229
	v_cvt_f32_f16_sdwa v217, v229 dst_sel:DWORD dst_unused:UNUSED_PAD src0_sel:WORD_1
	v_mov_b32_e32 v138, v3
	v_pk_fma_f32 v[80:81], v[0:1], s[86:87], v[80:81] op_sel_hi:[1,0,1]
	v_cvt_f32_f16_e32 v0, v230
	v_pk_fma_f32 v[82:83], v[216:217], s[86:87], v[82:83] op_sel_hi:[1,0,1]
	v_cvt_f32_f16_sdwa v1, v230 dst_sel:DWORD dst_unused:UNUSED_PAD src0_sel:WORD_1
	v_cvt_f32_f16_e32 v216, v231
	v_cvt_f32_f16_sdwa v217, v231 dst_sel:DWORD dst_unused:UNUSED_PAD src0_sel:WORD_1
	v_mov_b32_e32 v139, v3
	v_pk_fma_f32 v[72:73], v[0:1], s[86:87], v[72:73] op_sel_hi:[1,0,1]
	v_add_u32_e32 v0, 0x28000, v2
	v_pk_fma_f32 v[74:75], v[216:217], s[86:87], v[74:75] op_sel_hi:[1,0,1]
	v_mov_b32_e32 v1, v3
	v_add_u32_e32 v2, 0x2c000, v2
	v_lshl_add_u64 v[132:133], v[0:1], 1, s[2:3]
	v_lshl_add_u64 v[134:135], v[2:3], 1, s[2:3]
	global_load_dwordx2 v[0:1], v[132:133], off
	global_load_dwordx2 v[140:141], v[132:133], off offset:32
	global_load_dwordx2 v[136:137], v[132:133], off offset:256
	s_nop 0
	global_load_dwordx2 v[132:133], v[132:133], off offset:288
	s_nop 0
	global_load_dwordx2 v[144:145], v[134:135], off
	global_load_dwordx2 v[150:151], v[134:135], off offset:32
	global_load_dwordx2 v[178:179], v[134:135], off offset:256
	global_load_dwordx2 v[182:183], v[134:135], off offset:288
	v_mov_b32_e32 v2, v3
	v_mov_b32_e32 v134, v3
	v_mov_b32_e32 v135, v3
	v_mov_b32_e32 v146, v3
	v_mov_b32_e32 v147, v3
	v_mov_b32_e32 v152, v3
	v_mov_b32_e32 v153, v3
	v_mov_b32_e32 v180, v3
	v_mov_b32_e32 v181, v3
	v_mov_b32_e32 v184, v3
	v_mov_b32_e32 v185, v3
	s_lshl_b32 s2, s14, 3
	s_add_i32 s7, s2, 0
	s_waitcnt vmcnt(7)
	v_mov_b64_e32 v[188:189], v[2:3]
	v_mov_b64_e32 v[186:187], v[0:1]
	s_waitcnt vmcnt(0)
	s_nop 0
	v_cvt_f32_f16_e32 v0, v186
	v_cvt_f32_f16_sdwa v1, v186 dst_sel:DWORD dst_unused:UNUSED_PAD src0_sel:WORD_1
	v_cvt_f32_f16_e32 v134, v187
	v_cvt_f32_f16_sdwa v135, v187 dst_sel:DWORD dst_unused:UNUSED_PAD src0_sel:WORD_1
	v_xor_b32_e32 v2, 32, v171
	v_pk_fma_f32 v[124:125], v[0:1], s[86:87], v[124:125] op_sel_hi:[1,0,1]
	v_cvt_f32_f16_e32 v0, v140
	v_cvt_f32_f16_sdwa v1, v140 dst_sel:DWORD dst_unused:UNUSED_PAD src0_sel:WORD_1
	v_pk_fma_f32 v[126:127], v[134:135], s[86:87], v[126:127] op_sel_hi:[1,0,1]
	v_cvt_f32_f16_e32 v134, v141
	v_cvt_f32_f16_sdwa v135, v141 dst_sel:DWORD dst_unused:UNUSED_PAD src0_sel:WORD_1
	v_pk_fma_f32 v[116:117], v[0:1], s[86:87], v[116:117] op_sel_hi:[1,0,1]
	v_cvt_f32_f16_e32 v0, v136
	v_cvt_f32_f16_sdwa v1, v136 dst_sel:DWORD dst_unused:UNUSED_PAD src0_sel:WORD_1
	v_pk_fma_f32 v[118:119], v[134:135], s[86:87], v[118:119] op_sel_hi:[1,0,1]
	v_cvt_f32_f16_e32 v134, v137
	v_cvt_f32_f16_sdwa v135, v137 dst_sel:DWORD dst_unused:UNUSED_PAD src0_sel:WORD_1
	v_pk_fma_f32 v[108:109], v[0:1], s[86:87], v[108:109] op_sel_hi:[1,0,1]
	v_cvt_f32_f16_e32 v0, v132
	v_cvt_f32_f16_sdwa v1, v132 dst_sel:DWORD dst_unused:UNUSED_PAD src0_sel:WORD_1
	v_cvt_f32_f16_e32 v132, v133
	v_cvt_f32_f16_sdwa v133, v133 dst_sel:DWORD dst_unused:UNUSED_PAD src0_sel:WORD_1
	v_pk_fma_f32 v[110:111], v[134:135], s[86:87], v[110:111] op_sel_hi:[1,0,1]
	v_pk_fma_f32 v[100:101], v[0:1], s[86:87], v[100:101] op_sel_hi:[1,0,1]
	v_cvt_f32_f16_e32 v0, v144
	v_cvt_f32_f16_sdwa v1, v144 dst_sel:DWORD dst_unused:UNUSED_PAD src0_sel:WORD_1
	v_pk_fma_f32 v[102:103], v[132:133], s[86:87], v[102:103] op_sel_hi:[1,0,1]
	v_cvt_f32_f16_e32 v132, v145
	v_cvt_f32_f16_sdwa v133, v145 dst_sel:DWORD dst_unused:UNUSED_PAD src0_sel:WORD_1
	v_pk_fma_f32 v[128:129], v[0:1], s[86:87], v[128:129] op_sel_hi:[1,0,1]
	v_cvt_f32_f16_e32 v0, v150
	v_cvt_f32_f16_sdwa v1, v150 dst_sel:DWORD dst_unused:UNUSED_PAD src0_sel:WORD_1
	v_pk_fma_f32 v[130:131], v[132:133], s[86:87], v[130:131] op_sel_hi:[1,0,1]
	v_cvt_f32_f16_e32 v132, v151
	v_cvt_f32_f16_sdwa v133, v151 dst_sel:DWORD dst_unused:UNUSED_PAD src0_sel:WORD_1
	v_pk_fma_f32 v[120:121], v[0:1], s[86:87], v[120:121] op_sel_hi:[1,0,1]
	v_cvt_f32_f16_e32 v0, v178
	v_cvt_f32_f16_sdwa v1, v178 dst_sel:DWORD dst_unused:UNUSED_PAD src0_sel:WORD_1
	v_pk_fma_f32 v[122:123], v[132:133], s[86:87], v[122:123] op_sel_hi:[1,0,1]
	v_cvt_f32_f16_e32 v132, v179
	v_cvt_f32_f16_sdwa v133, v179 dst_sel:DWORD dst_unused:UNUSED_PAD src0_sel:WORD_1
	v_pk_fma_f32 v[112:113], v[0:1], s[86:87], v[112:113] op_sel_hi:[1,0,1]
	v_cvt_f32_f16_e32 v0, v182
	v_cvt_f32_f16_sdwa v1, v182 dst_sel:DWORD dst_unused:UNUSED_PAD src0_sel:WORD_1
	v_pk_fma_f32 v[114:115], v[132:133], s[86:87], v[114:115] op_sel_hi:[1,0,1]
	v_cvt_f32_f16_e32 v132, v183
	v_cvt_f32_f16_sdwa v133, v183 dst_sel:DWORD dst_unused:UNUSED_PAD src0_sel:WORD_1
	v_pk_fma_f32 v[104:105], v[0:1], s[86:87], v[104:105] op_sel_hi:[1,0,1]
	v_and_b32_e32 v1, 64, v171
	v_xor_b32_e32 v0, 16, v171
	v_pk_fma_f32 v[106:107], v[132:133], s[86:87], v[106:107] op_sel_hi:[1,0,1]
	v_add_u32_e32 v1, 64, v1
	v_mov_b32_e32 v132, v29
	v_mov_b32_e32 v133, v30
	v_mov_b32_e32 v134, v28
	v_mov_b32_e32 v135, v31
	v_cmp_lt_i32_e32 vcc, v0, v1
	v_pk_add_f32 v[132:133], v[132:133], v[134:135]
	v_mov_b32_e32 v134, v21
	v_mov_b32_e32 v135, v22
	v_mov_b32_e32 v136, v20
	v_mov_b32_e32 v137, v23
	v_cndmask_b32_e32 v0, v171, v0, vcc
	v_cmp_lt_i32_e32 vcc, v2, v1
	v_pk_add_f32 v[134:135], v[134:135], v[136:137]
	v_add_f32_e32 v137, v12, v13
	v_cndmask_b32_e32 v1, v171, v2, vcc
	v_add_f32_e32 v2, v132, v133
	v_pk_add_f32 v[134:135], v[134:135], v[134:135] op_sel_hi:[0,1]
	v_add_f32_e32 v133, 0, v2
	v_add_f32_e32 v139, v14, v15
	v_mov_b32_e32 v136, v4
	v_mov_b32_e32 v138, v5
	v_mov_b32_e32 v134, v6
	v_mov_b32_e32 v132, v7
	v_pk_add_f32 v[136:137], v[136:137], v[138:139]
	v_pk_add_f32 v[132:133], v[134:135], v[132:133]
	v_lshlrev_b32_e32 v0, 2, v0
	v_pk_add_f32 v[132:133], v[136:137], v[132:133]
	v_lshlrev_b32_e32 v1, 2, v1
	v_add_f32_e32 v2, v132, v133
	v_mov_b32_e32 v132, v2
	s_nop 1
	v_permlane16_swap_b32 v2, v132
	v_cmp_gt_u32_e32 vcc, 16, v149
	s_waitcnt lgkmcnt(0)
	v_add_f32_e32 v2, v2, v132
	v_mov_b32_e32 v132, v2
	s_nop 1
	v_permlane32_swap_b32 v2, v132
	s_waitcnt lgkmcnt(0)
	v_add_f32_e32 v2, v2, v132
	v_fmamk_f32 v133, v2, 0xbc800000, v31
	v_fmamk_f32 v135, v2, 0xbc800000, v29
	v_fmamk_f32 v132, v2, 0xbc800000, v30
	v_fmamk_f32 v134, v2, 0xbc800000, v28
	v_mul_f32_e32 v135, v135, v135
	v_mul_f32_e32 v133, v133, v133
	v_fmac_f32_e32 v135, v134, v134
	v_fmac_f32_e32 v133, v132, v132
	v_fmamk_f32 v134, v2, 0xbc800000, v23
	v_fmamk_f32 v136, v2, 0xbc800000, v21
	v_add_f32_e32 v132, v135, v133
	v_fmamk_f32 v133, v2, 0xbc800000, v22
	v_fmamk_f32 v135, v2, 0xbc800000, v20
	v_mul_f32_e32 v136, v136, v136
	v_mul_f32_e32 v134, v134, v134
	v_fmac_f32_e32 v136, v135, v135
	v_fmac_f32_e32 v134, v133, v133
	v_add_f32_e32 v133, v136, v134
	v_fmamk_f32 v134, v2, 0xbc800000, v15
	v_fmamk_f32 v136, v2, 0xbc800000, v13
	v_add_f32_e32 v132, v132, v133
	v_fmamk_f32 v133, v2, 0xbc800000, v14
	v_fmamk_f32 v135, v2, 0xbc800000, v12
	v_mul_f32_e32 v136, v136, v136
	v_mul_f32_e32 v134, v134, v134
	v_fmac_f32_e32 v136, v135, v135
	v_fmac_f32_e32 v134, v133, v133
	v_add_f32_e32 v133, v136, v134
	v_fmamk_f32 v134, v2, 0xbc800000, v7
	v_fmamk_f32 v136, v2, 0xbc800000, v5
	v_add_f32_e32 v132, v133, v132
	v_fmamk_f32 v133, v2, 0xbc800000, v6
	v_fmamk_f32 v135, v2, 0xbc800000, v4
	v_mul_f32_e32 v136, v136, v136
	v_mul_f32_e32 v134, v134, v134
	v_fmac_f32_e32 v136, v135, v135
	v_fmac_f32_e32 v134, v133, v133
	v_add_f32_e32 v133, v136, v134
	v_add_f32_e32 v132, v133, v132
	v_mov_b32_e32 v133, v132
	s_nop 1
	v_permlane16_swap_b32 v132, v133
	s_waitcnt lgkmcnt(0)
	v_add_f32_e32 v132, v132, v133
	ds_bpermute_b32 v133, v1, v132
	s_and_saveexec_b64 s[4:5], vcc
	s_cbranch_execz .LBB0_508
	s_lshl_b32 s2, s80, 11
	s_add_i32 s2, s7, s2
	v_mul_f32_e32 v134, 0x3c800000, v2
	s_waitcnt lgkmcnt(0)
	v_add_f32_e32 v135, v132, v133
	v_lshl_add_u32 v2, v176, 5, s2
	ds_write_b64 v2, v[134:135]
.LBB0_508:
	s_or_b64 exec, exec, s[4:5]
	v_mov_b32_e32 v132, v33
	s_waitcnt lgkmcnt(0)
	v_mov_b32_e32 v133, v34
	v_mov_b32_e32 v134, v32
	v_mov_b32_e32 v135, v35
	v_pk_add_f32 v[132:133], v[132:133], v[134:135]
	v_mov_b32_e32 v134, v25
	v_mov_b32_e32 v135, v26
	v_mov_b32_e32 v136, v24
	v_mov_b32_e32 v137, v27
	v_pk_add_f32 v[134:135], v[134:135], v[136:137]
	v_add_f32_e32 v2, v132, v133
	v_pk_add_f32 v[134:135], v[134:135], v[134:135] op_sel_hi:[0,1]
	v_add_f32_e32 v133, 0, v2
	v_add_f32_e32 v137, v16, v17
	v_add_f32_e32 v139, v18, v19
	v_mov_b32_e32 v136, v8
	v_mov_b32_e32 v138, v9
	v_mov_b32_e32 v134, v10
	v_mov_b32_e32 v132, v11
	v_pk_add_f32 v[136:137], v[136:137], v[138:139]
	v_pk_add_f32 v[132:133], v[134:135], v[132:133]
	s_nop 0
	v_pk_add_f32 v[132:133], v[136:137], v[132:133]
	s_nop 0
	v_add_f32_e32 v2, v132, v133
	v_mov_b32_e32 v132, v2
	s_nop 1
	v_permlane16_swap_b32 v2, v132
	s_waitcnt lgkmcnt(0)
	v_add_f32_e32 v2, v2, v132
	v_mov_b32_e32 v132, v2
	s_nop 1
	v_permlane32_swap_b32 v2, v132
	s_waitcnt lgkmcnt(0)
	v_add_f32_e32 v2, v2, v132
	v_fmamk_f32 v133, v2, 0xbc800000, v35
	v_fmamk_f32 v135, v2, 0xbc800000, v33
	v_fmamk_f32 v132, v2, 0xbc800000, v34
	v_fmamk_f32 v134, v2, 0xbc800000, v32
	v_mul_f32_e32 v135, v135, v135
	v_mul_f32_e32 v133, v133, v133
	v_fmac_f32_e32 v135, v134, v134
	v_fmac_f32_e32 v133, v132, v132
	v_fmamk_f32 v134, v2, 0xbc800000, v27
	v_fmamk_f32 v136, v2, 0xbc800000, v25
	v_add_f32_e32 v132, v135, v133
	v_fmamk_f32 v133, v2, 0xbc800000, v26
	v_fmamk_f32 v135, v2, 0xbc800000, v24
	v_mul_f32_e32 v136, v136, v136
	v_mul_f32_e32 v134, v134, v134
	v_fmac_f32_e32 v136, v135, v135
	v_fmac_f32_e32 v134, v133, v133
	v_add_f32_e32 v133, v136, v134
	v_fmamk_f32 v134, v2, 0xbc800000, v19
	v_fmamk_f32 v136, v2, 0xbc800000, v17
	v_add_f32_e32 v132, v132, v133
	v_fmamk_f32 v133, v2, 0xbc800000, v18
	v_fmamk_f32 v135, v2, 0xbc800000, v16
	v_mul_f32_e32 v136, v136, v136
	v_mul_f32_e32 v134, v134, v134
	v_fmac_f32_e32 v136, v135, v135
	v_fmac_f32_e32 v134, v133, v133
	v_add_f32_e32 v133, v136, v134
	v_fmamk_f32 v134, v2, 0xbc800000, v11
	v_fmamk_f32 v136, v2, 0xbc800000, v9
	v_add_f32_e32 v132, v133, v132
	v_fmamk_f32 v133, v2, 0xbc800000, v10
	v_fmamk_f32 v135, v2, 0xbc800000, v8
	v_mul_f32_e32 v136, v136, v136
	v_mul_f32_e32 v134, v134, v134
	v_fmac_f32_e32 v136, v135, v135
	v_fmac_f32_e32 v134, v133, v133
	v_add_f32_e32 v133, v136, v134
	v_add_f32_e32 v132, v133, v132
	v_mov_b32_e32 v133, v132
	s_nop 1
	v_permlane16_swap_b32 v132, v133
	s_waitcnt lgkmcnt(0)
	v_add_f32_e32 v132, v132, v133
	ds_bpermute_b32 v133, v1, v132
	s_and_saveexec_b64 s[4:5], vcc
	v_readlane_b32 s56, v253, 19
	v_readlane_b32 s16, v253, 21
	v_readlane_b32 s85, v253, 23
	v_readlane_b32 s92, v253, 24
	v_readlane_b32 s57, v253, 20
	v_readlane_b32 s17, v253, 22
	v_readlane_b32 s93, v253, 25
	s_cbranch_execz .LBB0_510
	s_lshl_b32 s2, s80, 11
	s_add_i32 s2, s7, s2
	v_mul_f32_e32 v134, 0x3c800000, v2
	s_waitcnt lgkmcnt(0)
	v_add_f32_e32 v135, v132, v133
	v_lshl_add_u32 v2, v176, 5, s2
	ds_write_b64 v2, v[134:135] offset:512

.LBB0_1154:
	s_lshl_b32 s4, s8, 5
	s_lshl_b32 s5, s44, 8
	s_or_b32 s4, s5, s4
	v_lshrrev_b32_e32 v0, 2, v145
	s_lshl_b32 s6, s1, 8
	v_and_or_b32 v140, v0, 12, s4
	s_add_i32 s4, s6, s14
	v_or_b32_e32 v0, s4, v144
	v_lshl_add_u32 v2, v0, 10, v140
	v_lshl_add_u64 v[0:1], v[2:3], 1, s[64:65]
	s_waitcnt vmcnt(0)
	s_barrier
	global_load_dwordx2 v[132:133], v[0:1], off
	global_load_dwordx2 v[136:137], v[0:1], off offset:32
	global_load_dwordx2 v[146:147], v[0:1], off offset:256
	global_load_dwordx2 v[150:151], v[0:1], off offset:288
	v_add_u32_e32 v0, 0x4000, v2
	v_mov_b32_e32 v1, v3
	v_lshl_add_u64 v[0:1], v[0:1], 1, s[64:65]
	global_load_dwordx2 v[186:187], v[0:1], off
	global_load_dwordx2 v[190:191], v[0:1], off offset:32
	global_load_dwordx2 v[194:195], v[0:1], off offset:256
	global_load_dwordx2 v[198:199], v[0:1], off offset:288
	v_mov_b32_e32 v134, v3
	v_mov_b32_e32 v135, v3
	v_mov_b32_e32 v138, v3
	v_mov_b32_e32 v139, v3
	v_mov_b32_e32 v148, v3
	v_mov_b32_e32 v149, v3
	v_mov_b32_e32 v152, v3
	v_mov_b32_e32 v153, v3
	v_mov_b32_e32 v188, v3
	v_mov_b32_e32 v189, v3
	v_mov_b32_e32 v192, v3
	v_mov_b32_e32 v193, v3
	v_mov_b32_e32 v196, v3
	v_mov_b32_e32 v197, v3
	v_mov_b32_e32 v200, v3
	v_mov_b32_e32 v201, v3
	s_mov_b32 s4, 0x3fd744fd
	v_and_b32_e32 v141, 63, v145
	v_cmp_gt_u32_e32 vcc, 16, v141
	v_add_u32_e32 v0, 0x8000, v2
	v_mov_b32_e32 v1, v3
	v_lshl_add_u64 v[0:1], v[0:1], 1, s[64:65]
	global_load_dwordx2 v[202:203], v[0:1], off
	global_load_dwordx2 v[204:205], v[0:1], off offset:32
	global_load_dwordx2 v[206:207], v[0:1], off offset:256
	global_load_dwordx2 v[208:209], v[0:1], off offset:288
	v_add_u32_e32 v0, 0xc000, v2
	v_mov_b32_e32 v1, v3
	v_lshl_add_u64 v[0:1], v[0:1], 1, s[64:65]
	global_load_dwordx2 v[210:211], v[0:1], off
	global_load_dwordx2 v[212:213], v[0:1], off offset:32
	global_load_dwordx2 v[214:215], v[0:1], off offset:256
	global_load_dwordx2 v[216:217], v[0:1], off offset:288
	v_add_u32_e32 v0, 0x20000, v2
	v_mov_b32_e32 v1, v3
	v_lshl_add_u64 v[0:1], v[0:1], 1, s[64:65]
	global_load_dwordx2 v[220:221], v[0:1], off
	global_load_dwordx2 v[222:223], v[0:1], off offset:32
	global_load_dwordx2 v[224:225], v[0:1], off offset:256
	global_load_dwordx2 v[218:219], v[0:1], off offset:288
	v_add_u32_e32 v0, 0x24000, v2
	v_mov_b32_e32 v1, v3
	v_lshl_add_u64 v[0:1], v[0:1], 1, s[64:65]
	global_load_dwordx2 v[226:227], v[0:1], off
	global_load_dwordx2 v[228:229], v[0:1], off offset:32
	global_load_dwordx2 v[230:231], v[0:1], off offset:256
	global_load_dwordx2 v[232:233], v[0:1], off offset:288
	s_waitcnt vmcnt(16)
	s_nop 0
	v_cvt_f32_f16_e32 v0, v132
	v_cvt_f32_f16_sdwa v1, v132 dst_sel:DWORD dst_unused:UNUSED_PAD src0_sel:WORD_1
	v_cvt_f32_f16_e32 v132, v133
	v_cvt_f32_f16_sdwa v133, v133 dst_sel:DWORD dst_unused:UNUSED_PAD src0_sel:WORD_1
	v_mov_b32_e32 v134, v3
	v_pk_fma_f32 v[36:37], v[0:1], s[4:5], v[36:37] op_sel_hi:[1,0,1]
	v_cvt_f32_f16_e32 v0, v136
	v_pk_fma_f32 v[38:39], v[132:133], s[4:5], v[38:39] op_sel_hi:[1,0,1]
	v_cvt_f32_f16_sdwa v1, v136 dst_sel:DWORD dst_unused:UNUSED_PAD src0_sel:WORD_1
	v_cvt_f32_f16_e32 v132, v137
	v_cvt_f32_f16_sdwa v133, v137 dst_sel:DWORD dst_unused:UNUSED_PAD src0_sel:WORD_1
	v_mov_b32_e32 v135, v3
	v_pk_fma_f32 v[20:21], v[0:1], s[4:5], v[20:21] op_sel_hi:[1,0,1]
	v_cvt_f32_f16_e32 v0, v146
	v_pk_fma_f32 v[22:23], v[132:133], s[4:5], v[22:23] op_sel_hi:[1,0,1]
	v_cvt_f32_f16_sdwa v1, v146 dst_sel:DWORD dst_unused:UNUSED_PAD src0_sel:WORD_1
	v_cvt_f32_f16_e32 v132, v147
	v_cvt_f32_f16_sdwa v133, v147 dst_sel:DWORD dst_unused:UNUSED_PAD src0_sel:WORD_1
	v_mov_b32_e32 v138, v3
	v_pk_fma_f32 v[12:13], v[0:1], s[4:5], v[12:13] op_sel_hi:[1,0,1]
	v_cvt_f32_f16_e32 v0, v150
	v_pk_fma_f32 v[14:15], v[132:133], s[4:5], v[14:15] op_sel_hi:[1,0,1]
	v_cvt_f32_f16_sdwa v1, v150 dst_sel:DWORD dst_unused:UNUSED_PAD src0_sel:WORD_1
	v_cvt_f32_f16_e32 v132, v151
	v_cvt_f32_f16_sdwa v133, v151 dst_sel:DWORD dst_unused:UNUSED_PAD src0_sel:WORD_1
	v_mov_b32_e32 v139, v3
	v_pk_fma_f32 v[4:5], v[0:1], s[4:5], v[4:5] op_sel_hi:[1,0,1]
	v_cvt_f32_f16_e32 v0, v186
	v_pk_fma_f32 v[6:7], v[132:133], s[4:5], v[6:7] op_sel_hi:[1,0,1]
	v_cvt_f32_f16_sdwa v1, v186 dst_sel:DWORD dst_unused:UNUSED_PAD src0_sel:WORD_1
	v_cvt_f32_f16_e32 v132, v187
	v_cvt_f32_f16_sdwa v133, v187 dst_sel:DWORD dst_unused:UNUSED_PAD src0_sel:WORD_1
	v_pk_fma_f32 v[40:41], v[0:1], s[4:5], v[40:41] op_sel_hi:[1,0,1]
	v_cvt_f32_f16_e32 v0, v190
	v_pk_fma_f32 v[42:43], v[132:133], s[4:5], v[42:43] op_sel_hi:[1,0,1]
	v_cvt_f32_f16_sdwa v1, v190 dst_sel:DWORD dst_unused:UNUSED_PAD src0_sel:WORD_1
	v_cvt_f32_f16_e32 v132, v191
	v_cvt_f32_f16_sdwa v133, v191 dst_sel:DWORD dst_unused:UNUSED_PAD src0_sel:WORD_1
	v_mov_b32_e32 v148, v3
	v_pk_fma_f32 v[24:25], v[0:1], s[4:5], v[24:25] op_sel_hi:[1,0,1]
	v_cvt_f32_f16_e32 v0, v194
	v_pk_fma_f32 v[26:27], v[132:133], s[4:5], v[26:27] op_sel_hi:[1,0,1]
	v_cvt_f32_f16_sdwa v1, v194 dst_sel:DWORD dst_unused:UNUSED_PAD src0_sel:WORD_1
	v_cvt_f32_f16_e32 v132, v195
	v_cvt_f32_f16_sdwa v133, v195 dst_sel:DWORD dst_unused:UNUSED_PAD src0_sel:WORD_1
	v_mov_b32_e32 v149, v3
	v_pk_fma_f32 v[16:17], v[0:1], s[4:5], v[16:17] op_sel_hi:[1,0,1]
	v_cvt_f32_f16_e32 v0, v198
	v_pk_fma_f32 v[18:19], v[132:133], s[4:5], v[18:19] op_sel_hi:[1,0,1]
	v_cvt_f32_f16_sdwa v1, v198 dst_sel:DWORD dst_unused:UNUSED_PAD src0_sel:WORD_1
	v_cvt_f32_f16_e32 v132, v199
	v_cvt_f32_f16_sdwa v133, v199 dst_sel:DWORD dst_unused:UNUSED_PAD src0_sel:WORD_1
	v_mov_b32_e32 v152, v3
	v_pk_fma_f32 v[8:9], v[0:1], s[4:5], v[8:9] op_sel_hi:[1,0,1]
	v_pk_fma_f32 v[10:11], v[132:133], s[4:5], v[10:11] op_sel_hi:[1,0,1]
	v_mov_b32_e32 v153, v3
	v_mov_b32_e32 v188, v3
	v_mov_b32_e32 v189, v3
	v_mov_b32_e32 v192, v3
	v_mov_b32_e32 v193, v3
	v_mov_b32_e32 v196, v3
	v_mov_b32_e32 v197, v3
	v_mov_b32_e32 v200, v3
	v_mov_b32_e32 v201, v3
	s_waitcnt vmcnt(8)
	s_nop 0
	v_cvt_f32_f16_e32 v0, v202
	v_cvt_f32_f16_sdwa v1, v202 dst_sel:DWORD dst_unused:UNUSED_PAD src0_sel:WORD_1
	v_cvt_f32_f16_e32 v202, v203
	v_cvt_f32_f16_sdwa v203, v203 dst_sel:DWORD dst_unused:UNUSED_PAD src0_sel:WORD_1
	v_mov_b32_e32 v138, v3
	v_pk_fma_f32 v[100:101], v[0:1], s[4:5], v[100:101] op_sel_hi:[1,0,1]
	v_cvt_f32_f16_e32 v0, v204
	v_pk_fma_f32 v[102:103], v[202:203], s[4:5], v[102:103] op_sel_hi:[1,0,1]
	v_cvt_f32_f16_sdwa v1, v204 dst_sel:DWORD dst_unused:UNUSED_PAD src0_sel:WORD_1
	v_cvt_f32_f16_e32 v202, v205
	v_cvt_f32_f16_sdwa v203, v205 dst_sel:DWORD dst_unused:UNUSED_PAD src0_sel:WORD_1
	v_mov_b32_e32 v139, v3
	v_pk_fma_f32 v[84:85], v[0:1], s[4:5], v[84:85] op_sel_hi:[1,0,1]
	v_cvt_f32_f16_e32 v0, v206
	v_pk_fma_f32 v[86:87], v[202:203], s[4:5], v[86:87] op_sel_hi:[1,0,1]
	v_cvt_f32_f16_sdwa v1, v206 dst_sel:DWORD dst_unused:UNUSED_PAD src0_sel:WORD_1
	v_cvt_f32_f16_e32 v202, v207
	v_cvt_f32_f16_sdwa v203, v207 dst_sel:DWORD dst_unused:UNUSED_PAD src0_sel:WORD_1
	v_mov_b32_e32 v148, v3
	v_pk_fma_f32 v[64:65], v[0:1], s[4:5], v[64:65] op_sel_hi:[1,0,1]
	v_cvt_f32_f16_e32 v0, v208
	v_pk_fma_f32 v[66:67], v[202:203], s[4:5], v[66:67] op_sel_hi:[1,0,1]
	v_cvt_f32_f16_sdwa v1, v208 dst_sel:DWORD dst_unused:UNUSED_PAD src0_sel:WORD_1
	v_cvt_f32_f16_e32 v202, v209
	v_cvt_f32_f16_sdwa v203, v209 dst_sel:DWORD dst_unused:UNUSED_PAD src0_sel:WORD_1
	v_mov_b32_e32 v149, v3
	v_pk_fma_f32 v[32:33], v[0:1], s[4:5], v[32:33] op_sel_hi:[1,0,1]
	v_cvt_f32_f16_e32 v0, v210
	v_pk_fma_f32 v[34:35], v[202:203], s[4:5], v[34:35] op_sel_hi:[1,0,1]
	v_cvt_f32_f16_sdwa v1, v210 dst_sel:DWORD dst_unused:UNUSED_PAD src0_sel:WORD_1
	v_cvt_f32_f16_e32 v202, v211
	v_cvt_f32_f16_sdwa v203, v211 dst_sel:DWORD dst_unused:UNUSED_PAD src0_sel:WORD_1
	v_pk_fma_f32 v[104:105], v[0:1], s[4:5], v[104:105] op_sel_hi:[1,0,1]
	v_cvt_f32_f16_e32 v0, v212
	v_pk_fma_f32 v[106:107], v[202:203], s[4:5], v[106:107] op_sel_hi:[1,0,1]
	v_cvt_f32_f16_sdwa v1, v212 dst_sel:DWORD dst_unused:UNUSED_PAD src0_sel:WORD_1
	v_cvt_f32_f16_e32 v202, v213
	v_cvt_f32_f16_sdwa v203, v213 dst_sel:DWORD dst_unused:UNUSED_PAD src0_sel:WORD_1
	v_mov_b32_e32 v152, v3
	v_pk_fma_f32 v[88:89], v[0:1], s[4:5], v[88:89] op_sel_hi:[1,0,1]
	v_cvt_f32_f16_e32 v0, v214
	v_pk_fma_f32 v[90:91], v[202:203], s[4:5], v[90:91] op_sel_hi:[1,0,1]
	v_cvt_f32_f16_sdwa v1, v214 dst_sel:DWORD dst_unused:UNUSED_PAD src0_sel:WORD_1
	v_cvt_f32_f16_e32 v202, v215
	v_cvt_f32_f16_sdwa v203, v215 dst_sel:DWORD dst_unused:UNUSED_PAD src0_sel:WORD_1
	v_mov_b32_e32 v153, v3
	v_pk_fma_f32 v[68:69], v[0:1], s[4:5], v[68:69] op_sel_hi:[1,0,1]
	v_cvt_f32_f16_e32 v0, v216
	v_pk_fma_f32 v[70:71], v[202:203], s[4:5], v[70:71] op_sel_hi:[1,0,1]
	v_cvt_f32_f16_sdwa v1, v216 dst_sel:DWORD dst_unused:UNUSED_PAD src0_sel:WORD_1
	v_cvt_f32_f16_e32 v202, v217
	v_cvt_f32_f16_sdwa v203, v217 dst_sel:DWORD dst_unused:UNUSED_PAD src0_sel:WORD_1
	v_mov_b32_e32 v134, v3
	v_pk_fma_f32 v[28:29], v[0:1], s[4:5], v[28:29] op_sel_hi:[1,0,1]
	v_pk_fma_f32 v[30:31], v[202:203], s[4:5], v[30:31] op_sel_hi:[1,0,1]
	v_mov_b32_e32 v135, v3
	v_mov_b32_e32 v188, v3
	v_mov_b32_e32 v189, v3
	v_mov_b32_e32 v192, v3
	v_mov_b32_e32 v193, v3
	v_mov_b32_e32 v196, v3
	v_mov_b32_e32 v197, v3
	v_mov_b32_e32 v200, v3
	v_mov_b32_e32 v201, v3
	s_waitcnt vmcnt(0)
	s_nop 0
	v_cvt_f32_f16_e32 v0, v220
	v_cvt_f32_f16_sdwa v1, v220 dst_sel:DWORD dst_unused:UNUSED_PAD src0_sel:WORD_1
	v_cvt_f32_f16_e32 v134, v221
	v_cvt_f32_f16_sdwa v135, v221 dst_sel:DWORD dst_unused:UNUSED_PAD src0_sel:WORD_1
	v_mov_b32_e32 v148, v3
	v_pk_fma_f32 v[128:129], v[0:1], s[4:5], v[128:129] op_sel_hi:[1,0,1]
	v_cvt_f32_f16_e32 v0, v222
	v_cvt_f32_f16_sdwa v1, v222 dst_sel:DWORD dst_unused:UNUSED_PAD src0_sel:WORD_1
	v_pk_fma_f32 v[130:131], v[134:135], s[4:5], v[130:131] op_sel_hi:[1,0,1]
	v_cvt_f32_f16_e32 v134, v223
	v_cvt_f32_f16_sdwa v135, v223 dst_sel:DWORD dst_unused:UNUSED_PAD src0_sel:WORD_1
	v_pk_fma_f32 v[124:125], v[0:1], s[4:5], v[124:125] op_sel_hi:[1,0,1]
	v_cvt_f32_f16_e32 v0, v224
	v_cvt_f32_f16_sdwa v1, v224 dst_sel:DWORD dst_unused:UNUSED_PAD src0_sel:WORD_1
	v_pk_fma_f32 v[126:127], v[134:135], s[4:5], v[126:127] op_sel_hi:[1,0,1]
	v_cvt_f32_f16_e32 v134, v225
	v_cvt_f32_f16_sdwa v135, v225 dst_sel:DWORD dst_unused:UNUSED_PAD src0_sel:WORD_1
	v_pk_fma_f32 v[108:109], v[0:1], s[4:5], v[108:109] op_sel_hi:[1,0,1]
	v_cvt_f32_f16_e32 v0, v218
	v_cvt_f32_f16_sdwa v1, v218 dst_sel:DWORD dst_unused:UNUSED_PAD src0_sel:WORD_1
	v_cvt_f32_f16_e32 v218, v219
	v_cvt_f32_f16_sdwa v219, v219 dst_sel:DWORD dst_unused:UNUSED_PAD src0_sel:WORD_1
	v_pk_fma_f32 v[110:111], v[134:135], s[4:5], v[110:111] op_sel_hi:[1,0,1]
	v_pk_fma_f32 v[92:93], v[0:1], s[4:5], v[92:93] op_sel_hi:[1,0,1]
	v_cvt_f32_f16_e32 v0, v226
	v_pk_fma_f32 v[94:95], v[218:219], s[4:5], v[94:95] op_sel_hi:[1,0,1]
	v_cvt_f32_f16_sdwa v1, v226 dst_sel:DWORD dst_unused:UNUSED_PAD src0_sel:WORD_1
	v_cvt_f32_f16_e32 v218, v227
	v_cvt_f32_f16_sdwa v219, v227 dst_sel:DWORD dst_unused:UNUSED_PAD src0_sel:WORD_1
	v_pk_fma_f32 v[120:121], v[0:1], s[4:5], v[120:121] op_sel_hi:[1,0,1]
	v_cvt_f32_f16_e32 v0, v228
	v_pk_fma_f32 v[122:123], v[218:219], s[4:5], v[122:123] op_sel_hi:[1,0,1]
	v_cvt_f32_f16_sdwa v1, v228 dst_sel:DWORD dst_unused:UNUSED_PAD src0_sel:WORD_1
	v_cvt_f32_f16_e32 v218, v229
	v_cvt_f32_f16_sdwa v219, v229 dst_sel:DWORD dst_unused:UNUSED_PAD src0_sel:WORD_1
	v_mov_b32_e32 v149, v3
	v_pk_fma_f32 v[116:117], v[0:1], s[4:5], v[116:117] op_sel_hi:[1,0,1]
	v_cvt_f32_f16_e32 v0, v230
	v_pk_fma_f32 v[118:119], v[218:219], s[4:5], v[118:119] op_sel_hi:[1,0,1]
	v_cvt_f32_f16_sdwa v1, v230 dst_sel:DWORD dst_unused:UNUSED_PAD src0_sel:WORD_1
	v_cvt_f32_f16_e32 v218, v231
	v_cvt_f32_f16_sdwa v219, v231 dst_sel:DWORD dst_unused:UNUSED_PAD src0_sel:WORD_1
	v_mov_b32_e32 v138, v3
	v_pk_fma_f32 v[112:113], v[0:1], s[4:5], v[112:113] op_sel_hi:[1,0,1]
	v_cvt_f32_f16_e32 v0, v232
	v_pk_fma_f32 v[114:115], v[218:219], s[4:5], v[114:115] op_sel_hi:[1,0,1]
	v_cvt_f32_f16_sdwa v1, v232 dst_sel:DWORD dst_unused:UNUSED_PAD src0_sel:WORD_1
	v_cvt_f32_f16_e32 v218, v233
	v_cvt_f32_f16_sdwa v219, v233 dst_sel:DWORD dst_unused:UNUSED_PAD src0_sel:WORD_1
	v_mov_b32_e32 v139, v3
	v_pk_fma_f32 v[96:97], v[0:1], s[4:5], v[96:97] op_sel_hi:[1,0,1]
	v_add_u32_e32 v0, 0x28000, v2
	v_pk_fma_f32 v[98:99], v[218:219], s[4:5], v[98:99] op_sel_hi:[1,0,1]
	v_mov_b32_e32 v1, v3
	v_add_u32_e32 v2, 0x2c000, v2
	v_lshl_add_u64 v[132:133], v[0:1], 1, s[64:65]
	v_lshl_add_u64 v[134:135], v[2:3], 1, s[64:65]
	global_load_dwordx2 v[0:1], v[132:133], off
	global_load_dwordx2 v[146:147], v[132:133], off offset:32
	global_load_dwordx2 v[136:137], v[132:133], off offset:256
	s_nop 0
	global_load_dwordx2 v[132:133], v[132:133], off offset:288
	s_nop 0
	global_load_dwordx2 v[150:151], v[134:135], off
	global_load_dwordx2 v[186:187], v[134:135], off offset:32
	global_load_dwordx2 v[190:191], v[134:135], off offset:256
	global_load_dwordx2 v[194:195], v[134:135], off offset:288
	v_mov_b32_e32 v2, v3
	v_mov_b32_e32 v134, v3
	v_mov_b32_e32 v135, v3
	v_mov_b32_e32 v152, v3
	v_mov_b32_e32 v153, v3
	v_mov_b32_e32 v188, v3
	v_mov_b32_e32 v189, v3
	v_mov_b32_e32 v192, v3
	v_mov_b32_e32 v193, v3
	v_mov_b32_e32 v196, v3
	v_mov_b32_e32 v197, v3
	s_waitcnt vmcnt(7)
	v_mov_b64_e32 v[200:201], v[2:3]
	v_mov_b64_e32 v[198:199], v[0:1]
	s_waitcnt vmcnt(0)
	s_nop 0
	v_cvt_f32_f16_e32 v0, v198
	v_cvt_f32_f16_sdwa v1, v198 dst_sel:DWORD dst_unused:UNUSED_PAD src0_sel:WORD_1
	v_cvt_f32_f16_e32 v134, v199
	v_cvt_f32_f16_sdwa v135, v199 dst_sel:DWORD dst_unused:UNUSED_PAD src0_sel:WORD_1
	v_pk_fma_f32 v[80:81], v[0:1], s[4:5], v[80:81] op_sel_hi:[1,0,1]
	v_cvt_f32_f16_e32 v0, v146
	v_cvt_f32_f16_sdwa v1, v146 dst_sel:DWORD dst_unused:UNUSED_PAD src0_sel:WORD_1
	v_pk_fma_f32 v[82:83], v[134:135], s[4:5], v[82:83] op_sel_hi:[1,0,1]
	v_cvt_f32_f16_e32 v134, v147
	v_cvt_f32_f16_sdwa v135, v147 dst_sel:DWORD dst_unused:UNUSED_PAD src0_sel:WORD_1
	v_pk_fma_f32 v[76:77], v[0:1], s[4:5], v[76:77] op_sel_hi:[1,0,1]
	v_cvt_f32_f16_e32 v0, v136
	v_cvt_f32_f16_sdwa v1, v136 dst_sel:DWORD dst_unused:UNUSED_PAD src0_sel:WORD_1
	v_pk_fma_f32 v[78:79], v[134:135], s[4:5], v[78:79] op_sel_hi:[1,0,1]
	v_cvt_f32_f16_e32 v134, v137
	v_cvt_f32_f16_sdwa v135, v137 dst_sel:DWORD dst_unused:UNUSED_PAD src0_sel:WORD_1
	v_pk_fma_f32 v[56:57], v[0:1], s[4:5], v[56:57] op_sel_hi:[1,0,1]
	v_cvt_f32_f16_e32 v0, v132
	v_cvt_f32_f16_sdwa v1, v132 dst_sel:DWORD dst_unused:UNUSED_PAD src0_sel:WORD_1
	v_cvt_f32_f16_e32 v132, v133
	v_cvt_f32_f16_sdwa v133, v133 dst_sel:DWORD dst_unused:UNUSED_PAD src0_sel:WORD_1
	v_pk_fma_f32 v[58:59], v[134:135], s[4:5], v[58:59] op_sel_hi:[1,0,1]
	v_pk_fma_f32 v[52:53], v[0:1], s[4:5], v[52:53] op_sel_hi:[1,0,1]
	v_cvt_f32_f16_e32 v0, v150
	v_pk_fma_f32 v[54:55], v[132:133], s[4:5], v[54:55] op_sel_hi:[1,0,1]
	v_cvt_f32_f16_sdwa v1, v150 dst_sel:DWORD dst_unused:UNUSED_PAD src0_sel:WORD_1
	v_cvt_f32_f16_e32 v132, v151
	v_cvt_f32_f16_sdwa v133, v151 dst_sel:DWORD dst_unused:UNUSED_PAD src0_sel:WORD_1
	v_mov_b32_e32 v134, v20
	v_pk_fma_f32 v[72:73], v[0:1], s[4:5], v[72:73] op_sel_hi:[1,0,1]
	v_cvt_f32_f16_e32 v0, v186
	v_pk_fma_f32 v[74:75], v[132:133], s[4:5], v[74:75] op_sel_hi:[1,0,1]
	v_cvt_f32_f16_sdwa v1, v186 dst_sel:DWORD dst_unused:UNUSED_PAD src0_sel:WORD_1
	v_cvt_f32_f16_e32 v132, v187
	v_cvt_f32_f16_sdwa v133, v187 dst_sel:DWORD dst_unused:UNUSED_PAD src0_sel:WORD_1
	v_mov_b32_e32 v135, v23
	v_pk_fma_f32 v[60:61], v[0:1], s[4:5], v[60:61] op_sel_hi:[1,0,1]
	v_cvt_f32_f16_e32 v0, v190
	v_pk_fma_f32 v[62:63], v[132:133], s[4:5], v[62:63] op_sel_hi:[1,0,1]
	v_cvt_f32_f16_sdwa v1, v190 dst_sel:DWORD dst_unused:UNUSED_PAD src0_sel:WORD_1
	v_cvt_f32_f16_e32 v132, v191
	v_cvt_f32_f16_sdwa v133, v191 dst_sel:DWORD dst_unused:UNUSED_PAD src0_sel:WORD_1
	v_add_f32_e32 v137, v14, v15
	v_pk_fma_f32 v[48:49], v[0:1], s[4:5], v[48:49] op_sel_hi:[1,0,1]
	v_cvt_f32_f16_e32 v0, v194
	v_pk_fma_f32 v[50:51], v[132:133], s[4:5], v[50:51] op_sel_hi:[1,0,1]
	v_cvt_f32_f16_sdwa v1, v194 dst_sel:DWORD dst_unused:UNUSED_PAD src0_sel:WORD_1
	v_cvt_f32_f16_e32 v132, v195
	v_cvt_f32_f16_sdwa v133, v195 dst_sel:DWORD dst_unused:UNUSED_PAD src0_sel:WORD_1
	v_mov_b32_e32 v136, v5
	v_pk_fma_f32 v[44:45], v[0:1], s[4:5], v[44:45] op_sel_hi:[1,0,1]
	v_mov_b32_e32 v0, v37
	v_pk_fma_f32 v[46:47], v[132:133], s[4:5], v[46:47] op_sel_hi:[1,0,1]
	v_mov_b32_e32 v1, v38
	v_mov_b32_e32 v132, v36
	v_mov_b32_e32 v133, v39
	v_pk_add_f32 v[0:1], v[0:1], v[132:133]
	v_mov_b32_e32 v132, v21
	v_mov_b32_e32 v133, v22
	v_pk_add_f32 v[132:133], v[132:133], v[134:135]
	v_add_f32_e32 v0, v0, v1
	v_pk_add_f32 v[132:133], v[132:133], v[132:133] op_sel_hi:[0,1]
	v_add_f32_e32 v1, 0, v0
	v_add_f32_e32 v135, v12, v13
	v_mov_b32_e32 v134, v4
	v_mov_b32_e32 v132, v6
	v_mov_b32_e32 v0, v7
	v_pk_add_f32 v[134:135], v[134:135], v[136:137]
	v_pk_add_f32 v[0:1], v[132:133], v[0:1]
	s_lshl_b32 s4, s8, 3
	v_pk_add_f32 v[0:1], v[134:135], v[0:1]
	s_add_i32 s7, s4, 0
	v_add_f32_e32 v0, v0, v1
	v_mov_b32_e32 v1, v0
	s_nop 1
	v_permlane16_swap_b32 v0, v1
	s_waitcnt lgkmcnt(0)
	v_add_f32_e32 v0, v0, v1
	v_mov_b32_e32 v1, v0
	s_nop 1
	v_permlane32_swap_b32 v0, v1
	s_waitcnt lgkmcnt(0)
	v_add_f32_e32 v0, v0, v1
	v_fmamk_f32 v2, v0, 0xbc800000, v39
	v_fmamk_f32 v133, v0, 0xbc800000, v37
	v_fmamk_f32 v1, v0, 0xbc800000, v38
	v_fmamk_f32 v132, v0, 0xbc800000, v36
	v_mul_f32_e32 v133, v133, v133
	v_mul_f32_e32 v2, v2, v2
	v_fmac_f32_e32 v133, v132, v132
	v_fmac_f32_e32 v2, v1, v1
	v_fmamk_f32 v132, v0, 0xbc800000, v23
	v_fmamk_f32 v134, v0, 0xbc800000, v21
	v_add_f32_e32 v1, v133, v2
	v_fmamk_f32 v2, v0, 0xbc800000, v22
	v_fmamk_f32 v133, v0, 0xbc800000, v20
	v_mul_f32_e32 v134, v134, v134
	v_mul_f32_e32 v132, v132, v132
	v_fmac_f32_e32 v134, v133, v133
	v_fmac_f32_e32 v132, v2, v2
	v_add_f32_e32 v2, v134, v132
	v_fmamk_f32 v132, v0, 0xbc800000, v15
	v_fmamk_f32 v134, v0, 0xbc800000, v13
	v_add_f32_e32 v1, v1, v2
	v_fmamk_f32 v2, v0, 0xbc800000, v14
	v_fmamk_f32 v133, v0, 0xbc800000, v12
	v_mul_f32_e32 v134, v134, v134
	v_mul_f32_e32 v132, v132, v132
	v_fmac_f32_e32 v134, v133, v133
	v_fmac_f32_e32 v132, v2, v2
	v_add_f32_e32 v2, v134, v132
	v_fmamk_f32 v132, v0, 0xbc800000, v7
	v_fmamk_f32 v134, v0, 0xbc800000, v5
	v_add_f32_e32 v1, v2, v1
	v_fmamk_f32 v2, v0, 0xbc800000, v6
	v_fmamk_f32 v133, v0, 0xbc800000, v4
	v_mul_f32_e32 v134, v134, v134
	v_mul_f32_e32 v132, v132, v132
	v_fmac_f32_e32 v134, v133, v133
	v_fmac_f32_e32 v132, v2, v2
	v_add_f32_e32 v2, v134, v132
	v_add_f32_e32 v1, v2, v1
	v_mov_b32_e32 v2, v1
	s_nop 1
	v_permlane16_swap_b32 v1, v2
	s_waitcnt lgkmcnt(0)
	v_add_f32_e32 v1, v1, v2
	v_mov_b32_e32 v2, v1
	s_nop 1
	v_permlane32_swap_b32 v1, v2
	s_and_saveexec_b64 s[4:5], vcc
	s_cbranch_execz .LBB0_1156
	s_lshl_b32 s8, s0, 11
	s_add_i32 s8, s7, s8
	v_mul_f32_e32 v0, 0x3c800000, v0
	s_waitcnt lgkmcnt(0)
	v_add_f32_e32 v1, v1, v2
	v_lshl_add_u32 v2, v144, 5, s8
	ds_write_b64 v2, v[0:1]
.LBB0_1156:
	s_or_b64 exec, exec, s[4:5]
	v_mov_b32_e32 v0, v41
	v_mov_b32_e32 v1, v42
	v_mov_b32_e32 v132, v40
	v_mov_b32_e32 v133, v43
	v_pk_add_f32 v[0:1], v[0:1], v[132:133]
	v_mov_b32_e32 v132, v25
	v_mov_b32_e32 v133, v26
	v_mov_b32_e32 v134, v24
	v_mov_b32_e32 v135, v27
	v_pk_add_f32 v[132:133], v[132:133], v[134:135]
	v_add_f32_e32 v0, v0, v1
	v_pk_add_f32 v[132:133], v[132:133], v[132:133] op_sel_hi:[0,1]
	v_add_f32_e32 v1, 0, v0
	v_add_f32_e32 v135, v16, v17
	v_add_f32_e32 v137, v18, v19
	v_mov_b32_e32 v134, v8
	v_mov_b32_e32 v136, v9
	v_mov_b32_e32 v132, v10
	v_mov_b32_e32 v0, v11
	v_pk_add_f32 v[134:135], v[134:135], v[136:137]
	v_pk_add_f32 v[0:1], v[132:133], v[0:1]
	s_nop 0
	v_pk_add_f32 v[0:1], v[134:135], v[0:1]
	s_nop 0
	v_add_f32_e32 v0, v0, v1
	v_mov_b32_e32 v1, v0
	s_nop 1
	v_permlane16_swap_b32 v0, v1
	s_waitcnt lgkmcnt(0)
	v_add_f32_e32 v0, v0, v1
	v_mov_b32_e32 v1, v0
	s_nop 1
	v_permlane32_swap_b32 v0, v1
	s_waitcnt lgkmcnt(0)
	v_add_f32_e32 v0, v0, v1
	v_fmamk_f32 v2, v0, 0xbc800000, v43
	v_fmamk_f32 v133, v0, 0xbc800000, v41
	v_fmamk_f32 v1, v0, 0xbc800000, v42
	v_fmamk_f32 v132, v0, 0xbc800000, v40
	v_mul_f32_e32 v133, v133, v133
	v_mul_f32_e32 v2, v2, v2
	v_fmac_f32_e32 v133, v132, v132
	v_fmac_f32_e32 v2, v1, v1
	v_fmamk_f32 v132, v0, 0xbc800000, v27
	v_fmamk_f32 v134, v0, 0xbc800000, v25
	v_add_f32_e32 v1, v133, v2
	v_fmamk_f32 v2, v0, 0xbc800000, v26
	v_fmamk_f32 v133, v0, 0xbc800000, v24
	v_mul_f32_e32 v134, v134, v134
	v_mul_f32_e32 v132, v132, v132
	v_fmac_f32_e32 v134, v133, v133
	v_fmac_f32_e32 v132, v2, v2
	v_add_f32_e32 v2, v134, v132
	v_fmamk_f32 v132, v0, 0xbc800000, v19
	v_fmamk_f32 v134, v0, 0xbc800000, v17
	v_add_f32_e32 v1, v1, v2
	v_fmamk_f32 v2, v0, 0xbc800000, v18
	v_fmamk_f32 v133, v0, 0xbc800000, v16
	v_mul_f32_e32 v134, v134, v134
	v_mul_f32_e32 v132, v132, v132
	v_fmac_f32_e32 v134, v133, v133
	v_fmac_f32_e32 v132, v2, v2
	v_add_f32_e32 v2, v134, v132
	v_fmamk_f32 v132, v0, 0xbc800000, v11
	v_fmamk_f32 v134, v0, 0xbc800000, v9
	v_add_f32_e32 v1, v2, v1
	v_fmamk_f32 v2, v0, 0xbc800000, v10
	v_fmamk_f32 v133, v0, 0xbc800000, v8
	v_mul_f32_e32 v134, v134, v134
	v_mul_f32_e32 v132, v132, v132
	v_fmac_f32_e32 v134, v133, v133
	v_fmac_f32_e32 v132, v2, v2
	v_add_f32_e32 v2, v134, v132
	v_add_f32_e32 v1, v2, v1
	v_mov_b32_e32 v2, v1
	s_nop 1
	v_permlane16_swap_b32 v1, v2
	s_waitcnt lgkmcnt(0)
	v_add_f32_e32 v1, v1, v2
	v_mov_b32_e32 v2, v1
	s_nop 1
	v_permlane32_swap_b32 v1, v2
	s_and_saveexec_b64 s[4:5], vcc
	v_readlane_b32 s56, v253, 19
	v_readlane_b32 s16, v253, 21
	v_readlane_b32 s57, v253, 20
	v_readlane_b32 s17, v253, 22
	s_cbranch_execz .LBB0_1158
	s_lshl_b32 s8, s0, 11
	s_add_i32 s8, s7, s8
	v_mul_f32_e32 v0, 0x3c800000, v0
	s_waitcnt lgkmcnt(0)
	v_add_f32_e32 v1, v1, v2
	v_lshl_add_u32 v2, v144, 5, s8
	ds_write_b64 v2, v[0:1] offset:512
.LBB0_1158:
	s_or_b64 exec, exec, s[4:5]
	v_mov_b32_e32 v0, v101
	v_mov_b32_e32 v1, v102
	v_mov_b32_e32 v132, v100
	v_mov_b32_e32 v133, v103
	v_pk_add_f32 v[0:1], v[0:1], v[132:133]
	v_mov_b32_e32 v132, v85
	v_mov_b32_e32 v133, v86
	v_mov_b32_e32 v134, v84
	v_mov_b32_e32 v135, v87
	v_pk_add_f32 v[132:133], v[132:133], v[134:135]
	v_add_f32_e32 v0, v0, v1
	v_pk_add_f32 v[132:133], v[132:133], v[132:133] op_sel_hi:[0,1]
	v_add_f32_e32 v1, 0, v0
	v_add_f32_e32 v135, v64, v65
	v_add_f32_e32 v137, v66, v67
	v_mov_b32_e32 v134, v32
	v_mov_b32_e32 v136, v33
	v_mov_b32_e32 v132, v34
	v_mov_b32_e32 v0, v35
	v_pk_add_f32 v[134:135], v[134:135], v[136:137]
	v_pk_add_f32 v[0:1], v[132:133], v[0:1]
	s_nop 0
	v_pk_add_f32 v[0:1], v[134:135], v[0:1]
	s_nop 0
	v_add_f32_e32 v0, v0, v1
	v_mov_b32_e32 v1, v0
	s_nop 1
	v_permlane16_swap_b32 v0, v1
	s_waitcnt lgkmcnt(0)
	v_add_f32_e32 v0, v0, v1
	v_mov_b32_e32 v1, v0
	s_nop 1
	v_permlane32_swap_b32 v0, v1
	s_waitcnt lgkmcnt(0)
	v_add_f32_e32 v0, v0, v1
	v_fmamk_f32 v2, v0, 0xbc800000, v103
	v_fmamk_f32 v133, v0, 0xbc800000, v101
	v_fmamk_f32 v1, v0, 0xbc800000, v102
	v_fmamk_f32 v132, v0, 0xbc800000, v100
	v_mul_f32_e32 v133, v133, v133
	v_mul_f32_e32 v2, v2, v2
	v_fmac_f32_e32 v133, v132, v132
	v_fmac_f32_e32 v2, v1, v1
	v_fmamk_f32 v132, v0, 0xbc800000, v87
	v_fmamk_f32 v134, v0, 0xbc800000, v85
	v_add_f32_e32 v1, v133, v2
	v_fmamk_f32 v2, v0, 0xbc800000, v86
	v_fmamk_f32 v133, v0, 0xbc800000, v84
	v_mul_f32_e32 v134, v134, v134
	v_mul_f32_e32 v132, v132, v132
	v_fmac_f32_e32 v134, v133, v133
	v_fmac_f32_e32 v132, v2, v2
	v_add_f32_e32 v2, v134, v132
	v_fmamk_f32 v132, v0, 0xbc800000, v67
	v_fmamk_f32 v134, v0, 0xbc800000, v65
	v_add_f32_e32 v1, v1, v2
	v_fmamk_f32 v2, v0, 0xbc800000, v66
	v_fmamk_f32 v133, v0, 0xbc800000, v64
	v_mul_f32_e32 v134, v134, v134
	v_mul_f32_e32 v132, v132, v132
	v_fmac_f32_e32 v134, v133, v133
	v_fmac_f32_e32 v132, v2, v2
	v_add_f32_e32 v2, v134, v132
	v_fmamk_f32 v132, v0, 0xbc800000, v35
	v_fmamk_f32 v134, v0, 0xbc800000, v33
	v_add_f32_e32 v1, v2, v1
	v_fmamk_f32 v2, v0, 0xbc800000, v34
	v_fmamk_f32 v133, v0, 0xbc800000, v32
	v_mul_f32_e32 v134, v134, v134
	v_mul_f32_e32 v132, v132, v132
	v_fmac_f32_e32 v134, v133, v133
	v_fmac_f32_e32 v132, v2, v2
	v_add_f32_e32 v2, v134, v132
	v_add_f32_e32 v1, v2, v1
	v_mov_b32_e32 v2, v1
	s_nop 1
	v_permlane16_swap_b32 v1, v2
	s_waitcnt lgkmcnt(0)
	v_add_f32_e32 v1, v1, v2
	v_mov_b32_e32 v2, v1
	s_nop 1
	v_permlane32_swap_b32 v1, v2
	s_and_saveexec_b64 s[4:5], vcc
	s_cbranch_execz .LBB0_1160
	s_lshl_b32 s8, s0, 11
	s_add_i32 s8, s7, s8
	v_mul_f32_e32 v0, 0x3c800000, v0
	s_waitcnt lgkmcnt(0)
	v_add_f32_e32 v1, v1, v2
	v_lshl_add_u32 v2, v144, 5, s8
	ds_write_b64 v2, v[0:1] offset:1024
.LBB0_1160:
	s_or_b64 exec, exec, s[4:5]
	v_mov_b32_e32 v0, v105
	v_mov_b32_e32 v1, v106
	v_mov_b32_e32 v132, v104
	v_mov_b32_e32 v133, v107
	v_pk_add_f32 v[0:1], v[0:1], v[132:133]
	v_mov_b32_e32 v132, v89
	v_mov_b32_e32 v133, v90
	v_mov_b32_e32 v134, v88
	v_mov_b32_e32 v135, v91
	v_pk_add_f32 v[132:133], v[132:133], v[134:135]
	v_add_f32_e32 v0, v0, v1
	v_pk_add_f32 v[132:133], v[132:133], v[132:133] op_sel_hi:[0,1]
	v_add_f32_e32 v1, 0, v0
	v_add_f32_e32 v135, v68, v69
	v_add_f32_e32 v137, v70, v71
	v_mov_b32_e32 v134, v28
	v_mov_b32_e32 v136, v29
	v_mov_b32_e32 v132, v30
	v_mov_b32_e32 v0, v31
	v_pk_add_f32 v[134:135], v[134:135], v[136:137]
	v_pk_add_f32 v[0:1], v[132:133], v[0:1]
	s_nop 0
	v_pk_add_f32 v[0:1], v[134:135], v[0:1]
	s_nop 0
	v_add_f32_e32 v0, v0, v1
	v_mov_b32_e32 v1, v0
	s_nop 1
	v_permlane16_swap_b32 v0, v1
	s_waitcnt lgkmcnt(0)
	v_add_f32_e32 v0, v0, v1
	v_mov_b32_e32 v1, v0
	s_nop 1
	v_permlane32_swap_b32 v0, v1
	s_waitcnt lgkmcnt(0)
	v_add_f32_e32 v0, v0, v1
	v_fmamk_f32 v2, v0, 0xbc800000, v107
	v_fmamk_f32 v133, v0, 0xbc800000, v105
	v_fmamk_f32 v1, v0, 0xbc800000, v106
	v_fmamk_f32 v132, v0, 0xbc800000, v104
	v_mul_f32_e32 v133, v133, v133
	v_mul_f32_e32 v2, v2, v2
	v_fmac_f32_e32 v133, v132, v132
	v_fmac_f32_e32 v2, v1, v1
	v_fmamk_f32 v132, v0, 0xbc800000, v91
	v_fmamk_f32 v134, v0, 0xbc800000, v89
	v_add_f32_e32 v1, v133, v2
	v_fmamk_f32 v2, v0, 0xbc800000, v90
	v_fmamk_f32 v133, v0, 0xbc800000, v88
	v_mul_f32_e32 v134, v134, v134
	v_mul_f32_e32 v132, v132, v132
	v_fmac_f32_e32 v134, v133, v133
	v_fmac_f32_e32 v132, v2, v2
	v_add_f32_e32 v2, v134, v132
	v_fmamk_f32 v132, v0, 0xbc800000, v71
	v_fmamk_f32 v134, v0, 0xbc800000, v69
	v_add_f32_e32 v1, v1, v2
	v_fmamk_f32 v2, v0, 0xbc800000, v70
	v_fmamk_f32 v133, v0, 0xbc800000, v68
	v_mul_f32_e32 v134, v134, v134
	v_mul_f32_e32 v132, v132, v132
	v_fmac_f32_e32 v134, v133, v133
	v_fmac_f32_e32 v132, v2, v2
	v_add_f32_e32 v2, v134, v132
	v_fmamk_f32 v132, v0, 0xbc800000, v31
	v_fmamk_f32 v134, v0, 0xbc800000, v29
	v_add_f32_e32 v1, v2, v1
	v_fmamk_f32 v2, v0, 0xbc800000, v30
	v_fmamk_f32 v133, v0, 0xbc800000, v28
	v_mul_f32_e32 v134, v134, v134
	v_mul_f32_e32 v132, v132, v132
	v_fmac_f32_e32 v134, v133, v133
	v_fmac_f32_e32 v132, v2, v2
	v_add_f32_e32 v2, v134, v132
	v_add_f32_e32 v1, v2, v1
	v_mov_b32_e32 v2, v1
	s_nop 1
	v_permlane16_swap_b32 v1, v2
	s_waitcnt lgkmcnt(0)
	v_add_f32_e32 v1, v1, v2
	v_mov_b32_e32 v2, v1
	s_nop 1
	v_permlane32_swap_b32 v1, v2
	s_and_saveexec_b64 s[4:5], vcc
	s_cbranch_execz .LBB0_1162
	s_lshl_b32 s8, s0, 11
	s_add_i32 s8, s7, s8
	v_mul_f32_e32 v0, 0x3c800000, v0
	s_waitcnt lgkmcnt(0)
	v_add_f32_e32 v1, v1, v2
	v_lshl_add_u32 v2, v144, 5, s8
	ds_write_b64 v2, v[0:1] offset:1536
.LBB0_1162:
	s_or_b64 exec, exec, s[4:5]
	v_mov_b32_e32 v0, v129
	v_mov_b32_e32 v1, v130
	v_mov_b32_e32 v132, v128
	v_mov_b32_e32 v133, v131
	v_pk_add_f32 v[0:1], v[0:1], v[132:133]
	v_mov_b32_e32 v132, v125
	v_mov_b32_e32 v133, v126
	v_mov_b32_e32 v134, v124
	v_mov_b32_e32 v135, v127
	v_pk_add_f32 v[132:133], v[132:133], v[134:135]
	v_add_f32_e32 v0, v0, v1
	v_pk_add_f32 v[132:133], v[132:133], v[132:133] op_sel_hi:[0,1]
	v_add_f32_e32 v1, 0, v0
	v_add_f32_e32 v135, v108, v109
	v_add_f32_e32 v137, v110, v111
	v_mov_b32_e32 v134, v92
	v_mov_b32_e32 v136, v93
	v_mov_b32_e32 v132, v94
	v_mov_b32_e32 v0, v95
	v_pk_add_f32 v[134:135], v[134:135], v[136:137]
	v_pk_add_f32 v[0:1], v[132:133], v[0:1]
	s_nop 0
	v_pk_add_f32 v[0:1], v[134:135], v[0:1]
	s_nop 0
	v_add_f32_e32 v0, v0, v1
	v_mov_b32_e32 v1, v0
	s_nop 1
	v_permlane16_swap_b32 v0, v1
	s_waitcnt lgkmcnt(0)
	v_add_f32_e32 v0, v0, v1
	v_mov_b32_e32 v1, v0
	s_nop 1
	v_permlane32_swap_b32 v0, v1
	s_waitcnt lgkmcnt(0)
	v_add_f32_e32 v0, v0, v1
	v_fmamk_f32 v2, v0, 0xbc800000, v131
	v_fmamk_f32 v133, v0, 0xbc800000, v129
	v_fmamk_f32 v1, v0, 0xbc800000, v130
	v_fmamk_f32 v132, v0, 0xbc800000, v128
	v_mul_f32_e32 v133, v133, v133
	v_mul_f32_e32 v2, v2, v2
	v_fmac_f32_e32 v133, v132, v132
	v_fmac_f32_e32 v2, v1, v1
	v_fmamk_f32 v132, v0, 0xbc800000, v127
	v_fmamk_f32 v134, v0, 0xbc800000, v125
	v_add_f32_e32 v1, v133, v2
	v_fmamk_f32 v2, v0, 0xbc800000, v126
	v_fmamk_f32 v133, v0, 0xbc800000, v124
	v_mul_f32_e32 v134, v134, v134
	v_mul_f32_e32 v132, v132, v132
	v_fmac_f32_e32 v134, v133, v133
	v_fmac_f32_e32 v132, v2, v2
	v_add_f32_e32 v2, v134, v132
	v_fmamk_f32 v132, v0, 0xbc800000, v111
	v_fmamk_f32 v134, v0, 0xbc800000, v109
	v_add_f32_e32 v1, v1, v2
	v_fmamk_f32 v2, v0, 0xbc800000, v110
	v_fmamk_f32 v133, v0, 0xbc800000, v108
	v_mul_f32_e32 v134, v134, v134
	v_mul_f32_e32 v132, v132, v132
	v_fmac_f32_e32 v134, v133, v133
	v_fmac_f32_e32 v132, v2, v2
	v_add_f32_e32 v2, v134, v132
	v_fmamk_f32 v132, v0, 0xbc800000, v95
	v_fmamk_f32 v134, v0, 0xbc800000, v93
	v_add_f32_e32 v1, v2, v1
	v_fmamk_f32 v2, v0, 0xbc800000, v94
	v_fmamk_f32 v133, v0, 0xbc800000, v92
	v_mul_f32_e32 v134, v134, v134
	v_mul_f32_e32 v132, v132, v132
	v_fmac_f32_e32 v134, v133, v133
	v_fmac_f32_e32 v132, v2, v2
	v_add_f32_e32 v2, v134, v132
	v_add_f32_e32 v1, v2, v1
	v_mov_b32_e32 v2, v1
	s_nop 1
	v_permlane16_swap_b32 v1, v2
	s_waitcnt lgkmcnt(0)
	v_add_f32_e32 v1, v1, v2
	v_mov_b32_e32 v2, v1
	s_nop 1
	v_permlane32_swap_b32 v1, v2
	s_and_saveexec_b64 s[4:5], vcc
	s_cbranch_execz .LBB0_1164
	s_lshl_b32 s8, s0, 11
	s_add_i32 s8, s7, s8
	v_mul_f32_e32 v0, 0x3c800000, v0
	s_waitcnt lgkmcnt(0)
	v_add_f32_e32 v1, v1, v2
	v_lshl_add_u32 v2, v144, 5, s8
	ds_write_b64 v2, v[0:1] offset:4096
.LBB0_1164:
	s_or_b64 exec, exec, s[4:5]
	v_mov_b32_e32 v0, v121
	v_mov_b32_e32 v1, v122
	v_mov_b32_e32 v132, v120
	v_mov_b32_e32 v133, v123
	v_pk_add_f32 v[0:1], v[0:1], v[132:133]
	v_mov_b32_e32 v132, v117
	v_mov_b32_e32 v133, v118
	v_mov_b32_e32 v134, v116
	v_mov_b32_e32 v135, v119
	v_pk_add_f32 v[132:133], v[132:133], v[134:135]
	v_add_f32_e32 v0, v0, v1
	v_pk_add_f32 v[132:133], v[132:133], v[132:133] op_sel_hi:[0,1]
	v_add_f32_e32 v1, 0, v0
	v_add_f32_e32 v135, v112, v113
	v_add_f32_e32 v137, v114, v115
	v_mov_b32_e32 v134, v96
	v_mov_b32_e32 v136, v97
	v_mov_b32_e32 v132, v98
	v_mov_b32_e32 v0, v99
	v_pk_add_f32 v[134:135], v[134:135], v[136:137]
	v_pk_add_f32 v[0:1], v[132:133], v[0:1]
	s_nop 0
	v_pk_add_f32 v[0:1], v[134:135], v[0:1]
	s_nop 0
	v_add_f32_e32 v0, v0, v1
	v_mov_b32_e32 v1, v0
	s_nop 1
	v_permlane16_swap_b32 v0, v1
	s_waitcnt lgkmcnt(0)
	v_add_f32_e32 v0, v0, v1
	v_mov_b32_e32 v1, v0
	s_nop 1
	v_permlane32_swap_b32 v0, v1
	s_waitcnt lgkmcnt(0)
	v_add_f32_e32 v0, v0, v1
	v_fmamk_f32 v2, v0, 0xbc800000, v123
	v_fmamk_f32 v133, v0, 0xbc800000, v121
	v_fmamk_f32 v1, v0, 0xbc800000, v122
	v_fmamk_f32 v132, v0, 0xbc800000, v120
	v_mul_f32_e32 v133, v133, v133
	v_mul_f32_e32 v2, v2, v2
	v_fmac_f32_e32 v133, v132, v132
	v_fmac_f32_e32 v2, v1, v1
	v_fmamk_f32 v132, v0, 0xbc800000, v119
	v_fmamk_f32 v134, v0, 0xbc800000, v117
	v_add_f32_e32 v1, v133, v2
	v_fmamk_f32 v2, v0, 0xbc800000, v118
	v_fmamk_f32 v133, v0, 0xbc800000, v116
	v_mul_f32_e32 v134, v134, v134
	v_mul_f32_e32 v132, v132, v132
	v_fmac_f32_e32 v134, v133, v133
	v_fmac_f32_e32 v132, v2, v2
	v_add_f32_e32 v2, v134, v132
	v_fmamk_f32 v132, v0, 0xbc800000, v115
	v_fmamk_f32 v134, v0, 0xbc800000, v113
	v_add_f32_e32 v1, v1, v2
	v_fmamk_f32 v2, v0, 0xbc800000, v114
	v_fmamk_f32 v133, v0, 0xbc800000, v112
	v_mul_f32_e32 v134, v134, v134
	v_mul_f32_e32 v132, v132, v132
	v_fmac_f32_e32 v134, v133, v133
	v_fmac_f32_e32 v132, v2, v2
	v_add_f32_e32 v2, v134, v132
	v_fmamk_f32 v132, v0, 0xbc800000, v99
	v_fmamk_f32 v134, v0, 0xbc800000, v97
	v_add_f32_e32 v1, v2, v1
	v_fmamk_f32 v2, v0, 0xbc800000, v98
	v_fmamk_f32 v133, v0, 0xbc800000, v96
	v_mul_f32_e32 v134, v134, v134
	v_mul_f32_e32 v132, v132, v132
	v_fmac_f32_e32 v134, v133, v133
	v_fmac_f32_e32 v132, v2, v2
	v_add_f32_e32 v2, v134, v132
	v_add_f32_e32 v1, v2, v1
	v_mov_b32_e32 v2, v1
	s_nop 1
	v_permlane16_swap_b32 v1, v2
	s_waitcnt lgkmcnt(0)
	v_add_f32_e32 v1, v1, v2
	v_mov_b32_e32 v2, v1
	s_nop 1
	v_permlane32_swap_b32 v1, v2
	s_and_saveexec_b64 s[4:5], vcc
	s_cbranch_execz .LBB0_1166
	s_lshl_b32 s8, s0, 11
	s_add_i32 s8, s7, s8
	v_mul_f32_e32 v0, 0x3c800000, v0
	s_waitcnt lgkmcnt(0)
	v_add_f32_e32 v1, v1, v2
	v_lshl_add_u32 v2, v144, 5, s8
	ds_write_b64 v2, v[0:1] offset:4608
.LBB0_1166:
	s_or_b64 exec, exec, s[4:5]
	v_mov_b32_e32 v0, v81
	v_mov_b32_e32 v1, v82
	v_mov_b32_e32 v132, v80
	v_mov_b32_e32 v133, v83
	v_pk_add_f32 v[0:1], v[0:1], v[132:133]
	v_mov_b32_e32 v132, v77
	v_mov_b32_e32 v133, v78
	v_mov_b32_e32 v134, v76
	v_mov_b32_e32 v135, v79
	v_pk_add_f32 v[132:133], v[132:133], v[134:135]
	v_add_f32_e32 v0, v0, v1
	v_pk_add_f32 v[132:133], v[132:133], v[132:133] op_sel_hi:[0,1]
	v_add_f32_e32 v1, 0, v0
	v_add_f32_e32 v135, v56, v57
	v_add_f32_e32 v137, v58, v59
	v_mov_b32_e32 v134, v52
	v_mov_b32_e32 v136, v53
	v_mov_b32_e32 v132, v54
	v_mov_b32_e32 v0, v55
	v_pk_add_f32 v[134:135], v[134:135], v[136:137]
	v_pk_add_f32 v[0:1], v[132:133], v[0:1]
	s_nop 0
	v_pk_add_f32 v[0:1], v[134:135], v[0:1]
	s_nop 0
	v_add_f32_e32 v0, v0, v1
	v_mov_b32_e32 v1, v0
	s_nop 1
	v_permlane16_swap_b32 v0, v1
	s_waitcnt lgkmcnt(0)
	v_add_f32_e32 v0, v0, v1
	v_mov_b32_e32 v1, v0
	s_nop 1
	v_permlane32_swap_b32 v0, v1
	s_waitcnt lgkmcnt(0)
	v_add_f32_e32 v0, v0, v1
	v_fmamk_f32 v2, v0, 0xbc800000, v83
	v_fmamk_f32 v133, v0, 0xbc800000, v81
	v_fmamk_f32 v1, v0, 0xbc800000, v82
	v_fmamk_f32 v132, v0, 0xbc800000, v80
	v_mul_f32_e32 v133, v133, v133
	v_mul_f32_e32 v2, v2, v2
	v_fmac_f32_e32 v133, v132, v132
	v_fmac_f32_e32 v2, v1, v1
	v_fmamk_f32 v132, v0, 0xbc800000, v79
	v_fmamk_f32 v134, v0, 0xbc800000, v77
	v_add_f32_e32 v1, v133, v2
	v_fmamk_f32 v2, v0, 0xbc800000, v78
	v_fmamk_f32 v133, v0, 0xbc800000, v76
	v_mul_f32_e32 v134, v134, v134
	v_mul_f32_e32 v132, v132, v132
	v_fmac_f32_e32 v134, v133, v133
	v_fmac_f32_e32 v132, v2, v2
	v_add_f32_e32 v2, v134, v132
	v_fmamk_f32 v132, v0, 0xbc800000, v59
	v_fmamk_f32 v134, v0, 0xbc800000, v57
	v_add_f32_e32 v1, v1, v2
	v_fmamk_f32 v2, v0, 0xbc800000, v58
	v_fmamk_f32 v133, v0, 0xbc800000, v56
	v_mul_f32_e32 v134, v134, v134
	v_mul_f32_e32 v132, v132, v132
	v_fmac_f32_e32 v134, v133, v133
	v_fmac_f32_e32 v132, v2, v2
	v_add_f32_e32 v2, v134, v132
	v_fmamk_f32 v132, v0, 0xbc800000, v55
	v_fmamk_f32 v134, v0, 0xbc800000, v53
	v_add_f32_e32 v1, v2, v1
	v_fmamk_f32 v2, v0, 0xbc800000, v54
	v_fmamk_f32 v133, v0, 0xbc800000, v52
	v_mul_f32_e32 v134, v134, v134
	v_mul_f32_e32 v132, v132, v132
	v_fmac_f32_e32 v134, v133, v133
	v_fmac_f32_e32 v132, v2, v2
	v_add_f32_e32 v2, v134, v132
	v_add_f32_e32 v1, v2, v1
	v_mov_b32_e32 v2, v1
	s_nop 1
	v_permlane16_swap_b32 v1, v2
	s_waitcnt lgkmcnt(0)
	v_add_f32_e32 v1, v1, v2
	v_mov_b32_e32 v2, v1
	s_nop 1
	v_permlane32_swap_b32 v1, v2
	s_and_saveexec_b64 s[4:5], vcc
	s_cbranch_execz .LBB0_1168
	s_lshl_b32 s8, s0, 11
	s_add_i32 s8, s7, s8
	v_mul_f32_e32 v0, 0x3c800000, v0
	s_waitcnt lgkmcnt(0)
	v_add_f32_e32 v1, v1, v2
	v_lshl_add_u32 v2, v144, 5, s8
	ds_write_b64 v2, v[0:1] offset:5120
.LBB0_1168:
	s_or_b64 exec, exec, s[4:5]
	v_mov_b32_e32 v0, v73
	v_mov_b32_e32 v1, v74
	v_mov_b32_e32 v132, v72
	v_mov_b32_e32 v133, v75
	v_pk_add_f32 v[0:1], v[0:1], v[132:133]
	v_mov_b32_e32 v132, v61
	v_mov_b32_e32 v133, v62
	v_mov_b32_e32 v134, v60
	v_mov_b32_e32 v135, v63
	v_pk_add_f32 v[132:133], v[132:133], v[134:135]
	v_add_f32_e32 v0, v0, v1
	v_pk_add_f32 v[132:133], v[132:133], v[132:133] op_sel_hi:[0,1]
	v_add_f32_e32 v1, 0, v0
	v_add_f32_e32 v135, v48, v49
	v_add_f32_e32 v137, v50, v51
	v_mov_b32_e32 v134, v44
	v_mov_b32_e32 v136, v45
	v_mov_b32_e32 v132, v46
	v_mov_b32_e32 v0, v47
	v_pk_add_f32 v[134:135], v[134:135], v[136:137]
	v_pk_add_f32 v[0:1], v[132:133], v[0:1]
	s_nop 0
	v_pk_add_f32 v[0:1], v[134:135], v[0:1]
	s_nop 0
	v_add_f32_e32 v0, v0, v1
	v_mov_b32_e32 v1, v0
	s_nop 1
	v_permlane16_swap_b32 v0, v1
	s_waitcnt lgkmcnt(0)
	v_add_f32_e32 v0, v0, v1
	v_mov_b32_e32 v1, v0
	s_nop 1
	v_permlane32_swap_b32 v0, v1
	s_waitcnt lgkmcnt(0)
	v_add_f32_e32 v0, v0, v1
	v_fmamk_f32 v2, v0, 0xbc800000, v75
	v_fmamk_f32 v133, v0, 0xbc800000, v73
	v_fmamk_f32 v1, v0, 0xbc800000, v74
	v_fmamk_f32 v132, v0, 0xbc800000, v72
	v_mul_f32_e32 v133, v133, v133
	v_mul_f32_e32 v2, v2, v2
	v_fmac_f32_e32 v133, v132, v132
	v_fmac_f32_e32 v2, v1, v1
	v_fmamk_f32 v132, v0, 0xbc800000, v63
	v_fmamk_f32 v134, v0, 0xbc800000, v61
	v_add_f32_e32 v1, v133, v2
	v_fmamk_f32 v2, v0, 0xbc800000, v62
	v_fmamk_f32 v133, v0, 0xbc800000, v60
	v_mul_f32_e32 v134, v134, v134
	v_mul_f32_e32 v132, v132, v132
	v_fmac_f32_e32 v134, v133, v133
	v_fmac_f32_e32 v132, v2, v2
	v_add_f32_e32 v2, v134, v132
	v_fmamk_f32 v132, v0, 0xbc800000, v51
	v_fmamk_f32 v134, v0, 0xbc800000, v49
	v_add_f32_e32 v1, v1, v2
	v_fmamk_f32 v2, v0, 0xbc800000, v50
	v_fmamk_f32 v133, v0, 0xbc800000, v48
	v_mul_f32_e32 v134, v134, v134
	v_mul_f32_e32 v132, v132, v132
	v_fmac_f32_e32 v134, v133, v133
	v_fmac_f32_e32 v132, v2, v2
	v_add_f32_e32 v2, v134, v132
	v_fmamk_f32 v132, v0, 0xbc800000, v47
	v_fmamk_f32 v134, v0, 0xbc800000, v45
	v_add_f32_e32 v1, v2, v1
	v_fmamk_f32 v2, v0, 0xbc800000, v46
	v_fmamk_f32 v133, v0, 0xbc800000, v44
	v_mul_f32_e32 v134, v134, v134
	v_mul_f32_e32 v132, v132, v132
	v_fmac_f32_e32 v134, v133, v133
	v_fmac_f32_e32 v132, v2, v2
	v_add_f32_e32 v2, v134, v132
	v_add_f32_e32 v1, v2, v1
	v_mov_b32_e32 v2, v1
	s_nop 1
	v_permlane16_swap_b32 v1, v2
	s_waitcnt lgkmcnt(0)
	v_add_f32_e32 v1, v1, v2
	v_mov_b32_e32 v2, v1
	s_nop 1
	v_permlane32_swap_b32 v1, v2
	s_and_saveexec_b64 s[4:5], vcc
	s_cbranch_execz .LBB0_1170
	s_lshl_b32 s8, s0, 11
	s_add_i32 s7, s7, s8
	v_mul_f32_e32 v0, 0x3c800000, v0
	s_waitcnt lgkmcnt(0)
	v_add_f32_e32 v1, v1, v2
	v_lshl_add_u32 v2, v144, 5, s7
	ds_write_b64 v2, v[0:1] offset:5632

.LBB0_1210:
	s_lshl_b32 s4, s8, 5
	s_lshl_b32 s5, s44, 8
	s_or_b32 s4, s5, s4
	v_lshrrev_b32_e32 v0, 2, v145
	s_lshl_b32 s6, s1, 8
	v_and_or_b32 v140, v0, 12, s4
	s_add_i32 s4, s6, s14
	v_or_b32_e32 v0, s4, v144
	v_lshl_add_u32 v2, v0, 10, v140
	v_lshl_add_u64 v[0:1], v[2:3], 1, s[64:65]
	s_waitcnt vmcnt(0)
	s_barrier
	global_load_dwordx2 v[132:133], v[0:1], off
	global_load_dwordx2 v[136:137], v[0:1], off offset:32
	global_load_dwordx2 v[146:147], v[0:1], off offset:256
	global_load_dwordx2 v[150:151], v[0:1], off offset:288
	v_add_u32_e32 v0, 0x4000, v2
	v_mov_b32_e32 v1, v3
	v_lshl_add_u64 v[0:1], v[0:1], 1, s[64:65]
	global_load_dwordx2 v[186:187], v[0:1], off
	global_load_dwordx2 v[190:191], v[0:1], off offset:32
	global_load_dwordx2 v[194:195], v[0:1], off offset:256
	global_load_dwordx2 v[198:199], v[0:1], off offset:288
	v_mov_b32_e32 v134, v3
	v_mov_b32_e32 v135, v3
	v_mov_b32_e32 v138, v3
	v_mov_b32_e32 v139, v3
	v_mov_b32_e32 v148, v3
	v_mov_b32_e32 v149, v3
	v_mov_b32_e32 v152, v3
	v_mov_b32_e32 v153, v3
	v_mov_b32_e32 v188, v3
	v_mov_b32_e32 v189, v3
	v_mov_b32_e32 v192, v3
	v_mov_b32_e32 v193, v3
	v_mov_b32_e32 v196, v3
	v_mov_b32_e32 v197, v3
	v_mov_b32_e32 v200, v3
	v_mov_b32_e32 v201, v3
	s_mov_b32 s4, 0x3fd744fd
	v_and_b32_e32 v141, 63, v145
	v_cmp_gt_u32_e32 vcc, 16, v141
	v_add_u32_e32 v0, 0x8000, v2
	v_mov_b32_e32 v1, v3
	v_lshl_add_u64 v[0:1], v[0:1], 1, s[64:65]
	global_load_dwordx2 v[202:203], v[0:1], off
	global_load_dwordx2 v[204:205], v[0:1], off offset:32
	global_load_dwordx2 v[206:207], v[0:1], off offset:256
	global_load_dwordx2 v[208:209], v[0:1], off offset:288
	v_add_u32_e32 v0, 0xc000, v2
	v_mov_b32_e32 v1, v3
	v_lshl_add_u64 v[0:1], v[0:1], 1, s[64:65]
	global_load_dwordx2 v[210:211], v[0:1], off
	global_load_dwordx2 v[212:213], v[0:1], off offset:32
	global_load_dwordx2 v[214:215], v[0:1], off offset:256
	global_load_dwordx2 v[216:217], v[0:1], off offset:288
	v_add_u32_e32 v0, 0x20000, v2
	v_mov_b32_e32 v1, v3
	v_lshl_add_u64 v[0:1], v[0:1], 1, s[64:65]
	global_load_dwordx2 v[220:221], v[0:1], off
	global_load_dwordx2 v[222:223], v[0:1], off offset:32
	global_load_dwordx2 v[224:225], v[0:1], off offset:256
	global_load_dwordx2 v[218:219], v[0:1], off offset:288
	v_add_u32_e32 v0, 0x24000, v2
	v_mov_b32_e32 v1, v3
	v_lshl_add_u64 v[0:1], v[0:1], 1, s[64:65]
	global_load_dwordx2 v[226:227], v[0:1], off
	global_load_dwordx2 v[228:229], v[0:1], off offset:32
	global_load_dwordx2 v[230:231], v[0:1], off offset:256
	global_load_dwordx2 v[232:233], v[0:1], off offset:288
	s_waitcnt vmcnt(16)
	s_nop 0
	v_cvt_f32_f16_e32 v0, v132
	v_cvt_f32_f16_sdwa v1, v132 dst_sel:DWORD dst_unused:UNUSED_PAD src0_sel:WORD_1
	v_cvt_f32_f16_e32 v132, v133
	v_cvt_f32_f16_sdwa v133, v133 dst_sel:DWORD dst_unused:UNUSED_PAD src0_sel:WORD_1
	v_mov_b32_e32 v134, v3
	v_pk_fma_f32 v[36:37], v[0:1], s[4:5], v[36:37] op_sel_hi:[1,0,1]
	v_cvt_f32_f16_e32 v0, v136
	v_pk_fma_f32 v[38:39], v[132:133], s[4:5], v[38:39] op_sel_hi:[1,0,1]
	v_cvt_f32_f16_sdwa v1, v136 dst_sel:DWORD dst_unused:UNUSED_PAD src0_sel:WORD_1
	v_cvt_f32_f16_e32 v132, v137
	v_cvt_f32_f16_sdwa v133, v137 dst_sel:DWORD dst_unused:UNUSED_PAD src0_sel:WORD_1
	v_mov_b32_e32 v135, v3
	v_pk_fma_f32 v[24:25], v[0:1], s[4:5], v[24:25] op_sel_hi:[1,0,1]
	v_cvt_f32_f16_e32 v0, v146
	v_pk_fma_f32 v[26:27], v[132:133], s[4:5], v[26:27] op_sel_hi:[1,0,1]
	v_cvt_f32_f16_sdwa v1, v146 dst_sel:DWORD dst_unused:UNUSED_PAD src0_sel:WORD_1
	v_cvt_f32_f16_e32 v132, v147
	v_cvt_f32_f16_sdwa v133, v147 dst_sel:DWORD dst_unused:UNUSED_PAD src0_sel:WORD_1
	v_mov_b32_e32 v138, v3
	v_pk_fma_f32 v[16:17], v[0:1], s[4:5], v[16:17] op_sel_hi:[1,0,1]
	v_cvt_f32_f16_e32 v0, v150
	v_pk_fma_f32 v[18:19], v[132:133], s[4:5], v[18:19] op_sel_hi:[1,0,1]
	v_cvt_f32_f16_sdwa v1, v150 dst_sel:DWORD dst_unused:UNUSED_PAD src0_sel:WORD_1
	v_cvt_f32_f16_e32 v132, v151
	v_cvt_f32_f16_sdwa v133, v151 dst_sel:DWORD dst_unused:UNUSED_PAD src0_sel:WORD_1
	v_mov_b32_e32 v139, v3
	v_pk_fma_f32 v[8:9], v[0:1], s[4:5], v[8:9] op_sel_hi:[1,0,1]
	v_cvt_f32_f16_e32 v0, v186
	v_pk_fma_f32 v[10:11], v[132:133], s[4:5], v[10:11] op_sel_hi:[1,0,1]
	v_cvt_f32_f16_sdwa v1, v186 dst_sel:DWORD dst_unused:UNUSED_PAD src0_sel:WORD_1
	v_cvt_f32_f16_e32 v132, v187
	v_cvt_f32_f16_sdwa v133, v187 dst_sel:DWORD dst_unused:UNUSED_PAD src0_sel:WORD_1
	v_pk_fma_f32 v[40:41], v[0:1], s[4:5], v[40:41] op_sel_hi:[1,0,1]
	v_cvt_f32_f16_e32 v0, v190
	v_pk_fma_f32 v[42:43], v[132:133], s[4:5], v[42:43] op_sel_hi:[1,0,1]
	v_cvt_f32_f16_sdwa v1, v190 dst_sel:DWORD dst_unused:UNUSED_PAD src0_sel:WORD_1
	v_cvt_f32_f16_e32 v132, v191
	v_cvt_f32_f16_sdwa v133, v191 dst_sel:DWORD dst_unused:UNUSED_PAD src0_sel:WORD_1
	v_mov_b32_e32 v148, v3
	v_pk_fma_f32 v[20:21], v[0:1], s[4:5], v[20:21] op_sel_hi:[1,0,1]
	v_cvt_f32_f16_e32 v0, v194
	v_pk_fma_f32 v[22:23], v[132:133], s[4:5], v[22:23] op_sel_hi:[1,0,1]
	v_cvt_f32_f16_sdwa v1, v194 dst_sel:DWORD dst_unused:UNUSED_PAD src0_sel:WORD_1
	v_cvt_f32_f16_e32 v132, v195
	v_cvt_f32_f16_sdwa v133, v195 dst_sel:DWORD dst_unused:UNUSED_PAD src0_sel:WORD_1
	v_mov_b32_e32 v149, v3
	v_pk_fma_f32 v[12:13], v[0:1], s[4:5], v[12:13] op_sel_hi:[1,0,1]
	v_cvt_f32_f16_e32 v0, v198
	v_pk_fma_f32 v[14:15], v[132:133], s[4:5], v[14:15] op_sel_hi:[1,0,1]
	v_cvt_f32_f16_sdwa v1, v198 dst_sel:DWORD dst_unused:UNUSED_PAD src0_sel:WORD_1
	v_cvt_f32_f16_e32 v132, v199
	v_cvt_f32_f16_sdwa v133, v199 dst_sel:DWORD dst_unused:UNUSED_PAD src0_sel:WORD_1
	v_mov_b32_e32 v152, v3
	v_pk_fma_f32 v[4:5], v[0:1], s[4:5], v[4:5] op_sel_hi:[1,0,1]
	v_pk_fma_f32 v[6:7], v[132:133], s[4:5], v[6:7] op_sel_hi:[1,0,1]
	v_mov_b32_e32 v153, v3
	v_mov_b32_e32 v188, v3
	v_mov_b32_e32 v189, v3
	v_mov_b32_e32 v192, v3
	v_mov_b32_e32 v193, v3
	v_mov_b32_e32 v196, v3
	v_mov_b32_e32 v197, v3
	v_mov_b32_e32 v200, v3
	v_mov_b32_e32 v201, v3
	s_waitcnt vmcnt(8)
	s_nop 0
	v_cvt_f32_f16_e32 v0, v202
	v_cvt_f32_f16_sdwa v1, v202 dst_sel:DWORD dst_unused:UNUSED_PAD src0_sel:WORD_1
	v_cvt_f32_f16_e32 v202, v203
	v_cvt_f32_f16_sdwa v203, v203 dst_sel:DWORD dst_unused:UNUSED_PAD src0_sel:WORD_1
	v_mov_b32_e32 v138, v3
	v_pk_fma_f32 v[100:101], v[0:1], s[4:5], v[100:101] op_sel_hi:[1,0,1]
	v_cvt_f32_f16_e32 v0, v204
	v_pk_fma_f32 v[102:103], v[202:203], s[4:5], v[102:103] op_sel_hi:[1,0,1]
	v_cvt_f32_f16_sdwa v1, v204 dst_sel:DWORD dst_unused:UNUSED_PAD src0_sel:WORD_1
	v_cvt_f32_f16_e32 v202, v205
	v_cvt_f32_f16_sdwa v203, v205 dst_sel:DWORD dst_unused:UNUSED_PAD src0_sel:WORD_1
	v_mov_b32_e32 v139, v3
	v_pk_fma_f32 v[88:89], v[0:1], s[4:5], v[88:89] op_sel_hi:[1,0,1]
	v_cvt_f32_f16_e32 v0, v206
	v_pk_fma_f32 v[90:91], v[202:203], s[4:5], v[90:91] op_sel_hi:[1,0,1]
	v_cvt_f32_f16_sdwa v1, v206 dst_sel:DWORD dst_unused:UNUSED_PAD src0_sel:WORD_1
	v_cvt_f32_f16_e32 v202, v207
	v_cvt_f32_f16_sdwa v203, v207 dst_sel:DWORD dst_unused:UNUSED_PAD src0_sel:WORD_1
	v_mov_b32_e32 v148, v3
	v_pk_fma_f32 v[52:53], v[0:1], s[4:5], v[52:53] op_sel_hi:[1,0,1]
	v_cvt_f32_f16_e32 v0, v208
	v_pk_fma_f32 v[54:55], v[202:203], s[4:5], v[54:55] op_sel_hi:[1,0,1]
	v_cvt_f32_f16_sdwa v1, v208 dst_sel:DWORD dst_unused:UNUSED_PAD src0_sel:WORD_1
	v_cvt_f32_f16_e32 v202, v209
	v_cvt_f32_f16_sdwa v203, v209 dst_sel:DWORD dst_unused:UNUSED_PAD src0_sel:WORD_1
	v_mov_b32_e32 v149, v3
	v_pk_fma_f32 v[32:33], v[0:1], s[4:5], v[32:33] op_sel_hi:[1,0,1]
	v_cvt_f32_f16_e32 v0, v210
	v_pk_fma_f32 v[34:35], v[202:203], s[4:5], v[34:35] op_sel_hi:[1,0,1]
	v_cvt_f32_f16_sdwa v1, v210 dst_sel:DWORD dst_unused:UNUSED_PAD src0_sel:WORD_1
	v_cvt_f32_f16_e32 v202, v211
	v_cvt_f32_f16_sdwa v203, v211 dst_sel:DWORD dst_unused:UNUSED_PAD src0_sel:WORD_1
	v_pk_fma_f32 v[104:105], v[0:1], s[4:5], v[104:105] op_sel_hi:[1,0,1]
	v_cvt_f32_f16_e32 v0, v212
	v_pk_fma_f32 v[106:107], v[202:203], s[4:5], v[106:107] op_sel_hi:[1,0,1]
	v_cvt_f32_f16_sdwa v1, v212 dst_sel:DWORD dst_unused:UNUSED_PAD src0_sel:WORD_1
	v_cvt_f32_f16_e32 v202, v213
	v_cvt_f32_f16_sdwa v203, v213 dst_sel:DWORD dst_unused:UNUSED_PAD src0_sel:WORD_1
	v_mov_b32_e32 v152, v3
	v_pk_fma_f32 v[84:85], v[0:1], s[4:5], v[84:85] op_sel_hi:[1,0,1]
	v_cvt_f32_f16_e32 v0, v214
	v_pk_fma_f32 v[86:87], v[202:203], s[4:5], v[86:87] op_sel_hi:[1,0,1]
	v_cvt_f32_f16_sdwa v1, v214 dst_sel:DWORD dst_unused:UNUSED_PAD src0_sel:WORD_1
	v_cvt_f32_f16_e32 v202, v215
	v_cvt_f32_f16_sdwa v203, v215 dst_sel:DWORD dst_unused:UNUSED_PAD src0_sel:WORD_1
	v_mov_b32_e32 v153, v3
	v_pk_fma_f32 v[48:49], v[0:1], s[4:5], v[48:49] op_sel_hi:[1,0,1]
	v_cvt_f32_f16_e32 v0, v216
	v_pk_fma_f32 v[50:51], v[202:203], s[4:5], v[50:51] op_sel_hi:[1,0,1]
	v_cvt_f32_f16_sdwa v1, v216 dst_sel:DWORD dst_unused:UNUSED_PAD src0_sel:WORD_1
	v_cvt_f32_f16_e32 v202, v217
	v_cvt_f32_f16_sdwa v203, v217 dst_sel:DWORD dst_unused:UNUSED_PAD src0_sel:WORD_1
	v_mov_b32_e32 v134, v3
	v_pk_fma_f32 v[28:29], v[0:1], s[4:5], v[28:29] op_sel_hi:[1,0,1]
	v_pk_fma_f32 v[30:31], v[202:203], s[4:5], v[30:31] op_sel_hi:[1,0,1]
	v_mov_b32_e32 v135, v3
	v_mov_b32_e32 v188, v3
	v_mov_b32_e32 v189, v3
	v_mov_b32_e32 v192, v3
	v_mov_b32_e32 v193, v3
	v_mov_b32_e32 v196, v3
	v_mov_b32_e32 v197, v3
	v_mov_b32_e32 v200, v3
	v_mov_b32_e32 v201, v3
	s_waitcnt vmcnt(0)
	s_nop 0
	v_cvt_f32_f16_e32 v0, v220
	v_cvt_f32_f16_sdwa v1, v220 dst_sel:DWORD dst_unused:UNUSED_PAD src0_sel:WORD_1
	v_cvt_f32_f16_e32 v134, v221
	v_cvt_f32_f16_sdwa v135, v221 dst_sel:DWORD dst_unused:UNUSED_PAD src0_sel:WORD_1
	v_mov_b32_e32 v148, v3
	v_pk_fma_f32 v[128:129], v[0:1], s[4:5], v[128:129] op_sel_hi:[1,0,1]
	v_cvt_f32_f16_e32 v0, v222
	v_cvt_f32_f16_sdwa v1, v222 dst_sel:DWORD dst_unused:UNUSED_PAD src0_sel:WORD_1
	v_pk_fma_f32 v[130:131], v[134:135], s[4:5], v[130:131] op_sel_hi:[1,0,1]
	v_cvt_f32_f16_e32 v134, v223
	v_cvt_f32_f16_sdwa v135, v223 dst_sel:DWORD dst_unused:UNUSED_PAD src0_sel:WORD_1
	v_pk_fma_f32 v[124:125], v[0:1], s[4:5], v[124:125] op_sel_hi:[1,0,1]
	v_cvt_f32_f16_e32 v0, v224
	v_cvt_f32_f16_sdwa v1, v224 dst_sel:DWORD dst_unused:UNUSED_PAD src0_sel:WORD_1
	v_pk_fma_f32 v[126:127], v[134:135], s[4:5], v[126:127] op_sel_hi:[1,0,1]
	v_cvt_f32_f16_e32 v134, v225
	v_cvt_f32_f16_sdwa v135, v225 dst_sel:DWORD dst_unused:UNUSED_PAD src0_sel:WORD_1
	v_pk_fma_f32 v[112:113], v[0:1], s[4:5], v[112:113] op_sel_hi:[1,0,1]
	v_cvt_f32_f16_e32 v0, v218
	v_cvt_f32_f16_sdwa v1, v218 dst_sel:DWORD dst_unused:UNUSED_PAD src0_sel:WORD_1
	v_cvt_f32_f16_e32 v218, v219
	v_cvt_f32_f16_sdwa v219, v219 dst_sel:DWORD dst_unused:UNUSED_PAD src0_sel:WORD_1
	v_pk_fma_f32 v[114:115], v[134:135], s[4:5], v[114:115] op_sel_hi:[1,0,1]
	v_pk_fma_f32 v[96:97], v[0:1], s[4:5], v[96:97] op_sel_hi:[1,0,1]
	v_cvt_f32_f16_e32 v0, v226
	v_pk_fma_f32 v[98:99], v[218:219], s[4:5], v[98:99] op_sel_hi:[1,0,1]
	v_cvt_f32_f16_sdwa v1, v226 dst_sel:DWORD dst_unused:UNUSED_PAD src0_sel:WORD_1
	v_cvt_f32_f16_e32 v218, v227
	v_cvt_f32_f16_sdwa v219, v227 dst_sel:DWORD dst_unused:UNUSED_PAD src0_sel:WORD_1
	v_pk_fma_f32 v[120:121], v[0:1], s[4:5], v[120:121] op_sel_hi:[1,0,1]
	v_cvt_f32_f16_e32 v0, v228
	v_pk_fma_f32 v[122:123], v[218:219], s[4:5], v[122:123] op_sel_hi:[1,0,1]
	v_cvt_f32_f16_sdwa v1, v228 dst_sel:DWORD dst_unused:UNUSED_PAD src0_sel:WORD_1
	v_cvt_f32_f16_e32 v218, v229
	v_cvt_f32_f16_sdwa v219, v229 dst_sel:DWORD dst_unused:UNUSED_PAD src0_sel:WORD_1
	v_mov_b32_e32 v149, v3
	v_pk_fma_f32 v[116:117], v[0:1], s[4:5], v[116:117] op_sel_hi:[1,0,1]
	v_cvt_f32_f16_e32 v0, v230
	v_pk_fma_f32 v[118:119], v[218:219], s[4:5], v[118:119] op_sel_hi:[1,0,1]
	v_cvt_f32_f16_sdwa v1, v230 dst_sel:DWORD dst_unused:UNUSED_PAD src0_sel:WORD_1
	v_cvt_f32_f16_e32 v218, v231
	v_cvt_f32_f16_sdwa v219, v231 dst_sel:DWORD dst_unused:UNUSED_PAD src0_sel:WORD_1
	v_mov_b32_e32 v138, v3
	v_pk_fma_f32 v[108:109], v[0:1], s[4:5], v[108:109] op_sel_hi:[1,0,1]
	v_cvt_f32_f16_e32 v0, v232
	v_pk_fma_f32 v[110:111], v[218:219], s[4:5], v[110:111] op_sel_hi:[1,0,1]
	v_cvt_f32_f16_sdwa v1, v232 dst_sel:DWORD dst_unused:UNUSED_PAD src0_sel:WORD_1
	v_cvt_f32_f16_e32 v218, v233
	v_cvt_f32_f16_sdwa v219, v233 dst_sel:DWORD dst_unused:UNUSED_PAD src0_sel:WORD_1
	v_mov_b32_e32 v139, v3
	v_pk_fma_f32 v[92:93], v[0:1], s[4:5], v[92:93] op_sel_hi:[1,0,1]
	v_add_u32_e32 v0, 0x28000, v2
	v_pk_fma_f32 v[94:95], v[218:219], s[4:5], v[94:95] op_sel_hi:[1,0,1]
	v_mov_b32_e32 v1, v3
	v_add_u32_e32 v2, 0x2c000, v2
	v_lshl_add_u64 v[132:133], v[0:1], 1, s[64:65]
	v_lshl_add_u64 v[134:135], v[2:3], 1, s[64:65]
	global_load_dwordx2 v[0:1], v[132:133], off
	global_load_dwordx2 v[146:147], v[132:133], off offset:32
	global_load_dwordx2 v[136:137], v[132:133], off offset:256
	s_nop 0
	global_load_dwordx2 v[132:133], v[132:133], off offset:288
	s_nop 0
	global_load_dwordx2 v[150:151], v[134:135], off
	global_load_dwordx2 v[186:187], v[134:135], off offset:32
	global_load_dwordx2 v[190:191], v[134:135], off offset:256
	global_load_dwordx2 v[194:195], v[134:135], off offset:288
	v_mov_b32_e32 v2, v3
	v_mov_b32_e32 v134, v3
	v_mov_b32_e32 v135, v3
	v_mov_b32_e32 v152, v3
	v_mov_b32_e32 v153, v3
	v_mov_b32_e32 v188, v3
	v_mov_b32_e32 v189, v3
	v_mov_b32_e32 v192, v3
	v_mov_b32_e32 v193, v3
	v_mov_b32_e32 v196, v3
	v_mov_b32_e32 v197, v3
	s_waitcnt vmcnt(7)
	v_mov_b64_e32 v[200:201], v[2:3]
	v_mov_b64_e32 v[198:199], v[0:1]
	s_waitcnt vmcnt(0)
	s_nop 0
	v_cvt_f32_f16_e32 v0, v198
	v_cvt_f32_f16_sdwa v1, v198 dst_sel:DWORD dst_unused:UNUSED_PAD src0_sel:WORD_1
	v_cvt_f32_f16_e32 v134, v199
	v_cvt_f32_f16_sdwa v135, v199 dst_sel:DWORD dst_unused:UNUSED_PAD src0_sel:WORD_1
	v_pk_fma_f32 v[80:81], v[0:1], s[4:5], v[80:81] op_sel_hi:[1,0,1]
	v_cvt_f32_f16_e32 v0, v146
	v_cvt_f32_f16_sdwa v1, v146 dst_sel:DWORD dst_unused:UNUSED_PAD src0_sel:WORD_1
	v_pk_fma_f32 v[82:83], v[134:135], s[4:5], v[82:83] op_sel_hi:[1,0,1]
	v_cvt_f32_f16_e32 v134, v147
	v_cvt_f32_f16_sdwa v135, v147 dst_sel:DWORD dst_unused:UNUSED_PAD src0_sel:WORD_1
	v_pk_fma_f32 v[76:77], v[0:1], s[4:5], v[76:77] op_sel_hi:[1,0,1]
	v_cvt_f32_f16_e32 v0, v136
	v_cvt_f32_f16_sdwa v1, v136 dst_sel:DWORD dst_unused:UNUSED_PAD src0_sel:WORD_1
	v_pk_fma_f32 v[78:79], v[134:135], s[4:5], v[78:79] op_sel_hi:[1,0,1]
	v_cvt_f32_f16_e32 v134, v137
	v_cvt_f32_f16_sdwa v135, v137 dst_sel:DWORD dst_unused:UNUSED_PAD src0_sel:WORD_1
	v_pk_fma_f32 v[64:65], v[0:1], s[4:5], v[64:65] op_sel_hi:[1,0,1]
	v_cvt_f32_f16_e32 v0, v132
	v_cvt_f32_f16_sdwa v1, v132 dst_sel:DWORD dst_unused:UNUSED_PAD src0_sel:WORD_1
	v_cvt_f32_f16_e32 v132, v133
	v_cvt_f32_f16_sdwa v133, v133 dst_sel:DWORD dst_unused:UNUSED_PAD src0_sel:WORD_1
	v_pk_fma_f32 v[66:67], v[134:135], s[4:5], v[66:67] op_sel_hi:[1,0,1]
	v_pk_fma_f32 v[60:61], v[0:1], s[4:5], v[60:61] op_sel_hi:[1,0,1]
	v_cvt_f32_f16_e32 v0, v150
	v_pk_fma_f32 v[62:63], v[132:133], s[4:5], v[62:63] op_sel_hi:[1,0,1]
	v_cvt_f32_f16_sdwa v1, v150 dst_sel:DWORD dst_unused:UNUSED_PAD src0_sel:WORD_1
	v_cvt_f32_f16_e32 v132, v151
	v_cvt_f32_f16_sdwa v133, v151 dst_sel:DWORD dst_unused:UNUSED_PAD src0_sel:WORD_1
	v_mov_b32_e32 v134, v24
	v_pk_fma_f32 v[72:73], v[0:1], s[4:5], v[72:73] op_sel_hi:[1,0,1]
	v_cvt_f32_f16_e32 v0, v186
	v_pk_fma_f32 v[74:75], v[132:133], s[4:5], v[74:75] op_sel_hi:[1,0,1]
	v_cvt_f32_f16_sdwa v1, v186 dst_sel:DWORD dst_unused:UNUSED_PAD src0_sel:WORD_1
	v_cvt_f32_f16_e32 v132, v187
	v_cvt_f32_f16_sdwa v133, v187 dst_sel:DWORD dst_unused:UNUSED_PAD src0_sel:WORD_1
	v_mov_b32_e32 v135, v27
	v_pk_fma_f32 v[68:69], v[0:1], s[4:5], v[68:69] op_sel_hi:[1,0,1]
	v_cvt_f32_f16_e32 v0, v190
	v_pk_fma_f32 v[70:71], v[132:133], s[4:5], v[70:71] op_sel_hi:[1,0,1]
	v_cvt_f32_f16_sdwa v1, v190 dst_sel:DWORD dst_unused:UNUSED_PAD src0_sel:WORD_1
	v_cvt_f32_f16_e32 v132, v191
	v_cvt_f32_f16_sdwa v133, v191 dst_sel:DWORD dst_unused:UNUSED_PAD src0_sel:WORD_1
	v_add_f32_e32 v137, v18, v19
	v_pk_fma_f32 v[56:57], v[0:1], s[4:5], v[56:57] op_sel_hi:[1,0,1]
	v_cvt_f32_f16_e32 v0, v194
	v_pk_fma_f32 v[58:59], v[132:133], s[4:5], v[58:59] op_sel_hi:[1,0,1]
	v_cvt_f32_f16_sdwa v1, v194 dst_sel:DWORD dst_unused:UNUSED_PAD src0_sel:WORD_1
	v_cvt_f32_f16_e32 v132, v195
	v_cvt_f32_f16_sdwa v133, v195 dst_sel:DWORD dst_unused:UNUSED_PAD src0_sel:WORD_1
	v_mov_b32_e32 v136, v9
	v_pk_fma_f32 v[44:45], v[0:1], s[4:5], v[44:45] op_sel_hi:[1,0,1]
	v_mov_b32_e32 v0, v37
	v_pk_fma_f32 v[46:47], v[132:133], s[4:5], v[46:47] op_sel_hi:[1,0,1]
	v_mov_b32_e32 v1, v38
	v_mov_b32_e32 v132, v36
	v_mov_b32_e32 v133, v39
	v_pk_add_f32 v[0:1], v[0:1], v[132:133]
	v_mov_b32_e32 v132, v25
	v_mov_b32_e32 v133, v26
	v_pk_add_f32 v[132:133], v[132:133], v[134:135]
	v_add_f32_e32 v0, v0, v1
	v_pk_add_f32 v[132:133], v[132:133], v[132:133] op_sel_hi:[0,1]
	v_add_f32_e32 v1, 0, v0
	v_add_f32_e32 v135, v16, v17
	v_mov_b32_e32 v134, v8
	v_mov_b32_e32 v132, v10
	v_mov_b32_e32 v0, v11
	v_pk_add_f32 v[134:135], v[134:135], v[136:137]
	v_pk_add_f32 v[0:1], v[132:133], v[0:1]
	s_lshl_b32 s4, s8, 3
	v_pk_add_f32 v[0:1], v[134:135], v[0:1]
	s_add_i32 s7, s4, 0
	v_add_f32_e32 v0, v0, v1
	v_mov_b32_e32 v1, v0
	s_nop 1
	v_permlane16_swap_b32 v0, v1
	s_waitcnt lgkmcnt(0)
	v_add_f32_e32 v0, v0, v1
	v_mov_b32_e32 v1, v0
	s_nop 1
	v_permlane32_swap_b32 v0, v1
	s_waitcnt lgkmcnt(0)
	v_add_f32_e32 v0, v0, v1
	v_fmamk_f32 v2, v0, 0xbc800000, v39
	v_fmamk_f32 v133, v0, 0xbc800000, v37
	v_fmamk_f32 v1, v0, 0xbc800000, v38
	v_fmamk_f32 v132, v0, 0xbc800000, v36
	v_mul_f32_e32 v133, v133, v133
	v_mul_f32_e32 v2, v2, v2
	v_fmac_f32_e32 v133, v132, v132
	v_fmac_f32_e32 v2, v1, v1
	v_fmamk_f32 v132, v0, 0xbc800000, v27
	v_fmamk_f32 v134, v0, 0xbc800000, v25
	v_add_f32_e32 v1, v133, v2
	v_fmamk_f32 v2, v0, 0xbc800000, v26
	v_fmamk_f32 v133, v0, 0xbc800000, v24
	v_mul_f32_e32 v134, v134, v134
	v_mul_f32_e32 v132, v132, v132
	v_fmac_f32_e32 v134, v133, v133
	v_fmac_f32_e32 v132, v2, v2
	v_add_f32_e32 v2, v134, v132
	v_fmamk_f32 v132, v0, 0xbc800000, v19
	v_fmamk_f32 v134, v0, 0xbc800000, v17
	v_add_f32_e32 v1, v1, v2
	v_fmamk_f32 v2, v0, 0xbc800000, v18
	v_fmamk_f32 v133, v0, 0xbc800000, v16
	v_mul_f32_e32 v134, v134, v134
	v_mul_f32_e32 v132, v132, v132
	v_fmac_f32_e32 v134, v133, v133
	v_fmac_f32_e32 v132, v2, v2
	v_add_f32_e32 v2, v134, v132
	v_fmamk_f32 v132, v0, 0xbc800000, v11
	v_fmamk_f32 v134, v0, 0xbc800000, v9
	v_add_f32_e32 v1, v2, v1
	v_fmamk_f32 v2, v0, 0xbc800000, v10
	v_fmamk_f32 v133, v0, 0xbc800000, v8
	v_mul_f32_e32 v134, v134, v134
	v_mul_f32_e32 v132, v132, v132
	v_fmac_f32_e32 v134, v133, v133
	v_fmac_f32_e32 v132, v2, v2
	v_add_f32_e32 v2, v134, v132
	v_add_f32_e32 v1, v2, v1
	v_mov_b32_e32 v2, v1
	s_nop 1
	v_permlane16_swap_b32 v1, v2
	s_waitcnt lgkmcnt(0)
	v_add_f32_e32 v1, v1, v2
	v_mov_b32_e32 v2, v1
	s_nop 1
	v_permlane32_swap_b32 v1, v2
	s_and_saveexec_b64 s[4:5], vcc
	s_cbranch_execz .LBB0_1212
	s_lshl_b32 s8, s0, 11
	s_add_i32 s8, s7, s8
	v_mul_f32_e32 v0, 0x3c800000, v0
	s_waitcnt lgkmcnt(0)
	v_add_f32_e32 v1, v1, v2
	v_lshl_add_u32 v2, v144, 5, s8
	ds_write_b64 v2, v[0:1]
.LBB0_1212:
	s_or_b64 exec, exec, s[4:5]
	v_mov_b32_e32 v0, v41
	v_mov_b32_e32 v1, v42
	v_mov_b32_e32 v132, v40
	v_mov_b32_e32 v133, v43
	v_pk_add_f32 v[0:1], v[0:1], v[132:133]
	v_mov_b32_e32 v132, v21
	v_mov_b32_e32 v133, v22
	v_mov_b32_e32 v134, v20
	v_mov_b32_e32 v135, v23
	v_pk_add_f32 v[132:133], v[132:133], v[134:135]
	v_add_f32_e32 v0, v0, v1
	v_pk_add_f32 v[132:133], v[132:133], v[132:133] op_sel_hi:[0,1]
	v_add_f32_e32 v1, 0, v0
	v_add_f32_e32 v135, v12, v13
	v_add_f32_e32 v137, v14, v15
	v_mov_b32_e32 v134, v4
	v_mov_b32_e32 v136, v5
	v_mov_b32_e32 v132, v6
	v_mov_b32_e32 v0, v7
	v_pk_add_f32 v[134:135], v[134:135], v[136:137]
	v_pk_add_f32 v[0:1], v[132:133], v[0:1]
	s_nop 0
	v_pk_add_f32 v[0:1], v[134:135], v[0:1]
	s_nop 0
	v_add_f32_e32 v0, v0, v1
	v_mov_b32_e32 v1, v0
	s_nop 1
	v_permlane16_swap_b32 v0, v1
	s_waitcnt lgkmcnt(0)
	v_add_f32_e32 v0, v0, v1
	v_mov_b32_e32 v1, v0
	s_nop 1
	v_permlane32_swap_b32 v0, v1
	s_waitcnt lgkmcnt(0)
	v_add_f32_e32 v0, v0, v1
	v_fmamk_f32 v2, v0, 0xbc800000, v43
	v_fmamk_f32 v133, v0, 0xbc800000, v41
	v_fmamk_f32 v1, v0, 0xbc800000, v42
	v_fmamk_f32 v132, v0, 0xbc800000, v40
	v_mul_f32_e32 v133, v133, v133
	v_mul_f32_e32 v2, v2, v2
	v_fmac_f32_e32 v133, v132, v132
	v_fmac_f32_e32 v2, v1, v1
	v_fmamk_f32 v132, v0, 0xbc800000, v23
	v_fmamk_f32 v134, v0, 0xbc800000, v21
	v_add_f32_e32 v1, v133, v2
	v_fmamk_f32 v2, v0, 0xbc800000, v22
	v_fmamk_f32 v133, v0, 0xbc800000, v20
	v_mul_f32_e32 v134, v134, v134
	v_mul_f32_e32 v132, v132, v132
	v_fmac_f32_e32 v134, v133, v133
	v_fmac_f32_e32 v132, v2, v2
	v_add_f32_e32 v2, v134, v132
	v_fmamk_f32 v132, v0, 0xbc800000, v15
	v_fmamk_f32 v134, v0, 0xbc800000, v13
	v_add_f32_e32 v1, v1, v2
	v_fmamk_f32 v2, v0, 0xbc800000, v14
	v_fmamk_f32 v133, v0, 0xbc800000, v12
	v_mul_f32_e32 v134, v134, v134
	v_mul_f32_e32 v132, v132, v132
	v_fmac_f32_e32 v134, v133, v133
	v_fmac_f32_e32 v132, v2, v2
	v_add_f32_e32 v2, v134, v132
	v_fmamk_f32 v132, v0, 0xbc800000, v7
	v_fmamk_f32 v134, v0, 0xbc800000, v5
	v_add_f32_e32 v1, v2, v1
	v_fmamk_f32 v2, v0, 0xbc800000, v6
	v_fmamk_f32 v133, v0, 0xbc800000, v4
	v_mul_f32_e32 v134, v134, v134
	v_mul_f32_e32 v132, v132, v132
	v_fmac_f32_e32 v134, v133, v133
	v_fmac_f32_e32 v132, v2, v2
	v_add_f32_e32 v2, v134, v132
	v_add_f32_e32 v1, v2, v1
	v_mov_b32_e32 v2, v1
	s_nop 1
	v_permlane16_swap_b32 v1, v2
	s_waitcnt lgkmcnt(0)
	v_add_f32_e32 v1, v1, v2
	v_mov_b32_e32 v2, v1
	s_nop 1
	v_permlane32_swap_b32 v1, v2
	s_and_saveexec_b64 s[4:5], vcc
	v_readlane_b32 s56, v253, 19
	v_readlane_b32 s16, v253, 21
	v_readlane_b32 s57, v253, 20
	v_readlane_b32 s17, v253, 22
	s_cbranch_execz .LBB0_1214
	s_lshl_b32 s8, s0, 11
	s_add_i32 s8, s7, s8
	v_mul_f32_e32 v0, 0x3c800000, v0
	s_waitcnt lgkmcnt(0)
	v_add_f32_e32 v1, v1, v2
	v_lshl_add_u32 v2, v144, 5, s8
	ds_write_b64 v2, v[0:1] offset:512
.LBB0_1214:
	s_or_b64 exec, exec, s[4:5]
	v_mov_b32_e32 v0, v101
	v_mov_b32_e32 v1, v102
	v_mov_b32_e32 v132, v100
	v_mov_b32_e32 v133, v103
	v_pk_add_f32 v[0:1], v[0:1], v[132:133]
	v_mov_b32_e32 v132, v89
	v_mov_b32_e32 v133, v90
	v_mov_b32_e32 v134, v88
	v_mov_b32_e32 v135, v91
	v_pk_add_f32 v[132:133], v[132:133], v[134:135]
	v_add_f32_e32 v0, v0, v1
	v_pk_add_f32 v[132:133], v[132:133], v[132:133] op_sel_hi:[0,1]
	v_add_f32_e32 v1, 0, v0
	v_add_f32_e32 v135, v52, v53
	v_add_f32_e32 v137, v54, v55
	v_mov_b32_e32 v134, v32
	v_mov_b32_e32 v136, v33
	v_mov_b32_e32 v132, v34
	v_mov_b32_e32 v0, v35
	v_pk_add_f32 v[134:135], v[134:135], v[136:137]
	v_pk_add_f32 v[0:1], v[132:133], v[0:1]
	s_nop 0
	v_pk_add_f32 v[0:1], v[134:135], v[0:1]
	s_nop 0
	v_add_f32_e32 v0, v0, v1
	v_mov_b32_e32 v1, v0
	s_nop 1
	v_permlane16_swap_b32 v0, v1
	s_waitcnt lgkmcnt(0)
	v_add_f32_e32 v0, v0, v1
	v_mov_b32_e32 v1, v0
	s_nop 1
	v_permlane32_swap_b32 v0, v1
	s_waitcnt lgkmcnt(0)
	v_add_f32_e32 v0, v0, v1
	v_fmamk_f32 v2, v0, 0xbc800000, v103
	v_fmamk_f32 v133, v0, 0xbc800000, v101
	v_fmamk_f32 v1, v0, 0xbc800000, v102
	v_fmamk_f32 v132, v0, 0xbc800000, v100
	v_mul_f32_e32 v133, v133, v133
	v_mul_f32_e32 v2, v2, v2
	v_fmac_f32_e32 v133, v132, v132
	v_fmac_f32_e32 v2, v1, v1
	v_fmamk_f32 v132, v0, 0xbc800000, v91
	v_fmamk_f32 v134, v0, 0xbc800000, v89
	v_add_f32_e32 v1, v133, v2
	v_fmamk_f32 v2, v0, 0xbc800000, v90
	v_fmamk_f32 v133, v0, 0xbc800000, v88
	v_mul_f32_e32 v134, v134, v134
	v_mul_f32_e32 v132, v132, v132
	v_fmac_f32_e32 v134, v133, v133
	v_fmac_f32_e32 v132, v2, v2
	v_add_f32_e32 v2, v134, v132
	v_fmamk_f32 v132, v0, 0xbc800000, v55
	v_fmamk_f32 v134, v0, 0xbc800000, v53
	v_add_f32_e32 v1, v1, v2
	v_fmamk_f32 v2, v0, 0xbc800000, v54
	v_fmamk_f32 v133, v0, 0xbc800000, v52
	v_mul_f32_e32 v134, v134, v134
	v_mul_f32_e32 v132, v132, v132
	v_fmac_f32_e32 v134, v133, v133
	v_fmac_f32_e32 v132, v2, v2
	v_add_f32_e32 v2, v134, v132
	v_fmamk_f32 v132, v0, 0xbc800000, v35
	v_fmamk_f32 v134, v0, 0xbc800000, v33
	v_add_f32_e32 v1, v2, v1
	v_fmamk_f32 v2, v0, 0xbc800000, v34
	v_fmamk_f32 v133, v0, 0xbc800000, v32
	v_mul_f32_e32 v134, v134, v134
	v_mul_f32_e32 v132, v132, v132
	v_fmac_f32_e32 v134, v133, v133
	v_fmac_f32_e32 v132, v2, v2
	v_add_f32_e32 v2, v134, v132
	v_add_f32_e32 v1, v2, v1
	v_mov_b32_e32 v2, v1
	s_nop 1
	v_permlane16_swap_b32 v1, v2
	s_waitcnt lgkmcnt(0)
	v_add_f32_e32 v1, v1, v2
	v_mov_b32_e32 v2, v1
	s_nop 1
	v_permlane32_swap_b32 v1, v2
	s_and_saveexec_b64 s[4:5], vcc
	s_cbranch_execz .LBB0_1216
	s_lshl_b32 s8, s0, 11
	s_add_i32 s8, s7, s8
	v_mul_f32_e32 v0, 0x3c800000, v0
	s_waitcnt lgkmcnt(0)
	v_add_f32_e32 v1, v1, v2
	v_lshl_add_u32 v2, v144, 5, s8
	ds_write_b64 v2, v[0:1] offset:1024
.LBB0_1216:
	s_or_b64 exec, exec, s[4:5]
	v_mov_b32_e32 v0, v105
	v_mov_b32_e32 v1, v106
	v_mov_b32_e32 v132, v104
	v_mov_b32_e32 v133, v107
	v_pk_add_f32 v[0:1], v[0:1], v[132:133]
	v_mov_b32_e32 v132, v85
	v_mov_b32_e32 v133, v86
	v_mov_b32_e32 v134, v84
	v_mov_b32_e32 v135, v87
	v_pk_add_f32 v[132:133], v[132:133], v[134:135]
	v_add_f32_e32 v0, v0, v1
	v_pk_add_f32 v[132:133], v[132:133], v[132:133] op_sel_hi:[0,1]
	v_add_f32_e32 v1, 0, v0
	v_add_f32_e32 v135, v48, v49
	v_add_f32_e32 v137, v50, v51
	v_mov_b32_e32 v134, v28
	v_mov_b32_e32 v136, v29
	v_mov_b32_e32 v132, v30
	v_mov_b32_e32 v0, v31
	v_pk_add_f32 v[134:135], v[134:135], v[136:137]
	v_pk_add_f32 v[0:1], v[132:133], v[0:1]
	s_nop 0
	v_pk_add_f32 v[0:1], v[134:135], v[0:1]
	s_nop 0
	v_add_f32_e32 v0, v0, v1
	v_mov_b32_e32 v1, v0
	s_nop 1
	v_permlane16_swap_b32 v0, v1
	s_waitcnt lgkmcnt(0)
	v_add_f32_e32 v0, v0, v1
	v_mov_b32_e32 v1, v0
	s_nop 1
	v_permlane32_swap_b32 v0, v1
	s_waitcnt lgkmcnt(0)
	v_add_f32_e32 v0, v0, v1
	v_fmamk_f32 v2, v0, 0xbc800000, v107
	v_fmamk_f32 v133, v0, 0xbc800000, v105
	v_fmamk_f32 v1, v0, 0xbc800000, v106
	v_fmamk_f32 v132, v0, 0xbc800000, v104
	v_mul_f32_e32 v133, v133, v133
	v_mul_f32_e32 v2, v2, v2
	v_fmac_f32_e32 v133, v132, v132
	v_fmac_f32_e32 v2, v1, v1
	v_fmamk_f32 v132, v0, 0xbc800000, v87
	v_fmamk_f32 v134, v0, 0xbc800000, v85
	v_add_f32_e32 v1, v133, v2
	v_fmamk_f32 v2, v0, 0xbc800000, v86
	v_fmamk_f32 v133, v0, 0xbc800000, v84
	v_mul_f32_e32 v134, v134, v134
	v_mul_f32_e32 v132, v132, v132
	v_fmac_f32_e32 v134, v133, v133
	v_fmac_f32_e32 v132, v2, v2
	v_add_f32_e32 v2, v134, v132
	v_fmamk_f32 v132, v0, 0xbc800000, v51
	v_fmamk_f32 v134, v0, 0xbc800000, v49
	v_add_f32_e32 v1, v1, v2
	v_fmamk_f32 v2, v0, 0xbc800000, v50
	v_fmamk_f32 v133, v0, 0xbc800000, v48
	v_mul_f32_e32 v134, v134, v134
	v_mul_f32_e32 v132, v132, v132
	v_fmac_f32_e32 v134, v133, v133
	v_fmac_f32_e32 v132, v2, v2
	v_add_f32_e32 v2, v134, v132
	v_fmamk_f32 v132, v0, 0xbc800000, v31
	v_fmamk_f32 v134, v0, 0xbc800000, v29
	v_add_f32_e32 v1, v2, v1
	v_fmamk_f32 v2, v0, 0xbc800000, v30
	v_fmamk_f32 v133, v0, 0xbc800000, v28
	v_mul_f32_e32 v134, v134, v134
	v_mul_f32_e32 v132, v132, v132
	v_fmac_f32_e32 v134, v133, v133
	v_fmac_f32_e32 v132, v2, v2
	v_add_f32_e32 v2, v134, v132
	v_add_f32_e32 v1, v2, v1
	v_mov_b32_e32 v2, v1
	s_nop 1
	v_permlane16_swap_b32 v1, v2
	s_waitcnt lgkmcnt(0)
	v_add_f32_e32 v1, v1, v2
	v_mov_b32_e32 v2, v1
	s_nop 1
	v_permlane32_swap_b32 v1, v2
	s_and_saveexec_b64 s[4:5], vcc
	s_cbranch_execz .LBB0_1218
	s_lshl_b32 s8, s0, 11
	s_add_i32 s8, s7, s8
	v_mul_f32_e32 v0, 0x3c800000, v0
	s_waitcnt lgkmcnt(0)
	v_add_f32_e32 v1, v1, v2
	v_lshl_add_u32 v2, v144, 5, s8
	ds_write_b64 v2, v[0:1] offset:1536
.LBB0_1218:
	s_or_b64 exec, exec, s[4:5]
	v_mov_b32_e32 v0, v129
	v_mov_b32_e32 v1, v130
	v_mov_b32_e32 v132, v128
	v_mov_b32_e32 v133, v131
	v_pk_add_f32 v[0:1], v[0:1], v[132:133]
	v_mov_b32_e32 v132, v125
	v_mov_b32_e32 v133, v126
	v_mov_b32_e32 v134, v124
	v_mov_b32_e32 v135, v127
	v_pk_add_f32 v[132:133], v[132:133], v[134:135]
	v_add_f32_e32 v0, v0, v1
	v_pk_add_f32 v[132:133], v[132:133], v[132:133] op_sel_hi:[0,1]
	v_add_f32_e32 v1, 0, v0
	v_add_f32_e32 v135, v112, v113
	v_add_f32_e32 v137, v114, v115
	v_mov_b32_e32 v134, v96
	v_mov_b32_e32 v136, v97
	v_mov_b32_e32 v132, v98
	v_mov_b32_e32 v0, v99
	v_pk_add_f32 v[134:135], v[134:135], v[136:137]
	v_pk_add_f32 v[0:1], v[132:133], v[0:1]
	s_nop 0
	v_pk_add_f32 v[0:1], v[134:135], v[0:1]
	s_nop 0
	v_add_f32_e32 v0, v0, v1
	v_mov_b32_e32 v1, v0
	s_nop 1
	v_permlane16_swap_b32 v0, v1
	s_waitcnt lgkmcnt(0)
	v_add_f32_e32 v0, v0, v1
	v_mov_b32_e32 v1, v0
	s_nop 1
	v_permlane32_swap_b32 v0, v1
	s_waitcnt lgkmcnt(0)
	v_add_f32_e32 v0, v0, v1
	v_fmamk_f32 v2, v0, 0xbc800000, v131
	v_fmamk_f32 v133, v0, 0xbc800000, v129
	v_fmamk_f32 v1, v0, 0xbc800000, v130
	v_fmamk_f32 v132, v0, 0xbc800000, v128
	v_mul_f32_e32 v133, v133, v133
	v_mul_f32_e32 v2, v2, v2
	v_fmac_f32_e32 v133, v132, v132
	v_fmac_f32_e32 v2, v1, v1
	v_fmamk_f32 v132, v0, 0xbc800000, v127
	v_fmamk_f32 v134, v0, 0xbc800000, v125
	v_add_f32_e32 v1, v133, v2
	v_fmamk_f32 v2, v0, 0xbc800000, v126
	v_fmamk_f32 v133, v0, 0xbc800000, v124
	v_mul_f32_e32 v134, v134, v134
	v_mul_f32_e32 v132, v132, v132
	v_fmac_f32_e32 v134, v133, v133
	v_fmac_f32_e32 v132, v2, v2
	v_add_f32_e32 v2, v134, v132
	v_fmamk_f32 v132, v0, 0xbc800000, v115
	v_fmamk_f32 v134, v0, 0xbc800000, v113
	v_add_f32_e32 v1, v1, v2
	v_fmamk_f32 v2, v0, 0xbc800000, v114
	v_fmamk_f32 v133, v0, 0xbc800000, v112
	v_mul_f32_e32 v134, v134, v134
	v_mul_f32_e32 v132, v132, v132
	v_fmac_f32_e32 v134, v133, v133
	v_fmac_f32_e32 v132, v2, v2
	v_add_f32_e32 v2, v134, v132
	v_fmamk_f32 v132, v0, 0xbc800000, v99
	v_fmamk_f32 v134, v0, 0xbc800000, v97
	v_add_f32_e32 v1, v2, v1
	v_fmamk_f32 v2, v0, 0xbc800000, v98
	v_fmamk_f32 v133, v0, 0xbc800000, v96
	v_mul_f32_e32 v134, v134, v134
	v_mul_f32_e32 v132, v132, v132
	v_fmac_f32_e32 v134, v133, v133
	v_fmac_f32_e32 v132, v2, v2
	v_add_f32_e32 v2, v134, v132
	v_add_f32_e32 v1, v2, v1
	v_mov_b32_e32 v2, v1
	s_nop 1
	v_permlane16_swap_b32 v1, v2
	s_waitcnt lgkmcnt(0)
	v_add_f32_e32 v1, v1, v2
	v_mov_b32_e32 v2, v1
	s_nop 1
	v_permlane32_swap_b32 v1, v2
	s_and_saveexec_b64 s[4:5], vcc
	s_cbranch_execz .LBB0_1220
	s_lshl_b32 s8, s0, 11
	s_add_i32 s8, s7, s8
	v_mul_f32_e32 v0, 0x3c800000, v0
	s_waitcnt lgkmcnt(0)
	v_add_f32_e32 v1, v1, v2
	v_lshl_add_u32 v2, v144, 5, s8
	ds_write_b64 v2, v[0:1] offset:4096
.LBB0_1220:
	s_or_b64 exec, exec, s[4:5]
	v_mov_b32_e32 v0, v121
	v_mov_b32_e32 v1, v122
	v_mov_b32_e32 v132, v120
	v_mov_b32_e32 v133, v123
	v_pk_add_f32 v[0:1], v[0:1], v[132:133]
	v_mov_b32_e32 v132, v117
	v_mov_b32_e32 v133, v118
	v_mov_b32_e32 v134, v116
	v_mov_b32_e32 v135, v119
	v_pk_add_f32 v[132:133], v[132:133], v[134:135]
	v_add_f32_e32 v0, v0, v1
	v_pk_add_f32 v[132:133], v[132:133], v[132:133] op_sel_hi:[0,1]
	v_add_f32_e32 v1, 0, v0
	v_add_f32_e32 v135, v108, v109
	v_add_f32_e32 v137, v110, v111
	v_mov_b32_e32 v134, v92
	v_mov_b32_e32 v136, v93
	v_mov_b32_e32 v132, v94
	v_mov_b32_e32 v0, v95
	v_pk_add_f32 v[134:135], v[134:135], v[136:137]
	v_pk_add_f32 v[0:1], v[132:133], v[0:1]
	s_nop 0
	v_pk_add_f32 v[0:1], v[134:135], v[0:1]
	s_nop 0
	v_add_f32_e32 v0, v0, v1
	v_mov_b32_e32 v1, v0
	s_nop 1
	v_permlane16_swap_b32 v0, v1
	s_waitcnt lgkmcnt(0)
	v_add_f32_e32 v0, v0, v1
	v_mov_b32_e32 v1, v0
	s_nop 1
	v_permlane32_swap_b32 v0, v1
	s_waitcnt lgkmcnt(0)
	v_add_f32_e32 v0, v0, v1
	v_fmamk_f32 v2, v0, 0xbc800000, v123
	v_fmamk_f32 v133, v0, 0xbc800000, v121
	v_fmamk_f32 v1, v0, 0xbc800000, v122
	v_fmamk_f32 v132, v0, 0xbc800000, v120
	v_mul_f32_e32 v133, v133, v133
	v_mul_f32_e32 v2, v2, v2
	v_fmac_f32_e32 v133, v132, v132
	v_fmac_f32_e32 v2, v1, v1
	v_fmamk_f32 v132, v0, 0xbc800000, v119
	v_fmamk_f32 v134, v0, 0xbc800000, v117
	v_add_f32_e32 v1, v133, v2
	v_fmamk_f32 v2, v0, 0xbc800000, v118
	v_fmamk_f32 v133, v0, 0xbc800000, v116
	v_mul_f32_e32 v134, v134, v134
	v_mul_f32_e32 v132, v132, v132
	v_fmac_f32_e32 v134, v133, v133
	v_fmac_f32_e32 v132, v2, v2
	v_add_f32_e32 v2, v134, v132
	v_fmamk_f32 v132, v0, 0xbc800000, v111
	v_fmamk_f32 v134, v0, 0xbc800000, v109
	v_add_f32_e32 v1, v1, v2
	v_fmamk_f32 v2, v0, 0xbc800000, v110
	v_fmamk_f32 v133, v0, 0xbc800000, v108
	v_mul_f32_e32 v134, v134, v134
	v_mul_f32_e32 v132, v132, v132
	v_fmac_f32_e32 v134, v133, v133
	v_fmac_f32_e32 v132, v2, v2
	v_add_f32_e32 v2, v134, v132
	v_fmamk_f32 v132, v0, 0xbc800000, v95
	v_fmamk_f32 v134, v0, 0xbc800000, v93
	v_add_f32_e32 v1, v2, v1
	v_fmamk_f32 v2, v0, 0xbc800000, v94
	v_fmamk_f32 v133, v0, 0xbc800000, v92
	v_mul_f32_e32 v134, v134, v134
	v_mul_f32_e32 v132, v132, v132
	v_fmac_f32_e32 v134, v133, v133
	v_fmac_f32_e32 v132, v2, v2
	v_add_f32_e32 v2, v134, v132
	v_add_f32_e32 v1, v2, v1
	v_mov_b32_e32 v2, v1
	s_nop 1
	v_permlane16_swap_b32 v1, v2
	s_waitcnt lgkmcnt(0)
	v_add_f32_e32 v1, v1, v2
	v_mov_b32_e32 v2, v1
	s_nop 1
	v_permlane32_swap_b32 v1, v2
	s_and_saveexec_b64 s[4:5], vcc
	s_cbranch_execz .LBB0_1222
	s_lshl_b32 s8, s0, 11
	s_add_i32 s8, s7, s8
	v_mul_f32_e32 v0, 0x3c800000, v0
	s_waitcnt lgkmcnt(0)
	v_add_f32_e32 v1, v1, v2
	v_lshl_add_u32 v2, v144, 5, s8
	ds_write_b64 v2, v[0:1] offset:4608
.LBB0_1222:
	s_or_b64 exec, exec, s[4:5]
	v_mov_b32_e32 v0, v81
	v_mov_b32_e32 v1, v82
	v_mov_b32_e32 v132, v80
	v_mov_b32_e32 v133, v83
	v_pk_add_f32 v[0:1], v[0:1], v[132:133]
	v_mov_b32_e32 v132, v77
	v_mov_b32_e32 v133, v78
	v_mov_b32_e32 v134, v76
	v_mov_b32_e32 v135, v79
	v_pk_add_f32 v[132:133], v[132:133], v[134:135]
	v_add_f32_e32 v0, v0, v1
	v_pk_add_f32 v[132:133], v[132:133], v[132:133] op_sel_hi:[0,1]
	v_add_f32_e32 v1, 0, v0
	v_add_f32_e32 v135, v64, v65
	v_add_f32_e32 v137, v66, v67
	v_mov_b32_e32 v134, v60
	v_mov_b32_e32 v136, v61
	v_mov_b32_e32 v132, v62
	v_mov_b32_e32 v0, v63
	v_pk_add_f32 v[134:135], v[134:135], v[136:137]
	v_pk_add_f32 v[0:1], v[132:133], v[0:1]
	s_nop 0
	v_pk_add_f32 v[0:1], v[134:135], v[0:1]
	s_nop 0
	v_add_f32_e32 v0, v0, v1
	v_mov_b32_e32 v1, v0
	s_nop 1
	v_permlane16_swap_b32 v0, v1
	s_waitcnt lgkmcnt(0)
	v_add_f32_e32 v0, v0, v1
	v_mov_b32_e32 v1, v0
	s_nop 1
	v_permlane32_swap_b32 v0, v1
	s_waitcnt lgkmcnt(0)
	v_add_f32_e32 v0, v0, v1
	v_fmamk_f32 v2, v0, 0xbc800000, v83
	v_fmamk_f32 v133, v0, 0xbc800000, v81
	v_fmamk_f32 v1, v0, 0xbc800000, v82
	v_fmamk_f32 v132, v0, 0xbc800000, v80
	v_mul_f32_e32 v133, v133, v133
	v_mul_f32_e32 v2, v2, v2
	v_fmac_f32_e32 v133, v132, v132
	v_fmac_f32_e32 v2, v1, v1
	v_fmamk_f32 v132, v0, 0xbc800000, v79
	v_fmamk_f32 v134, v0, 0xbc800000, v77
	v_add_f32_e32 v1, v133, v2
	v_fmamk_f32 v2, v0, 0xbc800000, v78
	v_fmamk_f32 v133, v0, 0xbc800000, v76
	v_mul_f32_e32 v134, v134, v134
	v_mul_f32_e32 v132, v132, v132
	v_fmac_f32_e32 v134, v133, v133
	v_fmac_f32_e32 v132, v2, v2
	v_add_f32_e32 v2, v134, v132
	v_fmamk_f32 v132, v0, 0xbc800000, v67
	v_fmamk_f32 v134, v0, 0xbc800000, v65
	v_add_f32_e32 v1, v1, v2
	v_fmamk_f32 v2, v0, 0xbc800000, v66
	v_fmamk_f32 v133, v0, 0xbc800000, v64
	v_mul_f32_e32 v134, v134, v134
	v_mul_f32_e32 v132, v132, v132
	v_fmac_f32_e32 v134, v133, v133
	v_fmac_f32_e32 v132, v2, v2
	v_add_f32_e32 v2, v134, v132
	v_fmamk_f32 v132, v0, 0xbc800000, v63
	v_fmamk_f32 v134, v0, 0xbc800000, v61
	v_add_f32_e32 v1, v2, v1
	v_fmamk_f32 v2, v0, 0xbc800000, v62
	v_fmamk_f32 v133, v0, 0xbc800000, v60
	v_mul_f32_e32 v134, v134, v134
	v_mul_f32_e32 v132, v132, v132
	v_fmac_f32_e32 v134, v133, v133
	v_fmac_f32_e32 v132, v2, v2
	v_add_f32_e32 v2, v134, v132
	v_add_f32_e32 v1, v2, v1
	v_mov_b32_e32 v2, v1
	s_nop 1
	v_permlane16_swap_b32 v1, v2
	s_waitcnt lgkmcnt(0)
	v_add_f32_e32 v1, v1, v2
	v_mov_b32_e32 v2, v1
	s_nop 1
	v_permlane32_swap_b32 v1, v2
	s_and_saveexec_b64 s[4:5], vcc
	s_cbranch_execz .LBB0_1224
	s_lshl_b32 s8, s0, 11
	s_add_i32 s8, s7, s8
	v_mul_f32_e32 v0, 0x3c800000, v0
	s_waitcnt lgkmcnt(0)
	v_add_f32_e32 v1, v1, v2
	v_lshl_add_u32 v2, v144, 5, s8
	ds_write_b64 v2, v[0:1] offset:5120
.LBB0_1224:
	s_or_b64 exec, exec, s[4:5]
	v_mov_b32_e32 v0, v73
	v_mov_b32_e32 v1, v74
	v_mov_b32_e32 v132, v72
	v_mov_b32_e32 v133, v75
	v_pk_add_f32 v[0:1], v[0:1], v[132:133]
	v_mov_b32_e32 v132, v69
	v_mov_b32_e32 v133, v70
	v_mov_b32_e32 v134, v68
	v_mov_b32_e32 v135, v71
	v_pk_add_f32 v[132:133], v[132:133], v[134:135]
	v_add_f32_e32 v0, v0, v1
	v_pk_add_f32 v[132:133], v[132:133], v[132:133] op_sel_hi:[0,1]
	v_add_f32_e32 v1, 0, v0
	v_add_f32_e32 v135, v56, v57
	v_add_f32_e32 v137, v58, v59
	v_mov_b32_e32 v134, v44
	v_mov_b32_e32 v136, v45
	v_mov_b32_e32 v132, v46
	v_mov_b32_e32 v0, v47
	v_pk_add_f32 v[134:135], v[134:135], v[136:137]
	v_pk_add_f32 v[0:1], v[132:133], v[0:1]
	s_nop 0
	v_pk_add_f32 v[0:1], v[134:135], v[0:1]
	s_nop 0
	v_add_f32_e32 v0, v0, v1
	v_mov_b32_e32 v1, v0
	s_nop 1
	v_permlane16_swap_b32 v0, v1
	s_waitcnt lgkmcnt(0)
	v_add_f32_e32 v0, v0, v1
	v_mov_b32_e32 v1, v0
	s_nop 1
	v_permlane32_swap_b32 v0, v1
	s_waitcnt lgkmcnt(0)
	v_add_f32_e32 v0, v0, v1
	v_fmamk_f32 v2, v0, 0xbc800000, v75
	v_fmamk_f32 v133, v0, 0xbc800000, v73
	v_fmamk_f32 v1, v0, 0xbc800000, v74
	v_fmamk_f32 v132, v0, 0xbc800000, v72
	v_mul_f32_e32 v133, v133, v133
	v_mul_f32_e32 v2, v2, v2
	v_fmac_f32_e32 v133, v132, v132
	v_fmac_f32_e32 v2, v1, v1
	v_fmamk_f32 v132, v0, 0xbc800000, v71
	v_fmamk_f32 v134, v0, 0xbc800000, v69
	v_add_f32_e32 v1, v133, v2
	v_fmamk_f32 v2, v0, 0xbc800000, v70
	v_fmamk_f32 v133, v0, 0xbc800000, v68
	v_mul_f32_e32 v134, v134, v134
	v_mul_f32_e32 v132, v132, v132
	v_fmac_f32_e32 v134, v133, v133
	v_fmac_f32_e32 v132, v2, v2
	v_add_f32_e32 v2, v134, v132
	v_fmamk_f32 v132, v0, 0xbc800000, v59
	v_fmamk_f32 v134, v0, 0xbc800000, v57
	v_add_f32_e32 v1, v1, v2
	v_fmamk_f32 v2, v0, 0xbc800000, v58
	v_fmamk_f32 v133, v0, 0xbc800000, v56
	v_mul_f32_e32 v134, v134, v134
	v_mul_f32_e32 v132, v132, v132
	v_fmac_f32_e32 v134, v133, v133
	v_fmac_f32_e32 v132, v2, v2
	v_add_f32_e32 v2, v134, v132
	v_fmamk_f32 v132, v0, 0xbc800000, v47
	v_fmamk_f32 v134, v0, 0xbc800000, v45
	v_add_f32_e32 v1, v2, v1
	v_fmamk_f32 v2, v0, 0xbc800000, v46
	v_fmamk_f32 v133, v0, 0xbc800000, v44
	v_mul_f32_e32 v134, v134, v134
	v_mul_f32_e32 v132, v132, v132
	v_fmac_f32_e32 v134, v133, v133
	v_fmac_f32_e32 v132, v2, v2
	v_add_f32_e32 v2, v134, v132
	v_add_f32_e32 v1, v2, v1
	v_mov_b32_e32 v2, v1
	s_nop 1
	v_permlane16_swap_b32 v1, v2
	s_waitcnt lgkmcnt(0)
	v_add_f32_e32 v1, v1, v2
	v_mov_b32_e32 v2, v1
	s_nop 1
	v_permlane32_swap_b32 v1, v2
	s_and_saveexec_b64 s[4:5], vcc
	s_cbranch_execz .LBB0_1226
	s_lshl_b32 s8, s0, 11
	s_add_i32 s7, s7, s8
	v_mul_f32_e32 v0, 0x3c800000, v0
	s_waitcnt lgkmcnt(0)
	v_add_f32_e32 v1, v1, v2
	v_lshl_add_u32 v2, v144, 5, s7
	ds_write_b64 v2, v[0:1] offset:5632
